# B + sample-row loads at the heads of P7 and P10 hoisted into batches (16 / 46 serialized round trips -> 2 / 6)
# speedup vs baseline: 1.0204x; 1.0204x over previous
.LBB0_1259:
	v_lshl_add_u64 v[0:1], s[6:7], 0, v[10:11]
	s_mov_b64 s[98:99], 0x100000
	s_mov_b64 s[100:101], 0x800000
	v_lshl_add_u64 v[198:199], v[0:1], 0, s[98:99]
	v_lshl_add_u64 v[200:201], v[198:199], 0, s[100:101]
	v_lshl_add_u64 v[202:203], v[200:201], 0, s[100:101]
	v_lshl_add_u64 v[204:205], v[202:203], 0, s[100:101]
	s_mov_b64 s[98:99], 0x1000
	v_lshl_add_u64 v[196:197], v[12:13], 0, s[98:99]
	global_load_dwordx4 v[100:103], v[12:13], off
	global_load_dwordx2 v[104:105], v[198:199], off
	global_load_dwordx2 v[106:107], v[200:201], off
	global_load_dwordx2 v[108:109], v[202:203], off
	global_load_dwordx2 v[110:111], v[204:205], off
	global_load_dwordx2 v[112:113], v[204:205], off offset:512
	global_load_dwordx2 v[114:115], v[202:203], off offset:512
	global_load_dwordx2 v[116:117], v[200:201], off offset:512
	global_load_dwordx2 v[118:119], v[198:199], off offset:512
	global_load_dwordx4 v[120:123], v[12:13], off offset:1024
	global_load_dwordx4 v[124:127], v[12:13], off offset:2048
	global_load_dwordx2 v[128:129], v[198:199], off offset:1024
	global_load_dwordx2 v[130:131], v[200:201], off offset:1024
	global_load_dwordx2 v[132:133], v[202:203], off offset:1024
	global_load_dwordx2 v[134:135], v[204:205], off offset:1024
	global_load_dwordx2 v[136:137], v[204:205], off offset:1536
	global_load_dwordx2 v[138:139], v[202:203], off offset:1536
	global_load_dwordx2 v[140:141], v[200:201], off offset:1536
	global_load_dwordx2 v[142:143], v[198:199], off offset:1536
	global_load_dwordx4 v[144:147], v[12:13], off offset:3072
	global_load_dwordx4 v[148:151], v[196:197], off
	global_load_dwordx2 v[152:153], v[198:199], off offset:2048
	global_load_dwordx2 v[154:155], v[200:201], off offset:2048
	global_load_dwordx2 v[156:157], v[202:203], off offset:2048
	global_load_dwordx2 v[158:159], v[204:205], off offset:2048
	global_load_dwordx2 v[160:161], v[204:205], off offset:2560
	global_load_dwordx2 v[162:163], v[202:203], off offset:2560
	global_load_dwordx2 v[164:165], v[200:201], off offset:2560
	global_load_dwordx2 v[166:167], v[198:199], off offset:2560
	global_load_dwordx4 v[168:171], v[196:197], off offset:1024
	global_load_dwordx4 v[172:175], v[196:197], off offset:2048
	global_load_dwordx2 v[176:177], v[198:199], off offset:3072
	global_load_dwordx2 v[178:179], v[200:201], off offset:3072
	global_load_dwordx2 v[180:181], v[202:203], off offset:3072
	global_load_dwordx2 v[182:183], v[204:205], off offset:3072
	global_load_dwordx2 v[184:185], v[204:205], off offset:3584
	global_load_dwordx2 v[186:187], v[202:203], off offset:3584
	global_load_dwordx2 v[188:189], v[200:201], off offset:3584
	global_load_dwordx2 v[190:191], v[198:199], off offset:3584
	global_load_dwordx4 v[192:195], v[196:197], off offset:3072
	v_add_co_u32_e32 v42, vcc, 0x100000, v0
	s_nop 0
	v_addc_co_u32_e32 v43, vcc, 0, v1, vcc
	v_add_co_u32_e32 v44, vcc, 0x900000, v0
	s_nop 0
	v_addc_co_u32_e32 v45, vcc, 0, v1, vcc
	v_add_co_u32_e32 v46, vcc, 0x1100000, v0
	s_nop 0
	v_addc_co_u32_e32 v47, vcc, 0, v1, vcc
	v_add_co_u32_e32 v48, vcc, 0x1900000, v0
	s_nop 0
	v_addc_co_u32_e32 v49, vcc, 0, v1, vcc
	s_movk_i32 s18, 0x1000
	v_add_co_u32_e32 v50, vcc, s18, v12
	s_movk_i32 s18, 0x2000
	s_nop 0
	v_addc_co_u32_e32 v51, vcc, 0, v13, vcc
	s_mov_b64 s[56:57], 0x100
	s_waitcnt vmcnt(38)
	v_mov_b32_e32 v16, v100
	v_mov_b32_e32 v17, v101
	v_mov_b32_e32 v18, v102
	v_mov_b32_e32 v19, v103
	v_mov_b32_e32 v2, v104
	v_mov_b32_e32 v3, v105
	v_lshlrev_b32_e32 v24, 16, v2
	v_and_b32_e32 v25, 0xffff0000, v2
	v_lshlrev_b32_e32 v2, 16, v3
	v_and_b32_e32 v3, 0xffff0000, v3
	s_waitcnt vmcnt(37)
	v_mov_b32_e32 v14, v106
	v_mov_b32_e32 v15, v107
	v_lshlrev_b32_e32 v26, 16, v14
	v_and_b32_e32 v27, 0xffff0000, v14
	v_lshlrev_b32_e32 v14, 16, v15
	v_and_b32_e32 v15, 0xffff0000, v15
	v_pk_add_f32 v[2:3], v[2:3], v[14:15]
	v_pk_add_f32 v[14:15], v[24:25], v[26:27]
	s_waitcnt vmcnt(36)
	v_mov_b32_e32 v20, v108
	v_mov_b32_e32 v21, v109
	v_lshlrev_b32_e32 v24, 16, v20
	v_and_b32_e32 v25, 0xffff0000, v20
	v_lshlrev_b32_e32 v20, 16, v21
	v_and_b32_e32 v21, 0xffff0000, v21
	s_waitcnt vmcnt(35)
	v_mov_b32_e32 v22, v110
	v_mov_b32_e32 v23, v111
	v_lshlrev_b32_e32 v26, 16, v22
	v_and_b32_e32 v27, 0xffff0000, v22
	v_lshlrev_b32_e32 v22, 16, v23
	v_and_b32_e32 v23, 0xffff0000, v23
	v_pk_add_f32 v[20:21], v[20:21], v[22:23]
	v_pk_add_f32 v[22:23], v[24:25], v[26:27]
	v_pk_add_f32 v[2:3], v[2:3], v[20:21]
	v_pk_add_f32 v[22:23], v[14:15], v[22:23]
	v_pk_fma_f32 v[14:15], v[18:19], s[38:39], v[2:3] op_sel_hi:[1,0,1]
	v_pk_fma_f32 v[16:17], v[16:17], s[38:39], v[22:23] op_sel_hi:[1,0,1]
	v_add_f32_e32 v3, v14, v15
	v_add_f32_e32 v2, v16, v17
	v_add_f32_e32 v2, v2, v3
	v_add_f32_e32 v32, 0, v2
	v_mul_f32_e32 v2, v17, v17
	v_mul_f32_e32 v3, v15, v15
	v_fmac_f32_e32 v2, v16, v16
	v_fmac_f32_e32 v3, v14, v14
	v_add_f32_e32 v33, v2, v3
	s_waitcnt vmcnt(32)
	v_mov_b32_e32 v2, v112
	v_mov_b32_e32 v3, v113
	v_mov_b32_e32 v18, v114
	v_mov_b32_e32 v19, v115
	v_mov_b32_e32 v24, v116
	v_mov_b32_e32 v25, v117
	v_lshlrev_b32_e32 v30, 16, v24
	s_waitcnt vmcnt(31)
	v_mov_b32_e32 v26, v118
	v_mov_b32_e32 v27, v119
	v_lshlrev_b32_e32 v28, 16, v26
	v_and_b32_e32 v29, 0xffff0000, v26
	v_lshlrev_b32_e32 v26, 16, v27
	v_and_b32_e32 v27, 0xffff0000, v27
	v_and_b32_e32 v31, 0xffff0000, v24
	v_lshlrev_b32_e32 v24, 16, v25
	v_and_b32_e32 v25, 0xffff0000, v25
	v_pk_add_f32 v[24:25], v[24:25], v[26:27]
	v_pk_add_f32 v[26:27], v[30:31], v[28:29]
	v_lshlrev_b32_e32 v28, 16, v18
	v_and_b32_e32 v29, 0xffff0000, v18
	v_lshlrev_b32_e32 v18, 16, v19
	v_and_b32_e32 v19, 0xffff0000, v19
	v_lshlrev_b32_e32 v30, 16, v2
	v_and_b32_e32 v31, 0xffff0000, v2
	v_lshlrev_b32_e32 v2, 16, v3
	v_and_b32_e32 v3, 0xffff0000, v3
	v_pk_add_f32 v[2:3], v[2:3], v[18:19]
	v_pk_add_f32 v[18:19], v[30:31], v[28:29]
	v_pk_add_f32 v[2:3], v[2:3], v[24:25]
	v_pk_add_f32 v[26:27], v[18:19], v[26:27]
	s_waitcnt vmcnt(30)
	v_mov_b32_e32 v20, v120
	v_mov_b32_e32 v21, v121
	v_mov_b32_e32 v22, v122
	v_mov_b32_e32 v23, v123
	v_pk_fma_f32 v[18:19], v[22:23], s[38:39], v[2:3] op_sel_hi:[1,0,1]
	v_pk_fma_f32 v[20:21], v[20:21], s[38:39], v[26:27] op_sel_hi:[1,0,1]
	v_add_f32_e32 v3, v18, v19
	v_add_f32_e32 v2, v20, v21
	v_add_f32_e32 v2, v2, v3
	v_add_f32_e32 v36, v32, v2
	v_mul_f32_e32 v2, v21, v21
	v_mul_f32_e32 v3, v19, v19
	v_fmac_f32_e32 v2, v20, v20
	v_fmac_f32_e32 v3, v18, v18
	v_add_f32_e32 v2, v2, v3
	v_add_f32_e32 v37, v33, v2
	s_waitcnt vmcnt(28)
	v_mov_b32_e32 v24, v124
	v_mov_b32_e32 v25, v125
	v_mov_b32_e32 v26, v126
	v_mov_b32_e32 v27, v127
	v_mov_b32_e32 v2, v128
	v_mov_b32_e32 v3, v129
	v_lshlrev_b32_e32 v32, 16, v2
	v_and_b32_e32 v33, 0xffff0000, v2
	v_lshlrev_b32_e32 v2, 16, v3
	v_and_b32_e32 v3, 0xffff0000, v3
	s_waitcnt vmcnt(27)
	v_mov_b32_e32 v22, v130
	v_mov_b32_e32 v23, v131
	v_lshlrev_b32_e32 v34, 16, v22
	v_and_b32_e32 v35, 0xffff0000, v22
	v_lshlrev_b32_e32 v22, 16, v23
	v_and_b32_e32 v23, 0xffff0000, v23
	v_pk_add_f32 v[2:3], v[2:3], v[22:23]
	v_pk_add_f32 v[22:23], v[32:33], v[34:35]
	s_waitcnt vmcnt(26)
	v_mov_b32_e32 v28, v132
	v_mov_b32_e32 v29, v133
	v_lshlrev_b32_e32 v32, 16, v28
	v_and_b32_e32 v33, 0xffff0000, v28
	v_lshlrev_b32_e32 v28, 16, v29
	v_and_b32_e32 v29, 0xffff0000, v29
	s_waitcnt vmcnt(25)
	v_mov_b32_e32 v30, v134
	v_mov_b32_e32 v31, v135
	v_lshlrev_b32_e32 v34, 16, v30
	v_and_b32_e32 v35, 0xffff0000, v30
	v_lshlrev_b32_e32 v30, 16, v31
	v_and_b32_e32 v31, 0xffff0000, v31
	v_pk_add_f32 v[28:29], v[28:29], v[30:31]
	v_pk_add_f32 v[30:31], v[32:33], v[34:35]
	v_pk_add_f32 v[2:3], v[2:3], v[28:29]
	v_pk_add_f32 v[30:31], v[22:23], v[30:31]
	v_pk_fma_f32 v[22:23], v[26:27], s[38:39], v[2:3] op_sel_hi:[1,0,1]
	v_pk_fma_f32 v[24:25], v[24:25], s[38:39], v[30:31] op_sel_hi:[1,0,1]
	v_add_f32_e32 v3, v22, v23
	v_add_f32_e32 v2, v24, v25
	v_add_f32_e32 v2, v2, v3
	v_add_f32_e32 v40, v36, v2
	v_mul_f32_e32 v2, v25, v25
	v_mul_f32_e32 v3, v23, v23
	v_fmac_f32_e32 v2, v24, v24
	v_fmac_f32_e32 v3, v22, v22
	v_add_f32_e32 v2, v2, v3
	v_add_f32_e32 v41, v37, v2
	s_waitcnt vmcnt(22)
	v_mov_b32_e32 v2, v136
	v_mov_b32_e32 v3, v137
	v_mov_b32_e32 v26, v138
	v_mov_b32_e32 v27, v139
	v_mov_b32_e32 v28, v140
	v_mov_b32_e32 v29, v141
	v_lshlrev_b32_e32 v38, 16, v28
	s_waitcnt vmcnt(21)
	v_mov_b32_e32 v30, v142
	v_mov_b32_e32 v31, v143
	v_lshlrev_b32_e32 v36, 16, v30
	v_and_b32_e32 v37, 0xffff0000, v30
	v_lshlrev_b32_e32 v30, 16, v31
	v_and_b32_e32 v31, 0xffff0000, v31
	v_and_b32_e32 v39, 0xffff0000, v28
	v_lshlrev_b32_e32 v28, 16, v29
	v_and_b32_e32 v29, 0xffff0000, v29
	v_pk_add_f32 v[28:29], v[28:29], v[30:31]
	v_pk_add_f32 v[30:31], v[38:39], v[36:37]
	v_lshlrev_b32_e32 v36, 16, v26
	v_and_b32_e32 v37, 0xffff0000, v26
	v_lshlrev_b32_e32 v26, 16, v27
	v_and_b32_e32 v27, 0xffff0000, v27
	v_lshlrev_b32_e32 v38, 16, v2
	v_and_b32_e32 v39, 0xffff0000, v2
	v_lshlrev_b32_e32 v2, 16, v3
	v_and_b32_e32 v3, 0xffff0000, v3
	v_pk_add_f32 v[2:3], v[2:3], v[26:27]
	v_pk_add_f32 v[26:27], v[38:39], v[36:37]
	v_pk_add_f32 v[2:3], v[2:3], v[28:29]
	v_pk_add_f32 v[30:31], v[26:27], v[30:31]
	s_waitcnt vmcnt(20)
	v_mov_b32_e32 v32, v144
	v_mov_b32_e32 v33, v145
	v_mov_b32_e32 v34, v146
	v_mov_b32_e32 v35, v147
	v_pk_fma_f32 v[26:27], v[34:35], s[38:39], v[2:3] op_sel_hi:[1,0,1]
	v_pk_fma_f32 v[28:29], v[32:33], s[38:39], v[30:31] op_sel_hi:[1,0,1]
	v_add_f32_e32 v3, v26, v27
	v_add_f32_e32 v2, v28, v29
	v_add_f32_e32 v2, v2, v3
	v_add_f32_e32 v56, v40, v2
	v_mul_f32_e32 v2, v29, v29
	v_mul_f32_e32 v3, v27, v27
	v_fmac_f32_e32 v2, v28, v28
	v_fmac_f32_e32 v3, v26, v26
	v_add_f32_e32 v2, v2, v3
	v_add_f32_e32 v57, v41, v2
	v_add_co_u32_e32 v2, vcc, s18, v12
	s_mov_b32 s18, 0x101000
	s_nop 0
	v_addc_co_u32_e32 v3, vcc, 0, v13, vcc
	s_waitcnt vmcnt(18)
	v_mov_b32_e32 v32, v148
	v_mov_b32_e32 v33, v149
	v_mov_b32_e32 v34, v150
	v_mov_b32_e32 v35, v151
	v_mov_b32_e32 v30, v152
	v_mov_b32_e32 v31, v153
	v_lshlrev_b32_e32 v52, 16, v30
	v_and_b32_e32 v53, 0xffff0000, v30
	v_lshlrev_b32_e32 v30, 16, v31
	v_and_b32_e32 v31, 0xffff0000, v31
	s_waitcnt vmcnt(17)
	v_mov_b32_e32 v36, v154
	v_mov_b32_e32 v37, v155
	v_lshlrev_b32_e32 v54, 16, v36
	v_and_b32_e32 v55, 0xffff0000, v36
	v_lshlrev_b32_e32 v36, 16, v37
	v_and_b32_e32 v37, 0xffff0000, v37
	v_pk_add_f32 v[30:31], v[30:31], v[36:37]
	v_pk_add_f32 v[36:37], v[52:53], v[54:55]
	s_waitcnt vmcnt(16)
	v_mov_b32_e32 v38, v156
	v_mov_b32_e32 v39, v157
	v_lshlrev_b32_e32 v52, 16, v38
	v_and_b32_e32 v53, 0xffff0000, v38
	v_lshlrev_b32_e32 v38, 16, v39
	v_and_b32_e32 v39, 0xffff0000, v39
	s_waitcnt vmcnt(15)
	v_mov_b32_e32 v40, v158
	v_mov_b32_e32 v41, v159
	v_lshlrev_b32_e32 v54, 16, v40
	v_and_b32_e32 v55, 0xffff0000, v40
	v_lshlrev_b32_e32 v40, 16, v41
	v_and_b32_e32 v41, 0xffff0000, v41
	v_pk_add_f32 v[38:39], v[38:39], v[40:41]
	v_pk_add_f32 v[40:41], v[52:53], v[54:55]
	v_pk_add_f32 v[30:31], v[30:31], v[38:39]
	v_pk_add_f32 v[36:37], v[36:37], v[40:41]
	v_pk_fma_f32 v[30:31], v[34:35], s[38:39], v[30:31] op_sel_hi:[1,0,1]
	v_pk_fma_f32 v[32:33], v[32:33], s[38:39], v[36:37] op_sel_hi:[1,0,1]
	v_add_f32_e32 v35, v30, v31
	v_add_f32_e32 v34, v32, v33
	v_add_f32_e32 v34, v34, v35
	v_add_f32_e32 v60, v56, v34
	v_mul_f32_e32 v34, v33, v33
	v_mul_f32_e32 v35, v31, v31
	v_fmac_f32_e32 v34, v32, v32
	v_fmac_f32_e32 v35, v30, v30
	v_add_f32_e32 v34, v34, v35
	v_add_f32_e32 v61, v57, v34
	s_waitcnt vmcnt(12)
	v_mov_b32_e32 v34, v160
	v_mov_b32_e32 v35, v161
	v_mov_b32_e32 v36, v162
	v_mov_b32_e32 v37, v163
	v_mov_b32_e32 v52, v164
	v_mov_b32_e32 v53, v165
	v_lshlrev_b32_e32 v58, 16, v52
	s_waitcnt vmcnt(11)
	v_mov_b32_e32 v54, v166
	v_mov_b32_e32 v55, v167
	v_lshlrev_b32_e32 v56, 16, v54
	v_and_b32_e32 v57, 0xffff0000, v54
	v_lshlrev_b32_e32 v54, 16, v55
	v_and_b32_e32 v55, 0xffff0000, v55
	v_and_b32_e32 v59, 0xffff0000, v52
	v_lshlrev_b32_e32 v52, 16, v53
	v_and_b32_e32 v53, 0xffff0000, v53
	v_pk_add_f32 v[52:53], v[52:53], v[54:55]
	v_pk_add_f32 v[54:55], v[58:59], v[56:57]
	v_lshlrev_b32_e32 v56, 16, v36
	v_and_b32_e32 v57, 0xffff0000, v36
	v_lshlrev_b32_e32 v36, 16, v37
	v_and_b32_e32 v37, 0xffff0000, v37
	v_lshlrev_b32_e32 v58, 16, v34
	v_and_b32_e32 v59, 0xffff0000, v34
	v_lshlrev_b32_e32 v34, 16, v35
	v_and_b32_e32 v35, 0xffff0000, v35
	v_pk_add_f32 v[34:35], v[34:35], v[36:37]
	v_pk_add_f32 v[36:37], v[58:59], v[56:57]
	v_pk_add_f32 v[34:35], v[34:35], v[52:53]
	v_pk_add_f32 v[36:37], v[36:37], v[54:55]
	s_waitcnt vmcnt(10)
	v_mov_b32_e32 v38, v168
	v_mov_b32_e32 v39, v169
	v_mov_b32_e32 v40, v170
	v_mov_b32_e32 v41, v171
	v_pk_fma_f32 v[34:35], v[40:41], s[38:39], v[34:35] op_sel_hi:[1,0,1]
	v_pk_fma_f32 v[36:37], v[38:39], s[38:39], v[36:37] op_sel_hi:[1,0,1]
	v_add_f32_e32 v39, v34, v35
	v_add_f32_e32 v38, v36, v37
	v_add_f32_e32 v38, v38, v39
	v_add_f32_e32 v64, v60, v38
	v_mul_f32_e32 v38, v37, v37
	v_mul_f32_e32 v39, v35, v35
	v_fmac_f32_e32 v38, v36, v36
	v_fmac_f32_e32 v39, v34, v34
	v_add_f32_e32 v38, v38, v39
	v_add_f32_e32 v65, v61, v38
	s_waitcnt vmcnt(8)
	v_mov_b32_e32 v52, v172
	v_mov_b32_e32 v53, v173
	v_mov_b32_e32 v54, v174
	v_mov_b32_e32 v55, v175
	v_mov_b32_e32 v38, v176
	v_mov_b32_e32 v39, v177
	v_lshlrev_b32_e32 v60, 16, v38
	v_and_b32_e32 v61, 0xffff0000, v38
	v_lshlrev_b32_e32 v38, 16, v39
	v_and_b32_e32 v39, 0xffff0000, v39
	s_waitcnt vmcnt(7)
	v_mov_b32_e32 v40, v178
	v_mov_b32_e32 v41, v179
	v_lshlrev_b32_e32 v62, 16, v40
	v_and_b32_e32 v63, 0xffff0000, v40
	v_lshlrev_b32_e32 v40, 16, v41
	v_and_b32_e32 v41, 0xffff0000, v41
	v_pk_add_f32 v[38:39], v[38:39], v[40:41]
	v_pk_add_f32 v[40:41], v[60:61], v[62:63]
	s_waitcnt vmcnt(6)
	v_mov_b32_e32 v56, v180
	v_mov_b32_e32 v57, v181
	v_lshlrev_b32_e32 v60, 16, v56
	v_and_b32_e32 v61, 0xffff0000, v56
	v_lshlrev_b32_e32 v56, 16, v57
	v_and_b32_e32 v57, 0xffff0000, v57
	s_waitcnt vmcnt(5)
	v_mov_b32_e32 v58, v182
	v_mov_b32_e32 v59, v183
	v_lshlrev_b32_e32 v62, 16, v58
	v_and_b32_e32 v63, 0xffff0000, v58
	v_lshlrev_b32_e32 v58, 16, v59
	v_and_b32_e32 v59, 0xffff0000, v59
	v_pk_add_f32 v[56:57], v[56:57], v[58:59]
	v_pk_add_f32 v[58:59], v[60:61], v[62:63]
	v_pk_add_f32 v[38:39], v[38:39], v[56:57]
	v_pk_add_f32 v[40:41], v[40:41], v[58:59]
	v_pk_fma_f32 v[38:39], v[54:55], s[38:39], v[38:39] op_sel_hi:[1,0,1]
	v_pk_fma_f32 v[40:41], v[52:53], s[38:39], v[40:41] op_sel_hi:[1,0,1]
	v_add_f32_e32 v53, v38, v39
	v_add_f32_e32 v52, v40, v41
	v_add_f32_e32 v52, v52, v53
	v_add_f32_e32 v58, v64, v52
	v_mul_f32_e32 v52, v41, v41
	v_mul_f32_e32 v53, v39, v39
	v_fmac_f32_e32 v52, v40, v40
	v_fmac_f32_e32 v53, v38, v38
	v_add_f32_e32 v52, v52, v53
	v_add_f32_e32 v59, v65, v52
	s_nop 0
	s_nop 0
	s_nop 0
	s_nop 0
	s_waitcnt vmcnt(2)
	v_mov_b32_e32 v48, v184
	v_mov_b32_e32 v49, v185
	v_mov_b32_e32 v46, v186
	v_mov_b32_e32 v47, v187
	v_mov_b32_e32 v44, v188
	v_mov_b32_e32 v45, v189
	v_lshlrev_b32_e32 v56, 16, v44
	s_waitcnt vmcnt(1)
	v_mov_b32_e32 v42, v190
	v_mov_b32_e32 v43, v191
	v_lshlrev_b32_e32 v54, 16, v42
	v_and_b32_e32 v55, 0xffff0000, v42
	v_lshlrev_b32_e32 v42, 16, v43
	v_and_b32_e32 v43, 0xffff0000, v43
	v_and_b32_e32 v57, 0xffff0000, v44
	v_lshlrev_b32_e32 v44, 16, v45
	v_and_b32_e32 v45, 0xffff0000, v45
	v_pk_add_f32 v[42:43], v[44:45], v[42:43]
	v_pk_add_f32 v[44:45], v[56:57], v[54:55]
	v_lshlrev_b32_e32 v54, 16, v46
	v_and_b32_e32 v55, 0xffff0000, v46
	v_lshlrev_b32_e32 v46, 16, v47
	v_and_b32_e32 v47, 0xffff0000, v47
	v_lshlrev_b32_e32 v56, 16, v48
	v_and_b32_e32 v57, 0xffff0000, v48
	v_lshlrev_b32_e32 v48, 16, v49
	v_and_b32_e32 v49, 0xffff0000, v49
	v_pk_add_f32 v[46:47], v[48:49], v[46:47]
	v_pk_add_f32 v[48:49], v[56:57], v[54:55]
	v_pk_add_f32 v[42:43], v[46:47], v[42:43]
	v_pk_add_f32 v[44:45], v[48:49], v[44:45]
	s_waitcnt vmcnt(0)
	v_mov_b32_e32 v50, v192
	v_mov_b32_e32 v51, v193
	v_mov_b32_e32 v52, v194
	v_mov_b32_e32 v53, v195
	s_mov_b64 s[98:99], 0x1000
	v_lshl_add_u64 v[198:199], v[198:199], 0, s[98:99]
	v_lshl_add_u64 v[200:201], v[200:201], 0, s[98:99]
	v_lshl_add_u64 v[202:203], v[202:203], 0, s[98:99]
	v_lshl_add_u64 v[204:205], v[204:205], 0, s[98:99]
	v_lshl_add_u64 v[196:197], v[196:197], 0, s[98:99]
	v_lshl_add_u64 v[206:207], v[196:197], 0, s[98:99]
	global_load_dwordx2 v[100:101], v[198:199], off
	global_load_dwordx2 v[102:103], v[200:201], off
	global_load_dwordx2 v[104:105], v[202:203], off
	global_load_dwordx2 v[106:107], v[204:205], off
	global_load_dwordx4 v[108:111], v[196:197], off
	global_load_dwordx2 v[112:113], v[204:205], off offset:512
	global_load_dwordx2 v[114:115], v[202:203], off offset:512
	global_load_dwordx2 v[116:117], v[200:201], off offset:512
	global_load_dwordx2 v[118:119], v[198:199], off offset:512
	global_load_dwordx4 v[120:123], v[196:197], off offset:1024
	global_load_dwordx4 v[124:127], v[196:197], off offset:2048
	global_load_dwordx2 v[128:129], v[198:199], off offset:1024
	global_load_dwordx2 v[130:131], v[200:201], off offset:1024
	global_load_dwordx2 v[132:133], v[202:203], off offset:1024
	global_load_dwordx2 v[134:135], v[204:205], off offset:1024
	global_load_dwordx2 v[136:137], v[204:205], off offset:1536
	global_load_dwordx2 v[138:139], v[202:203], off offset:1536
	global_load_dwordx2 v[140:141], v[200:201], off offset:1536
	global_load_dwordx2 v[142:143], v[198:199], off offset:1536
	global_load_dwordx4 v[144:147], v[196:197], off offset:3072
	global_load_dwordx4 v[148:151], v[206:207], off
	global_load_dwordx2 v[152:153], v[198:199], off offset:2048
	global_load_dwordx2 v[154:155], v[200:201], off offset:2048
	global_load_dwordx2 v[156:157], v[202:203], off offset:2048
	global_load_dwordx2 v[158:159], v[204:205], off offset:2048
	global_load_dwordx2 v[160:161], v[204:205], off offset:2560
	global_load_dwordx2 v[162:163], v[202:203], off offset:2560
	global_load_dwordx2 v[164:165], v[200:201], off offset:2560
	global_load_dwordx2 v[166:167], v[198:199], off offset:2560
	global_load_dwordx4 v[168:171], v[206:207], off offset:1024
	global_load_dwordx4 v[172:175], v[206:207], off offset:2048
	global_load_dwordx2 v[176:177], v[198:199], off offset:3072
	global_load_dwordx2 v[178:179], v[200:201], off offset:3072
	global_load_dwordx2 v[180:181], v[202:203], off offset:3072
	global_load_dwordx2 v[182:183], v[204:205], off offset:3072
	global_load_dwordx2 v[184:185], v[204:205], off offset:3584
	global_load_dwordx2 v[186:187], v[202:203], off offset:3584
	global_load_dwordx2 v[188:189], v[200:201], off offset:3584
	global_load_dwordx2 v[190:191], v[198:199], off offset:3584
	global_load_dwordx4 v[192:195], v[206:207], off offset:3072
	v_pk_fma_f32 v[42:43], v[52:53], s[38:39], v[42:43] op_sel_hi:[1,0,1]
	v_pk_fma_f32 v[44:45], v[50:51], s[38:39], v[44:45] op_sel_hi:[1,0,1]
	v_add_f32_e32 v47, v42, v43
	v_add_f32_e32 v46, v44, v45
	v_add_f32_e32 v46, v46, v47
	v_add_f32_e32 v68, v58, v46
	v_mul_f32_e32 v46, v45, v45
	v_mul_f32_e32 v47, v43, v43
	v_fmac_f32_e32 v46, v44, v44
	v_fmac_f32_e32 v47, v42, v42
	v_add_f32_e32 v46, v46, v47
	v_add_co_u32_e32 v58, vcc, s18, v0
	v_add_f32_e32 v69, v59, v46
	s_nop 0
	v_addc_co_u32_e32 v59, vcc, 0, v1, vcc
	s_mov_b32 s18, 0x901000
	v_add_co_u32_e32 v60, vcc, s18, v0
	s_mov_b32 s18, 0x1101000
	s_nop 0
	v_addc_co_u32_e32 v61, vcc, 0, v1, vcc
	v_add_co_u32_e32 v66, vcc, s18, v0
	s_mov_b32 s18, 0x1901000
	s_nop 0
	v_addc_co_u32_e32 v67, vcc, 0, v1, vcc
	v_add_co_u32_e32 v0, vcc, s18, v0
	v_addc_co_u32_e32 v1, vcc, 0, v1, vcc
	s_movk_i32 s18, 0x3000
	s_waitcnt vmcnt(39)
	v_mov_b32_e32 v46, v100
	v_mov_b32_e32 v47, v101
	v_lshlrev_b32_e32 v62, 16, v46
	v_and_b32_e32 v63, 0xffff0000, v46
	v_lshlrev_b32_e32 v46, 16, v47
	v_and_b32_e32 v47, 0xffff0000, v47
	s_waitcnt vmcnt(38)
	v_mov_b32_e32 v52, v102
	v_mov_b32_e32 v53, v103
	v_lshlrev_b32_e32 v64, 16, v52
	v_and_b32_e32 v65, 0xffff0000, v52
	v_lshlrev_b32_e32 v52, 16, v53
	v_and_b32_e32 v53, 0xffff0000, v53
	v_pk_add_f32 v[46:47], v[46:47], v[52:53]
	v_pk_add_f32 v[52:53], v[62:63], v[64:65]
	s_waitcnt vmcnt(37)
	v_mov_b32_e32 v54, v104
	v_mov_b32_e32 v55, v105
	v_lshlrev_b32_e32 v62, 16, v54
	v_and_b32_e32 v63, 0xffff0000, v54
	v_lshlrev_b32_e32 v54, 16, v55
	v_and_b32_e32 v55, 0xffff0000, v55
	s_waitcnt vmcnt(36)
	v_mov_b32_e32 v56, v106
	v_mov_b32_e32 v57, v107
	v_lshlrev_b32_e32 v64, 16, v56
	v_and_b32_e32 v65, 0xffff0000, v56
	v_lshlrev_b32_e32 v56, 16, v57
	v_and_b32_e32 v57, 0xffff0000, v57
	v_pk_add_f32 v[54:55], v[54:55], v[56:57]
	v_pk_add_f32 v[56:57], v[62:63], v[64:65]
	v_pk_add_f32 v[46:47], v[46:47], v[54:55]
	v_pk_add_f32 v[52:53], v[52:53], v[56:57]
	s_waitcnt vmcnt(35)
	v_mov_b32_e32 v48, v108
	v_mov_b32_e32 v49, v109
	v_mov_b32_e32 v50, v110
	v_mov_b32_e32 v51, v111
	v_pk_fma_f32 v[46:47], v[50:51], s[38:39], v[46:47] op_sel_hi:[1,0,1]
	v_pk_fma_f32 v[48:49], v[48:49], s[38:39], v[52:53] op_sel_hi:[1,0,1]
	v_add_f32_e32 v51, v46, v47
	v_add_f32_e32 v50, v48, v49
	v_add_f32_e32 v50, v50, v51
	v_add_f32_e32 v72, v68, v50
	v_mul_f32_e32 v50, v49, v49
	v_mul_f32_e32 v51, v47, v47
	v_fmac_f32_e32 v50, v48, v48
	v_fmac_f32_e32 v51, v46, v46
	v_add_f32_e32 v50, v50, v51
	v_add_f32_e32 v73, v69, v50
	s_waitcnt vmcnt(32)
	v_mov_b32_e32 v50, v112
	v_mov_b32_e32 v51, v113
	v_mov_b32_e32 v52, v114
	v_mov_b32_e32 v53, v115
	v_mov_b32_e32 v62, v116
	v_mov_b32_e32 v63, v117
	v_lshlrev_b32_e32 v70, 16, v62
	s_waitcnt vmcnt(31)
	v_mov_b32_e32 v64, v118
	v_mov_b32_e32 v65, v119
	v_lshlrev_b32_e32 v68, 16, v64
	v_and_b32_e32 v69, 0xffff0000, v64
	v_lshlrev_b32_e32 v64, 16, v65
	v_and_b32_e32 v65, 0xffff0000, v65
	v_and_b32_e32 v71, 0xffff0000, v62
	v_lshlrev_b32_e32 v62, 16, v63
	v_and_b32_e32 v63, 0xffff0000, v63
	v_pk_add_f32 v[62:63], v[62:63], v[64:65]
	v_pk_add_f32 v[64:65], v[70:71], v[68:69]
	v_lshlrev_b32_e32 v68, 16, v52
	v_and_b32_e32 v69, 0xffff0000, v52
	v_lshlrev_b32_e32 v52, 16, v53
	v_and_b32_e32 v53, 0xffff0000, v53
	v_lshlrev_b32_e32 v70, 16, v50
	v_and_b32_e32 v71, 0xffff0000, v50
	v_lshlrev_b32_e32 v50, 16, v51
	v_and_b32_e32 v51, 0xffff0000, v51
	v_pk_add_f32 v[50:51], v[50:51], v[52:53]
	v_pk_add_f32 v[52:53], v[70:71], v[68:69]
	v_pk_add_f32 v[50:51], v[50:51], v[62:63]
	v_pk_add_f32 v[52:53], v[52:53], v[64:65]
	s_waitcnt vmcnt(30)
	v_mov_b32_e32 v54, v120
	v_mov_b32_e32 v55, v121
	v_mov_b32_e32 v56, v122
	v_mov_b32_e32 v57, v123
	v_pk_fma_f32 v[50:51], v[56:57], s[38:39], v[50:51] op_sel_hi:[1,0,1]
	v_pk_fma_f32 v[52:53], v[54:55], s[38:39], v[52:53] op_sel_hi:[1,0,1]
	v_add_f32_e32 v55, v50, v51
	v_add_f32_e32 v54, v52, v53
	v_add_f32_e32 v54, v54, v55
	v_add_f32_e32 v76, v72, v54
	v_mul_f32_e32 v54, v53, v53
	v_mul_f32_e32 v55, v51, v51
	v_fmac_f32_e32 v54, v52, v52
	v_fmac_f32_e32 v55, v50, v50
	v_add_f32_e32 v54, v54, v55
	v_add_f32_e32 v77, v73, v54
	s_waitcnt vmcnt(28)
	v_mov_b32_e32 v62, v124
	v_mov_b32_e32 v63, v125
	v_mov_b32_e32 v64, v126
	v_mov_b32_e32 v65, v127
	v_mov_b32_e32 v54, v128
	v_mov_b32_e32 v55, v129
	v_lshlrev_b32_e32 v72, 16, v54
	v_and_b32_e32 v73, 0xffff0000, v54
	v_lshlrev_b32_e32 v54, 16, v55
	v_and_b32_e32 v55, 0xffff0000, v55
	s_waitcnt vmcnt(27)
	v_mov_b32_e32 v56, v130
	v_mov_b32_e32 v57, v131
	v_lshlrev_b32_e32 v74, 16, v56
	v_and_b32_e32 v75, 0xffff0000, v56
	v_lshlrev_b32_e32 v56, 16, v57
	v_and_b32_e32 v57, 0xffff0000, v57
	v_pk_add_f32 v[54:55], v[54:55], v[56:57]
	v_pk_add_f32 v[56:57], v[72:73], v[74:75]
	s_waitcnt vmcnt(26)
	v_mov_b32_e32 v68, v132
	v_mov_b32_e32 v69, v133
	v_lshlrev_b32_e32 v72, 16, v68
	v_and_b32_e32 v73, 0xffff0000, v68
	v_lshlrev_b32_e32 v68, 16, v69
	v_and_b32_e32 v69, 0xffff0000, v69
	s_waitcnt vmcnt(25)
	v_mov_b32_e32 v70, v134
	v_mov_b32_e32 v71, v135
	v_lshlrev_b32_e32 v74, 16, v70
	v_and_b32_e32 v75, 0xffff0000, v70
	v_lshlrev_b32_e32 v70, 16, v71
	v_and_b32_e32 v71, 0xffff0000, v71
	v_pk_add_f32 v[68:69], v[68:69], v[70:71]
	v_pk_add_f32 v[70:71], v[72:73], v[74:75]
	v_pk_add_f32 v[54:55], v[54:55], v[68:69]
	v_pk_add_f32 v[56:57], v[56:57], v[70:71]
	v_pk_fma_f32 v[54:55], v[64:65], s[38:39], v[54:55] op_sel_hi:[1,0,1]
	v_pk_fma_f32 v[56:57], v[62:63], s[38:39], v[56:57] op_sel_hi:[1,0,1]
	v_add_f32_e32 v63, v54, v55
	v_add_f32_e32 v62, v56, v57
	v_add_f32_e32 v62, v62, v63
	v_add_f32_e32 v78, v76, v62
	v_mul_f32_e32 v62, v57, v57
	v_mul_f32_e32 v63, v55, v55
	v_fmac_f32_e32 v62, v56, v56
	v_fmac_f32_e32 v63, v54, v54
	v_add_f32_e32 v62, v62, v63
	v_add_f32_e32 v79, v77, v62
	s_waitcnt vmcnt(22)
	v_mov_b32_e32 v62, v136
	v_mov_b32_e32 v63, v137
	v_mov_b32_e32 v64, v138
	v_mov_b32_e32 v65, v139
	v_mov_b32_e32 v68, v140
	v_mov_b32_e32 v69, v141
	v_lshlrev_b32_e32 v76, 16, v68
	s_waitcnt vmcnt(21)
	v_mov_b32_e32 v74, v142
	v_mov_b32_e32 v75, v143
	v_lshlrev_b32_e32 v2, 16, v74
	v_and_b32_e32 v3, 0xffff0000, v74
	v_lshlrev_b32_e32 v74, 16, v75
	v_and_b32_e32 v75, 0xffff0000, v75
	v_and_b32_e32 v77, 0xffff0000, v68
	v_lshlrev_b32_e32 v68, 16, v69
	v_and_b32_e32 v69, 0xffff0000, v69
	v_pk_add_f32 v[68:69], v[68:69], v[74:75]
	v_pk_add_f32 v[2:3], v[76:77], v[2:3]
	v_lshlrev_b32_e32 v74, 16, v64
	v_and_b32_e32 v75, 0xffff0000, v64
	v_lshlrev_b32_e32 v64, 16, v65
	v_and_b32_e32 v65, 0xffff0000, v65
	v_lshlrev_b32_e32 v76, 16, v62
	v_and_b32_e32 v77, 0xffff0000, v62
	v_lshlrev_b32_e32 v62, 16, v63
	v_and_b32_e32 v63, 0xffff0000, v63
	v_pk_add_f32 v[62:63], v[62:63], v[64:65]
	v_pk_add_f32 v[64:65], v[76:77], v[74:75]
	v_pk_add_f32 v[62:63], v[62:63], v[68:69]
	v_pk_add_f32 v[2:3], v[64:65], v[2:3]
	s_waitcnt vmcnt(20)
	v_mov_b32_e32 v70, v144
	v_mov_b32_e32 v71, v145
	v_mov_b32_e32 v72, v146
	v_mov_b32_e32 v73, v147
	v_pk_fma_f32 v[62:63], v[72:73], s[38:39], v[62:63] op_sel_hi:[1,0,1]
	v_pk_fma_f32 v[64:65], v[70:71], s[38:39], v[2:3] op_sel_hi:[1,0,1]
	v_add_f32_e32 v3, v62, v63
	v_add_f32_e32 v2, v64, v65
	v_add_f32_e32 v2, v2, v3
	v_add_f32_e32 v86, v78, v2
	v_mul_f32_e32 v2, v65, v65
	v_mul_f32_e32 v3, v63, v63
	v_fmac_f32_e32 v2, v64, v64
	v_fmac_f32_e32 v3, v62, v62
	v_add_f32_e32 v2, v2, v3
	v_add_f32_e32 v87, v79, v2
	v_add_co_u32_e32 v2, vcc, s18, v12
	s_nop 1
	v_addc_co_u32_e32 v3, vcc, 0, v13, vcc
	s_waitcnt vmcnt(18)
	v_mov_b32_e32 v70, v148
	v_mov_b32_e32 v71, v149
	v_mov_b32_e32 v72, v150
	v_mov_b32_e32 v73, v151
	v_mov_b32_e32 v68, v152
	v_mov_b32_e32 v69, v153
	v_lshlrev_b32_e32 v80, 16, v68
	v_and_b32_e32 v81, 0xffff0000, v68
	v_lshlrev_b32_e32 v68, 16, v69
	v_and_b32_e32 v69, 0xffff0000, v69
	s_waitcnt vmcnt(17)
	v_mov_b32_e32 v74, v154
	v_mov_b32_e32 v75, v155
	v_lshlrev_b32_e32 v84, 16, v74
	v_and_b32_e32 v85, 0xffff0000, v74
	v_lshlrev_b32_e32 v74, 16, v75
	v_and_b32_e32 v75, 0xffff0000, v75
	v_pk_add_f32 v[68:69], v[68:69], v[74:75]
	v_pk_add_f32 v[74:75], v[80:81], v[84:85]
	s_waitcnt vmcnt(16)
	v_mov_b32_e32 v76, v156
	v_mov_b32_e32 v77, v157
	v_lshlrev_b32_e32 v80, 16, v76
	v_and_b32_e32 v81, 0xffff0000, v76
	v_lshlrev_b32_e32 v76, 16, v77
	v_and_b32_e32 v77, 0xffff0000, v77
	s_waitcnt vmcnt(15)
	v_mov_b32_e32 v78, v158
	v_mov_b32_e32 v79, v159
	v_lshlrev_b32_e32 v84, 16, v78
	v_and_b32_e32 v85, 0xffff0000, v78
	v_lshlrev_b32_e32 v78, 16, v79
	v_and_b32_e32 v79, 0xffff0000, v79
	v_pk_add_f32 v[76:77], v[76:77], v[78:79]
	v_pk_add_f32 v[78:79], v[80:81], v[84:85]
	v_pk_add_f32 v[68:69], v[68:69], v[76:77]
	v_pk_add_f32 v[74:75], v[74:75], v[78:79]
	v_pk_fma_f32 v[68:69], v[72:73], s[38:39], v[68:69] op_sel_hi:[1,0,1]
	v_pk_fma_f32 v[70:71], v[70:71], s[38:39], v[74:75] op_sel_hi:[1,0,1]
	v_add_f32_e32 v73, v68, v69
	v_add_f32_e32 v72, v70, v71
	v_add_f32_e32 v72, v72, v73
	v_add_f32_e32 v90, v86, v72
	v_mul_f32_e32 v72, v71, v71
	v_mul_f32_e32 v73, v69, v69
	v_fmac_f32_e32 v72, v70, v70
	v_fmac_f32_e32 v73, v68, v68
	v_add_f32_e32 v72, v72, v73
	v_add_f32_e32 v91, v87, v72
	s_waitcnt vmcnt(12)
	v_mov_b32_e32 v72, v160
	v_mov_b32_e32 v73, v161
	v_mov_b32_e32 v74, v162
	v_mov_b32_e32 v75, v163
	v_mov_b32_e32 v80, v164
	v_mov_b32_e32 v81, v165
	v_lshlrev_b32_e32 v88, 16, v80
	s_waitcnt vmcnt(11)
	v_mov_b32_e32 v84, v166
	v_mov_b32_e32 v85, v167
	v_lshlrev_b32_e32 v86, 16, v84
	v_and_b32_e32 v87, 0xffff0000, v84
	v_lshlrev_b32_e32 v84, 16, v85
	v_and_b32_e32 v85, 0xffff0000, v85
	v_and_b32_e32 v89, 0xffff0000, v80
	v_lshlrev_b32_e32 v80, 16, v81
	v_and_b32_e32 v81, 0xffff0000, v81
	v_pk_add_f32 v[80:81], v[80:81], v[84:85]
	v_pk_add_f32 v[84:85], v[88:89], v[86:87]
	v_lshlrev_b32_e32 v86, 16, v74
	v_and_b32_e32 v87, 0xffff0000, v74
	v_lshlrev_b32_e32 v74, 16, v75
	v_and_b32_e32 v75, 0xffff0000, v75
	v_lshlrev_b32_e32 v88, 16, v72
	v_and_b32_e32 v89, 0xffff0000, v72
	v_lshlrev_b32_e32 v72, 16, v73
	v_and_b32_e32 v73, 0xffff0000, v73
	v_pk_add_f32 v[72:73], v[72:73], v[74:75]
	v_pk_add_f32 v[74:75], v[88:89], v[86:87]
	v_pk_add_f32 v[72:73], v[72:73], v[80:81]
	v_pk_add_f32 v[74:75], v[74:75], v[84:85]
	s_waitcnt vmcnt(10)
	v_mov_b32_e32 v76, v168
	v_mov_b32_e32 v77, v169
	v_mov_b32_e32 v78, v170
	v_mov_b32_e32 v79, v171
	v_pk_fma_f32 v[72:73], v[78:79], s[38:39], v[72:73] op_sel_hi:[1,0,1]
	v_pk_fma_f32 v[74:75], v[76:77], s[38:39], v[74:75] op_sel_hi:[1,0,1]
	v_add_f32_e32 v77, v72, v73
	v_add_f32_e32 v76, v74, v75
	v_add_f32_e32 v76, v76, v77
	v_add_f32_e32 v94, v90, v76
	v_mul_f32_e32 v76, v75, v75
	v_mul_f32_e32 v77, v73, v73
	v_fmac_f32_e32 v76, v74, v74
	v_fmac_f32_e32 v77, v72, v72
	v_add_f32_e32 v76, v76, v77
	v_add_f32_e32 v95, v91, v76
	s_waitcnt vmcnt(8)
	v_mov_b32_e32 v78, v172
	v_mov_b32_e32 v79, v173
	v_mov_b32_e32 v80, v174
	v_mov_b32_e32 v81, v175
	v_mov_b32_e32 v76, v176
	v_mov_b32_e32 v77, v177
	v_lshlrev_b32_e32 v90, 16, v76
	v_and_b32_e32 v91, 0xffff0000, v76
	v_lshlrev_b32_e32 v76, 16, v77
	v_and_b32_e32 v77, 0xffff0000, v77
	s_waitcnt vmcnt(7)
	v_mov_b32_e32 v84, v178
	v_mov_b32_e32 v85, v179
	v_lshlrev_b32_e32 v92, 16, v84
	v_and_b32_e32 v93, 0xffff0000, v84
	v_lshlrev_b32_e32 v84, 16, v85
	v_and_b32_e32 v85, 0xffff0000, v85
	v_pk_add_f32 v[76:77], v[76:77], v[84:85]
	v_pk_add_f32 v[84:85], v[90:91], v[92:93]
	s_waitcnt vmcnt(6)
	v_mov_b32_e32 v86, v180
	v_mov_b32_e32 v87, v181
	v_lshlrev_b32_e32 v90, 16, v86
	v_and_b32_e32 v91, 0xffff0000, v86
	v_lshlrev_b32_e32 v86, 16, v87
	v_and_b32_e32 v87, 0xffff0000, v87
	s_waitcnt vmcnt(5)
	v_mov_b32_e32 v88, v182
	v_mov_b32_e32 v89, v183
	v_lshlrev_b32_e32 v92, 16, v88
	v_and_b32_e32 v93, 0xffff0000, v88
	v_lshlrev_b32_e32 v88, 16, v89
	v_and_b32_e32 v89, 0xffff0000, v89
	v_pk_add_f32 v[86:87], v[86:87], v[88:89]
	v_pk_add_f32 v[88:89], v[90:91], v[92:93]
	v_pk_add_f32 v[76:77], v[76:77], v[86:87]
	v_pk_add_f32 v[84:85], v[84:85], v[88:89]
	v_pk_fma_f32 v[76:77], v[80:81], s[38:39], v[76:77] op_sel_hi:[1,0,1]
	v_pk_fma_f32 v[78:79], v[78:79], s[38:39], v[84:85] op_sel_hi:[1,0,1]
	v_add_f32_e32 v81, v76, v77
	v_add_f32_e32 v80, v78, v79
	v_add_f32_e32 v80, v80, v81
	v_add_f32_e32 v85, v94, v80
	v_mul_f32_e32 v80, v79, v79
	v_mul_f32_e32 v81, v77, v77
	v_fmac_f32_e32 v80, v78, v78
	v_fmac_f32_e32 v81, v76, v76
	v_add_f32_e32 v80, v80, v81
	v_add_f32_e32 v84, v95, v80
	s_nop 0
	s_nop 0
	s_nop 0
	s_nop 0
	s_waitcnt vmcnt(2)
	v_mov_b32_e32 v80, v184
	v_mov_b32_e32 v81, v185
	v_mov_b32_e32 v66, v186
	v_mov_b32_e32 v67, v187
	v_mov_b32_e32 v60, v188
	v_mov_b32_e32 v61, v189
	v_lshlrev_b32_e32 v88, 16, v60
	s_waitcnt vmcnt(1)
	v_mov_b32_e32 v58, v190
	v_mov_b32_e32 v59, v191
	v_lshlrev_b32_e32 v86, 16, v58
	v_and_b32_e32 v87, 0xffff0000, v58
	v_lshlrev_b32_e32 v58, 16, v59
	v_and_b32_e32 v59, 0xffff0000, v59
	v_and_b32_e32 v89, 0xffff0000, v60
	v_lshlrev_b32_e32 v60, 16, v61
	v_and_b32_e32 v61, 0xffff0000, v61
	v_pk_add_f32 v[58:59], v[60:61], v[58:59]
	v_pk_add_f32 v[60:61], v[88:89], v[86:87]
	v_lshlrev_b32_e32 v86, 16, v66
	v_and_b32_e32 v87, 0xffff0000, v66
	v_lshlrev_b32_e32 v66, 16, v67
	v_and_b32_e32 v67, 0xffff0000, v67
	v_lshlrev_b32_e32 v88, 16, v80
	v_and_b32_e32 v89, 0xffff0000, v80
	v_lshlrev_b32_e32 v80, 16, v81
	v_and_b32_e32 v81, 0xffff0000, v81
	v_pk_add_f32 v[66:67], v[80:81], v[66:67]
	v_pk_add_f32 v[80:81], v[88:89], v[86:87]
	v_pk_add_f32 v[58:59], v[66:67], v[58:59]
	v_pk_add_f32 v[60:61], v[80:81], v[60:61]
	s_waitcnt vmcnt(0)
	v_mov_b32_e32 v0, v192
	v_mov_b32_e32 v1, v193
	v_mov_b32_e32 v2, v194
	v_mov_b32_e32 v3, v195
	v_pk_fma_f32 v[2:3], v[2:3], s[38:39], v[58:59] op_sel_hi:[1,0,1]
	v_pk_fma_f32 v[0:1], v[0:1], s[38:39], v[60:61] op_sel_hi:[1,0,1]
	v_add_f32_e32 v59, v2, v3
	v_add_f32_e32 v58, v0, v1
	v_add_f32_e32 v58, v58, v59
	v_mul_f32_e32 v59, v1, v1
	v_mul_f32_e32 v60, v3, v3
	v_add_f32_e32 v58, v85, v58
	v_fmac_f32_e32 v59, v0, v0
	v_fmac_f32_e32 v60, v2, v2
	v_add_f32_e32 v59, v59, v60
	ds_swizzle_b32 v60, v58 offset:swizzle(SWAP,1)
	v_add_f32_e32 v59, v84, v59
	v_and_b32_sdwa v67, v16, v83 dst_sel:DWORD dst_unused:UNUSED_PAD src0_sel:WORD_1 src1_sel:DWORD
	v_and_b32_sdwa v81, v17, v83 dst_sel:DWORD dst_unused:UNUSED_PAD src0_sel:WORD_1 src1_sel:DWORD
	v_and_b32_sdwa v66, v14, v83 dst_sel:DWORD dst_unused:UNUSED_PAD src0_sel:WORD_1 src1_sel:DWORD
	s_waitcnt lgkmcnt(0)
	v_add_f32_e32 v58, v58, v60
	ds_swizzle_b32 v60, v58 offset:swizzle(SWAP,2)
	v_add3_u32 v80, v16, v67, s21
	v_and_b32_sdwa v67, v15, v83 dst_sel:DWORD dst_unused:UNUSED_PAD src0_sel:WORD_1 src1_sel:DWORD
	v_add3_u32 v81, v17, v81, s21
	v_mul_f32_e32 v17, 0x417e0000, v17
	s_waitcnt lgkmcnt(0)
	v_add_f32_e32 v58, v58, v60
	ds_swizzle_b32 v60, v58 offset:swizzle(SWAP,4)
	v_add3_u32 v66, v14, v66, s21
	v_add3_u32 v67, v15, v67, s21
	v_mul_f32_e32 v16, 0x417e0000, v16
	v_mul_f32_e32 v14, 0x417e0000, v14
	s_waitcnt lgkmcnt(0)
	v_add_f32_e32 v58, v58, v60
	ds_swizzle_b32 v60, v58 offset:swizzle(SWAP,8)
	v_mul_f32_e32 v15, 0x417e0000, v15
	v_med3_f32 v17, v17, s23, v5
	v_med3_f32 v16, v16, s23, v5
	v_rndne_f32_e32 v17, v17
	s_waitcnt lgkmcnt(0)
	v_add_f32_e32 v58, v58, v60
	ds_swizzle_b32 v60, v58 offset:swizzle(SWAP,16)
	v_med3_f32 v14, v14, s23, v5
	v_med3_f32 v15, v15, s23, v5
	v_rndne_f32_e32 v16, v16
	v_cvt_i32_f32_e32 v17, v17
	s_waitcnt lgkmcnt(0)
	v_add_f32_e32 v58, v58, v60
	v_rndne_f32_e32 v14, v14
	v_readlane_b32 s19, v58, 0
	v_readlane_b32 s39, v58, 32
	ds_swizzle_b32 v58, v59 offset:swizzle(SWAP,1)
	v_rndne_f32_e32 v15, v15
	v_cvt_i32_f32_e32 v16, v16
	v_cvt_i32_f32_sdwa v14, v14 dst_sel:WORD_1 dst_unused:UNUSED_PAD src0_sel:DWORD
	v_cvt_i32_f32_e32 v15, v15
	s_waitcnt lgkmcnt(0)
	v_add_f32_e32 v58, v59, v58
	ds_swizzle_b32 v59, v58 offset:swizzle(SWAP,2)
	v_lshlrev_b32_e32 v17, 8, v17
	v_and_b32_e32 v17, 0xff00, v17
	v_and_b32_e32 v14, 0xff0000, v14
	v_perm_b32 v15, v15, v16, s27
	s_waitcnt lgkmcnt(0)
	v_add_f32_e32 v58, v58, v59
	ds_swizzle_b32 v59, v58 offset:swizzle(SWAP,4)
	v_and_b32_e32 v67, 0xffff0000, v67
	v_and_b32_e32 v81, 0xffff0000, v81
	v_or3_b32 v14, v15, v17, v14
	v_and_b32_sdwa v15, v20, v83 dst_sel:DWORD dst_unused:UNUSED_PAD src0_sel:WORD_1 src1_sel:DWORD
	s_waitcnt lgkmcnt(0)
	v_add_f32_e32 v58, v58, v59
	ds_swizzle_b32 v59, v58 offset:swizzle(SWAP,8)
	v_lshl_add_u64 v[60:61], s[6:7], 0, v[6:7]
	v_or_b32_sdwa v67, v67, v66 dst_sel:DWORD dst_unused:UNUSED_PAD src0_sel:DWORD src1_sel:WORD_1
	v_or_b32_sdwa v66, v81, v80 dst_sel:DWORD dst_unused:UNUSED_PAD src0_sel:DWORD src1_sel:WORD_1
	global_store_dwordx2 v[60:61], v[66:67], off sc1
	s_nop 1
	s_waitcnt lgkmcnt(0)
	v_add_f32_e32 v58, v58, v59
	ds_swizzle_b32 v59, v58 offset:swizzle(SWAP,16)
	v_add3_u32 v16, v20, v15, s21
	v_and_b32_sdwa v15, v19, v83 dst_sel:DWORD dst_unused:UNUSED_PAD src0_sel:WORD_1 src1_sel:DWORD
	v_and_b32_sdwa v17, v21, v83 dst_sel:DWORD dst_unused:UNUSED_PAD src0_sel:WORD_1 src1_sel:DWORD
	v_add3_u32 v15, v19, v15, s21
	s_waitcnt lgkmcnt(0)
	v_add_f32_e32 v58, v58, v59
	v_add3_u32 v17, v21, v17, s21
	v_readlane_b32 s18, v58, 0
	v_readlane_b32 s55, v58, 32
	v_lshl_add_u64 v[58:59], s[6:7], 0, v[8:9]
	global_store_dword v[58:59], v14, off sc1
	s_nop 1
	v_and_b32_sdwa v14, v18, v83 dst_sel:DWORD dst_unused:UNUSED_PAD src0_sel:WORD_1 src1_sel:DWORD
	v_add3_u32 v14, v18, v14, s21
	v_and_b32_e32 v15, 0xffff0000, v15
	v_and_b32_e32 v17, 0xffff0000, v17
	v_or_b32_sdwa v15, v15, v14 dst_sel:DWORD dst_unused:UNUSED_PAD src0_sel:DWORD src1_sel:WORD_1
	v_or_b32_sdwa v14, v17, v16 dst_sel:DWORD dst_unused:UNUSED_PAD src0_sel:DWORD src1_sel:WORD_1
	v_lshl_add_u64 v[16:17], v[60:61], 0, s[40:41]
	global_store_dwordx2 v[16:17], v[14:15], off sc1
	s_nop 1
	v_mul_f32_e32 v17, 0x417e0000, v21
	v_mul_f32_e32 v16, 0x417e0000, v20
	v_mul_f32_e32 v18, 0x417e0000, v18
	v_mul_f32_e32 v19, 0x417e0000, v19
	v_med3_f32 v17, v17, s23, v5
	v_med3_f32 v16, v16, s23, v5
	v_rndne_f32_e32 v17, v17
	v_med3_f32 v18, v18, s23, v5
	v_med3_f32 v19, v19, s23, v5
	v_rndne_f32_e32 v16, v16
	v_cvt_i32_f32_e32 v17, v17
	v_rndne_f32_e32 v18, v18
	v_rndne_f32_e32 v19, v19
	v_cvt_i32_f32_e32 v16, v16
	v_cvt_i32_f32_sdwa v18, v18 dst_sel:WORD_1 dst_unused:UNUSED_PAD src0_sel:DWORD
	v_cvt_i32_f32_e32 v19, v19
	v_lshlrev_b32_e32 v17, 8, v17
	v_lshl_add_u64 v[14:15], v[58:59], 0, s[56:57]
	v_and_b32_e32 v17, 0xff00, v17
	v_and_b32_e32 v18, 0xff0000, v18
	v_perm_b32 v16, v19, v16, s27
	v_or3_b32 v16, v16, v17, v18
	global_store_dword v[14:15], v16, off sc1
	s_nop 1
	v_and_b32_sdwa v15, v24, v83 dst_sel:DWORD dst_unused:UNUSED_PAD src0_sel:WORD_1 src1_sel:DWORD
	v_add3_u32 v16, v24, v15, s21
	v_and_b32_sdwa v15, v23, v83 dst_sel:DWORD dst_unused:UNUSED_PAD src0_sel:WORD_1 src1_sel:DWORD
	v_and_b32_sdwa v17, v25, v83 dst_sel:DWORD dst_unused:UNUSED_PAD src0_sel:WORD_1 src1_sel:DWORD
	v_and_b32_sdwa v14, v22, v83 dst_sel:DWORD dst_unused:UNUSED_PAD src0_sel:WORD_1 src1_sel:DWORD
	v_add3_u32 v15, v23, v15, s21
	v_add3_u32 v17, v25, v17, s21
	v_add3_u32 v14, v22, v14, s21
	v_and_b32_e32 v15, 0xffff0000, v15
	v_and_b32_e32 v17, 0xffff0000, v17
	v_or_b32_sdwa v15, v15, v14 dst_sel:DWORD dst_unused:UNUSED_PAD src0_sel:DWORD src1_sel:WORD_1
	v_or_b32_sdwa v14, v17, v16 dst_sel:DWORD dst_unused:UNUSED_PAD src0_sel:DWORD src1_sel:WORD_1
	v_lshl_add_u64 v[16:17], v[60:61], 0, s[42:43]
	global_store_dwordx2 v[16:17], v[14:15], off sc1
	s_nop 1
	v_mul_f32_e32 v17, 0x417e0000, v25
	v_mul_f32_e32 v16, 0x417e0000, v24
	v_mul_f32_e32 v18, 0x417e0000, v22
	v_mul_f32_e32 v19, 0x417e0000, v23
	v_med3_f32 v17, v17, s23, v5
	v_med3_f32 v16, v16, s23, v5
	v_rndne_f32_e32 v17, v17
	v_med3_f32 v18, v18, s23, v5
	v_med3_f32 v19, v19, s23, v5
	v_rndne_f32_e32 v16, v16
	v_cvt_i32_f32_e32 v17, v17
	v_rndne_f32_e32 v18, v18
	v_rndne_f32_e32 v19, v19
	v_cvt_i32_f32_e32 v16, v16
	v_cvt_i32_f32_sdwa v18, v18 dst_sel:WORD_1 dst_unused:UNUSED_PAD src0_sel:DWORD
	v_cvt_i32_f32_e32 v19, v19
	v_lshlrev_b32_e32 v17, 8, v17
	v_lshl_add_u64 v[14:15], v[58:59], 0, s[40:41]
	v_and_b32_e32 v17, 0xff00, v17
	v_and_b32_e32 v18, 0xff0000, v18
	v_perm_b32 v16, v19, v16, s27
	v_or3_b32 v16, v16, v17, v18
	global_store_dword v[14:15], v16, off sc1
	s_nop 1
	v_and_b32_sdwa v15, v28, v83 dst_sel:DWORD dst_unused:UNUSED_PAD src0_sel:WORD_1 src1_sel:DWORD
	v_add3_u32 v16, v28, v15, s21
	v_and_b32_sdwa v15, v27, v83 dst_sel:DWORD dst_unused:UNUSED_PAD src0_sel:WORD_1 src1_sel:DWORD
	v_and_b32_sdwa v17, v29, v83 dst_sel:DWORD dst_unused:UNUSED_PAD src0_sel:WORD_1 src1_sel:DWORD
	v_and_b32_sdwa v14, v26, v83 dst_sel:DWORD dst_unused:UNUSED_PAD src0_sel:WORD_1 src1_sel:DWORD
	v_add3_u32 v15, v27, v15, s21
	v_add3_u32 v17, v29, v17, s21
	v_add3_u32 v14, v26, v14, s21
	v_and_b32_e32 v15, 0xffff0000, v15
	v_and_b32_e32 v17, 0xffff0000, v17
	v_or_b32_sdwa v15, v15, v14 dst_sel:DWORD dst_unused:UNUSED_PAD src0_sel:DWORD src1_sel:WORD_1
	v_or_b32_sdwa v14, v17, v16 dst_sel:DWORD dst_unused:UNUSED_PAD src0_sel:DWORD src1_sel:WORD_1
	v_lshl_add_u64 v[16:17], v[60:61], 0, s[44:45]
	global_store_dwordx2 v[16:17], v[14:15], off sc1
	s_nop 1
	v_mul_f32_e32 v17, 0x417e0000, v29
	v_mul_f32_e32 v16, 0x417e0000, v28
	v_mul_f32_e32 v18, 0x417e0000, v26
	v_mul_f32_e32 v19, 0x417e0000, v27
	v_med3_f32 v17, v17, s23, v5
	v_med3_f32 v16, v16, s23, v5
	v_rndne_f32_e32 v17, v17
	v_med3_f32 v18, v18, s23, v5
	v_med3_f32 v19, v19, s23, v5
	v_rndne_f32_e32 v16, v16
	v_cvt_i32_f32_e32 v17, v17
	v_rndne_f32_e32 v18, v18
	v_rndne_f32_e32 v19, v19
	v_cvt_i32_f32_e32 v16, v16
	v_cvt_i32_f32_sdwa v18, v18 dst_sel:WORD_1 dst_unused:UNUSED_PAD src0_sel:DWORD
	v_cvt_i32_f32_e32 v19, v19
	s_mov_b64 s[56:57], 0x300
	v_lshlrev_b32_e32 v17, 8, v17
	v_lshl_add_u64 v[14:15], v[58:59], 0, s[56:57]
	v_and_b32_e32 v17, 0xff00, v17
	v_and_b32_e32 v18, 0xff0000, v18
	v_perm_b32 v16, v19, v16, s27
	v_or3_b32 v16, v16, v17, v18
	global_store_dword v[14:15], v16, off sc1
	s_nop 1
	v_and_b32_sdwa v15, v32, v83 dst_sel:DWORD dst_unused:UNUSED_PAD src0_sel:WORD_1 src1_sel:DWORD
	v_add3_u32 v16, v32, v15, s21
	v_and_b32_sdwa v15, v31, v83 dst_sel:DWORD dst_unused:UNUSED_PAD src0_sel:WORD_1 src1_sel:DWORD
	v_and_b32_sdwa v17, v33, v83 dst_sel:DWORD dst_unused:UNUSED_PAD src0_sel:WORD_1 src1_sel:DWORD
	v_and_b32_sdwa v14, v30, v83 dst_sel:DWORD dst_unused:UNUSED_PAD src0_sel:WORD_1 src1_sel:DWORD
	v_add3_u32 v15, v31, v15, s21
	v_add3_u32 v17, v33, v17, s21
	v_add3_u32 v14, v30, v14, s21
	v_and_b32_e32 v15, 0xffff0000, v15
	v_and_b32_e32 v17, 0xffff0000, v17
	v_or_b32_sdwa v15, v15, v14 dst_sel:DWORD dst_unused:UNUSED_PAD src0_sel:DWORD src1_sel:WORD_1
	v_or_b32_sdwa v14, v17, v16 dst_sel:DWORD dst_unused:UNUSED_PAD src0_sel:DWORD src1_sel:WORD_1
	v_lshl_add_u64 v[16:17], v[60:61], 0, s[46:47]
	global_store_dwordx2 v[16:17], v[14:15], off sc1
	s_nop 1
	v_mul_f32_e32 v17, 0x417e0000, v33
	v_mul_f32_e32 v16, 0x417e0000, v32
	v_mul_f32_e32 v18, 0x417e0000, v30
	v_mul_f32_e32 v19, 0x417e0000, v31
	v_med3_f32 v17, v17, s23, v5
	v_med3_f32 v16, v16, s23, v5
	v_rndne_f32_e32 v17, v17
	v_med3_f32 v18, v18, s23, v5
	v_med3_f32 v19, v19, s23, v5
	v_rndne_f32_e32 v16, v16
	v_cvt_i32_f32_e32 v17, v17
	v_rndne_f32_e32 v18, v18
	v_rndne_f32_e32 v19, v19
	v_cvt_i32_f32_e32 v16, v16
	v_cvt_i32_f32_sdwa v18, v18 dst_sel:WORD_1 dst_unused:UNUSED_PAD src0_sel:DWORD
	v_cvt_i32_f32_e32 v19, v19
	v_lshlrev_b32_e32 v17, 8, v17
	v_lshl_add_u64 v[14:15], v[58:59], 0, s[42:43]
	v_and_b32_e32 v17, 0xff00, v17
	v_and_b32_e32 v18, 0xff0000, v18
	v_perm_b32 v16, v19, v16, s27
	v_or3_b32 v16, v16, v17, v18
	global_store_dword v[14:15], v16, off sc1
	s_nop 1
	v_and_b32_sdwa v15, v36, v83 dst_sel:DWORD dst_unused:UNUSED_PAD src0_sel:WORD_1 src1_sel:DWORD
	v_add3_u32 v16, v36, v15, s21
	v_and_b32_sdwa v15, v35, v83 dst_sel:DWORD dst_unused:UNUSED_PAD src0_sel:WORD_1 src1_sel:DWORD
	v_and_b32_sdwa v17, v37, v83 dst_sel:DWORD dst_unused:UNUSED_PAD src0_sel:WORD_1 src1_sel:DWORD
	v_and_b32_sdwa v14, v34, v83 dst_sel:DWORD dst_unused:UNUSED_PAD src0_sel:WORD_1 src1_sel:DWORD
	v_add3_u32 v15, v35, v15, s21
	v_add3_u32 v17, v37, v17, s21
	v_add3_u32 v14, v34, v14, s21
	v_and_b32_e32 v15, 0xffff0000, v15
	v_and_b32_e32 v17, 0xffff0000, v17
	v_or_b32_sdwa v15, v15, v14 dst_sel:DWORD dst_unused:UNUSED_PAD src0_sel:DWORD src1_sel:WORD_1
	v_or_b32_sdwa v14, v17, v16 dst_sel:DWORD dst_unused:UNUSED_PAD src0_sel:DWORD src1_sel:WORD_1
	v_lshl_add_u64 v[16:17], v[60:61], 0, s[48:49]
	global_store_dwordx2 v[16:17], v[14:15], off sc1
	s_nop 1
	v_mul_f32_e32 v17, 0x417e0000, v37
	v_mul_f32_e32 v16, 0x417e0000, v36
	v_mul_f32_e32 v18, 0x417e0000, v34
	v_mul_f32_e32 v19, 0x417e0000, v35
	v_med3_f32 v17, v17, s23, v5
	v_med3_f32 v16, v16, s23, v5
	v_rndne_f32_e32 v17, v17
	v_med3_f32 v18, v18, s23, v5
	v_med3_f32 v19, v19, s23, v5
	v_rndne_f32_e32 v16, v16
	v_cvt_i32_f32_e32 v17, v17
	v_rndne_f32_e32 v18, v18
	v_rndne_f32_e32 v19, v19
	v_cvt_i32_f32_e32 v16, v16
	v_cvt_i32_f32_sdwa v18, v18 dst_sel:WORD_1 dst_unused:UNUSED_PAD src0_sel:DWORD
	v_cvt_i32_f32_e32 v19, v19
	s_mov_b64 s[56:57], 0x500
	v_lshlrev_b32_e32 v17, 8, v17
	v_lshl_add_u64 v[14:15], v[58:59], 0, s[56:57]
	v_and_b32_e32 v17, 0xff00, v17
	v_and_b32_e32 v18, 0xff0000, v18
	v_perm_b32 v16, v19, v16, s27
	v_or3_b32 v16, v16, v17, v18
	global_store_dword v[14:15], v16, off sc1
	s_nop 1
	v_and_b32_sdwa v15, v40, v83 dst_sel:DWORD dst_unused:UNUSED_PAD src0_sel:WORD_1 src1_sel:DWORD
	v_add3_u32 v16, v40, v15, s21
	v_and_b32_sdwa v15, v39, v83 dst_sel:DWORD dst_unused:UNUSED_PAD src0_sel:WORD_1 src1_sel:DWORD
	v_and_b32_sdwa v17, v41, v83 dst_sel:DWORD dst_unused:UNUSED_PAD src0_sel:WORD_1 src1_sel:DWORD
	v_and_b32_sdwa v14, v38, v83 dst_sel:DWORD dst_unused:UNUSED_PAD src0_sel:WORD_1 src1_sel:DWORD
	v_add3_u32 v15, v39, v15, s21
	v_add3_u32 v17, v41, v17, s21
	v_add3_u32 v14, v38, v14, s21
	v_and_b32_e32 v15, 0xffff0000, v15
	v_and_b32_e32 v17, 0xffff0000, v17
	v_or_b32_sdwa v15, v15, v14 dst_sel:DWORD dst_unused:UNUSED_PAD src0_sel:DWORD src1_sel:WORD_1
	v_or_b32_sdwa v14, v17, v16 dst_sel:DWORD dst_unused:UNUSED_PAD src0_sel:DWORD src1_sel:WORD_1
	v_lshl_add_u64 v[16:17], v[60:61], 0, s[50:51]
	global_store_dwordx2 v[16:17], v[14:15], off sc1
	s_nop 1
	v_mul_f32_e32 v17, 0x417e0000, v41
	v_mul_f32_e32 v16, 0x417e0000, v40
	v_mul_f32_e32 v18, 0x417e0000, v38
	v_mul_f32_e32 v19, 0x417e0000, v39
	v_med3_f32 v17, v17, s23, v5
	v_med3_f32 v16, v16, s23, v5
	v_rndne_f32_e32 v17, v17
	v_med3_f32 v18, v18, s23, v5
	v_med3_f32 v19, v19, s23, v5
	v_rndne_f32_e32 v16, v16
	v_cvt_i32_f32_e32 v17, v17
	v_rndne_f32_e32 v18, v18
	v_rndne_f32_e32 v19, v19
	v_cvt_i32_f32_e32 v16, v16
	v_cvt_i32_f32_sdwa v18, v18 dst_sel:WORD_1 dst_unused:UNUSED_PAD src0_sel:DWORD
	v_cvt_i32_f32_e32 v19, v19
	v_lshlrev_b32_e32 v17, 8, v17
	v_lshl_add_u64 v[14:15], v[58:59], 0, s[44:45]
	v_and_b32_e32 v17, 0xff00, v17
	v_and_b32_e32 v18, 0xff0000, v18
	v_perm_b32 v16, v19, v16, s27
	v_or3_b32 v16, v16, v17, v18
	global_store_dword v[14:15], v16, off sc1
	s_nop 1
	v_and_b32_sdwa v15, v44, v83 dst_sel:DWORD dst_unused:UNUSED_PAD src0_sel:WORD_1 src1_sel:DWORD
	v_add3_u32 v16, v44, v15, s21
	v_and_b32_sdwa v15, v43, v83 dst_sel:DWORD dst_unused:UNUSED_PAD src0_sel:WORD_1 src1_sel:DWORD
	v_and_b32_sdwa v17, v45, v83 dst_sel:DWORD dst_unused:UNUSED_PAD src0_sel:WORD_1 src1_sel:DWORD
	v_and_b32_sdwa v14, v42, v83 dst_sel:DWORD dst_unused:UNUSED_PAD src0_sel:WORD_1 src1_sel:DWORD
	v_add3_u32 v15, v43, v15, s21
	v_add3_u32 v17, v45, v17, s21
	v_add3_u32 v14, v42, v14, s21
	v_and_b32_e32 v15, 0xffff0000, v15
	v_and_b32_e32 v17, 0xffff0000, v17
	v_or_b32_sdwa v15, v15, v14 dst_sel:DWORD dst_unused:UNUSED_PAD src0_sel:DWORD src1_sel:WORD_1
	v_or_b32_sdwa v14, v17, v16 dst_sel:DWORD dst_unused:UNUSED_PAD src0_sel:DWORD src1_sel:WORD_1
	v_lshl_add_u64 v[16:17], v[60:61], 0, s[52:53]
	global_store_dwordx2 v[16:17], v[14:15], off sc1
	s_nop 1
	v_mul_f32_e32 v17, 0x417e0000, v45
	v_mul_f32_e32 v16, 0x417e0000, v44
	v_mul_f32_e32 v18, 0x417e0000, v42
	v_mul_f32_e32 v19, 0x417e0000, v43
	v_med3_f32 v17, v17, s23, v5
	v_med3_f32 v16, v16, s23, v5
	v_rndne_f32_e32 v17, v17
	v_med3_f32 v18, v18, s23, v5
	v_med3_f32 v19, v19, s23, v5
	v_rndne_f32_e32 v16, v16
	v_cvt_i32_f32_e32 v17, v17
	v_rndne_f32_e32 v18, v18
	v_rndne_f32_e32 v19, v19
	v_cvt_i32_f32_e32 v16, v16
	v_cvt_i32_f32_sdwa v18, v18 dst_sel:WORD_1 dst_unused:UNUSED_PAD src0_sel:DWORD
	v_cvt_i32_f32_e32 v19, v19
	s_mov_b64 s[56:57], 0x700
	v_lshlrev_b32_e32 v17, 8, v17
	v_lshl_add_u64 v[14:15], v[58:59], 0, s[56:57]
	v_and_b32_e32 v17, 0xff00, v17
	v_and_b32_e32 v18, 0xff0000, v18
	v_perm_b32 v16, v19, v16, s27
	v_or3_b32 v16, v16, v17, v18
	global_store_dword v[14:15], v16, off sc1
	s_nop 1
	v_and_b32_sdwa v15, v48, v83 dst_sel:DWORD dst_unused:UNUSED_PAD src0_sel:WORD_1 src1_sel:DWORD
	v_add3_u32 v16, v48, v15, s21
	v_and_b32_sdwa v15, v47, v83 dst_sel:DWORD dst_unused:UNUSED_PAD src0_sel:WORD_1 src1_sel:DWORD
	v_and_b32_sdwa v17, v49, v83 dst_sel:DWORD dst_unused:UNUSED_PAD src0_sel:WORD_1 src1_sel:DWORD
	v_and_b32_sdwa v14, v46, v83 dst_sel:DWORD dst_unused:UNUSED_PAD src0_sel:WORD_1 src1_sel:DWORD
	v_add3_u32 v15, v47, v15, s21
	v_add3_u32 v17, v49, v17, s21
	v_add3_u32 v14, v46, v14, s21
	v_and_b32_e32 v15, 0xffff0000, v15
	v_and_b32_e32 v17, 0xffff0000, v17
	s_mov_b64 s[56:57], 0x1000
	v_or_b32_sdwa v15, v15, v14 dst_sel:DWORD dst_unused:UNUSED_PAD src0_sel:DWORD src1_sel:WORD_1
	v_or_b32_sdwa v14, v17, v16 dst_sel:DWORD dst_unused:UNUSED_PAD src0_sel:DWORD src1_sel:WORD_1
	v_lshl_add_u64 v[16:17], v[60:61], 0, s[56:57]
	global_store_dwordx2 v[16:17], v[14:15], off sc1
	s_nop 1
	v_mul_f32_e32 v17, 0x417e0000, v49
	v_mul_f32_e32 v16, 0x417e0000, v48
	v_mul_f32_e32 v18, 0x417e0000, v46
	v_mul_f32_e32 v19, 0x417e0000, v47
	v_med3_f32 v17, v17, s23, v5
	v_med3_f32 v16, v16, s23, v5
	v_rndne_f32_e32 v17, v17
	v_med3_f32 v18, v18, s23, v5
	v_med3_f32 v19, v19, s23, v5
	v_rndne_f32_e32 v16, v16
	v_cvt_i32_f32_e32 v17, v17
	v_rndne_f32_e32 v18, v18
	v_rndne_f32_e32 v19, v19
	v_cvt_i32_f32_e32 v16, v16
	v_cvt_i32_f32_sdwa v18, v18 dst_sel:WORD_1 dst_unused:UNUSED_PAD src0_sel:DWORD
	v_cvt_i32_f32_e32 v19, v19
	v_lshlrev_b32_e32 v17, 8, v17
	v_lshl_add_u64 v[14:15], v[58:59], 0, s[46:47]
	v_and_b32_e32 v17, 0xff00, v17
	v_and_b32_e32 v18, 0xff0000, v18
	v_perm_b32 v16, v19, v16, s27
	v_or3_b32 v16, v16, v17, v18
	global_store_dword v[14:15], v16, off sc1
	s_nop 1
	v_and_b32_sdwa v15, v52, v83 dst_sel:DWORD dst_unused:UNUSED_PAD src0_sel:WORD_1 src1_sel:DWORD
	v_add3_u32 v16, v52, v15, s21
	v_and_b32_sdwa v15, v51, v83 dst_sel:DWORD dst_unused:UNUSED_PAD src0_sel:WORD_1 src1_sel:DWORD
	v_and_b32_sdwa v17, v53, v83 dst_sel:DWORD dst_unused:UNUSED_PAD src0_sel:WORD_1 src1_sel:DWORD
	v_and_b32_sdwa v14, v50, v83 dst_sel:DWORD dst_unused:UNUSED_PAD src0_sel:WORD_1 src1_sel:DWORD
	v_add3_u32 v15, v51, v15, s21
	v_add3_u32 v17, v53, v17, s21
	v_add3_u32 v14, v50, v14, s21
	v_and_b32_e32 v15, 0xffff0000, v15
	v_and_b32_e32 v17, 0xffff0000, v17
	s_mov_b64 s[56:57], 0x1200
	v_or_b32_sdwa v15, v15, v14 dst_sel:DWORD dst_unused:UNUSED_PAD src0_sel:DWORD src1_sel:WORD_1
	v_or_b32_sdwa v14, v17, v16 dst_sel:DWORD dst_unused:UNUSED_PAD src0_sel:DWORD src1_sel:WORD_1
	v_lshl_add_u64 v[16:17], v[60:61], 0, s[56:57]
	global_store_dwordx2 v[16:17], v[14:15], off sc1
	s_nop 1
	v_mul_f32_e32 v17, 0x417e0000, v53
	v_mul_f32_e32 v16, 0x417e0000, v52
	v_mul_f32_e32 v18, 0x417e0000, v50
	v_mul_f32_e32 v19, 0x417e0000, v51
	v_med3_f32 v17, v17, s23, v5
	v_med3_f32 v16, v16, s23, v5
	v_rndne_f32_e32 v17, v17
	v_med3_f32 v18, v18, s23, v5
	v_med3_f32 v19, v19, s23, v5
	v_rndne_f32_e32 v16, v16
	v_cvt_i32_f32_e32 v17, v17
	v_rndne_f32_e32 v18, v18
	v_rndne_f32_e32 v19, v19
	v_cvt_i32_f32_e32 v16, v16
	v_cvt_i32_f32_sdwa v18, v18 dst_sel:WORD_1 dst_unused:UNUSED_PAD src0_sel:DWORD
	v_cvt_i32_f32_e32 v19, v19
	s_mov_b64 s[56:57], 0x900
	v_lshlrev_b32_e32 v17, 8, v17
	v_lshl_add_u64 v[14:15], v[58:59], 0, s[56:57]
	v_and_b32_e32 v17, 0xff00, v17
	v_and_b32_e32 v18, 0xff0000, v18
	v_perm_b32 v16, v19, v16, s27
	v_or3_b32 v16, v16, v17, v18
	global_store_dword v[14:15], v16, off sc1
	s_nop 1
	v_and_b32_sdwa v15, v56, v83 dst_sel:DWORD dst_unused:UNUSED_PAD src0_sel:WORD_1 src1_sel:DWORD
	v_add3_u32 v16, v56, v15, s21
	v_and_b32_sdwa v15, v55, v83 dst_sel:DWORD dst_unused:UNUSED_PAD src0_sel:WORD_1 src1_sel:DWORD
	v_and_b32_sdwa v17, v57, v83 dst_sel:DWORD dst_unused:UNUSED_PAD src0_sel:WORD_1 src1_sel:DWORD
	v_and_b32_sdwa v14, v54, v83 dst_sel:DWORD dst_unused:UNUSED_PAD src0_sel:WORD_1 src1_sel:DWORD
	v_add3_u32 v15, v55, v15, s21
	v_add3_u32 v17, v57, v17, s21
	v_add3_u32 v14, v54, v14, s21
	v_and_b32_e32 v15, 0xffff0000, v15
	v_and_b32_e32 v17, 0xffff0000, v17
	s_mov_b64 s[56:57], 0x1400
	v_or_b32_sdwa v15, v15, v14 dst_sel:DWORD dst_unused:UNUSED_PAD src0_sel:DWORD src1_sel:WORD_1
	v_or_b32_sdwa v14, v17, v16 dst_sel:DWORD dst_unused:UNUSED_PAD src0_sel:DWORD src1_sel:WORD_1
	v_lshl_add_u64 v[16:17], v[60:61], 0, s[56:57]
	global_store_dwordx2 v[16:17], v[14:15], off sc1
	s_nop 1
	v_mul_f32_e32 v17, 0x417e0000, v57
	v_mul_f32_e32 v16, 0x417e0000, v56
	v_mul_f32_e32 v18, 0x417e0000, v54
	v_mul_f32_e32 v19, 0x417e0000, v55
	v_med3_f32 v17, v17, s23, v5
	v_med3_f32 v16, v16, s23, v5
	v_rndne_f32_e32 v17, v17
	v_med3_f32 v18, v18, s23, v5
	v_med3_f32 v19, v19, s23, v5
	v_rndne_f32_e32 v16, v16
	v_cvt_i32_f32_e32 v17, v17
	v_rndne_f32_e32 v18, v18
	v_rndne_f32_e32 v19, v19
	v_cvt_i32_f32_e32 v16, v16
	v_cvt_i32_f32_sdwa v18, v18 dst_sel:WORD_1 dst_unused:UNUSED_PAD src0_sel:DWORD
	v_cvt_i32_f32_e32 v19, v19
	v_lshlrev_b32_e32 v17, 8, v17
	v_lshl_add_u64 v[14:15], v[58:59], 0, s[48:49]
	v_and_b32_e32 v17, 0xff00, v17
	v_and_b32_e32 v18, 0xff0000, v18
	v_perm_b32 v16, v19, v16, s27
	v_or3_b32 v16, v16, v17, v18
	global_store_dword v[14:15], v16, off sc1
	s_nop 1
	v_and_b32_sdwa v15, v64, v83 dst_sel:DWORD dst_unused:UNUSED_PAD src0_sel:WORD_1 src1_sel:DWORD
	v_add3_u32 v16, v64, v15, s21
	v_and_b32_sdwa v15, v63, v83 dst_sel:DWORD dst_unused:UNUSED_PAD src0_sel:WORD_1 src1_sel:DWORD
	v_and_b32_sdwa v17, v65, v83 dst_sel:DWORD dst_unused:UNUSED_PAD src0_sel:WORD_1 src1_sel:DWORD
	v_and_b32_sdwa v14, v62, v83 dst_sel:DWORD dst_unused:UNUSED_PAD src0_sel:WORD_1 src1_sel:DWORD
	v_add3_u32 v15, v63, v15, s21
	v_add3_u32 v17, v65, v17, s21
	v_add3_u32 v14, v62, v14, s21
	v_and_b32_e32 v15, 0xffff0000, v15
	v_and_b32_e32 v17, 0xffff0000, v17
	s_mov_b64 s[56:57], 0x1600
	v_or_b32_sdwa v15, v15, v14 dst_sel:DWORD dst_unused:UNUSED_PAD src0_sel:DWORD src1_sel:WORD_1
	v_or_b32_sdwa v14, v17, v16 dst_sel:DWORD dst_unused:UNUSED_PAD src0_sel:DWORD src1_sel:WORD_1
	v_lshl_add_u64 v[16:17], v[60:61], 0, s[56:57]
	global_store_dwordx2 v[16:17], v[14:15], off sc1
	s_nop 1
	v_mul_f32_e32 v17, 0x417e0000, v65
	v_mul_f32_e32 v16, 0x417e0000, v64
	v_mul_f32_e32 v18, 0x417e0000, v62
	v_mul_f32_e32 v19, 0x417e0000, v63
	v_med3_f32 v17, v17, s23, v5
	v_med3_f32 v16, v16, s23, v5
	v_rndne_f32_e32 v17, v17
	v_med3_f32 v18, v18, s23, v5
	v_med3_f32 v19, v19, s23, v5
	v_rndne_f32_e32 v16, v16
	v_cvt_i32_f32_e32 v17, v17
	v_rndne_f32_e32 v18, v18
	v_rndne_f32_e32 v19, v19
	v_cvt_i32_f32_e32 v16, v16
	v_cvt_i32_f32_sdwa v18, v18 dst_sel:WORD_1 dst_unused:UNUSED_PAD src0_sel:DWORD
	v_cvt_i32_f32_e32 v19, v19
	s_mov_b64 s[56:57], 0xb00
	v_lshlrev_b32_e32 v17, 8, v17
	v_lshl_add_u64 v[14:15], v[58:59], 0, s[56:57]
	v_and_b32_e32 v17, 0xff00, v17
	v_and_b32_e32 v18, 0xff0000, v18
	v_perm_b32 v16, v19, v16, s27
	v_or3_b32 v16, v16, v17, v18
	global_store_dword v[14:15], v16, off sc1
	s_nop 1
	v_and_b32_sdwa v15, v70, v83 dst_sel:DWORD dst_unused:UNUSED_PAD src0_sel:WORD_1 src1_sel:DWORD
	v_add3_u32 v16, v70, v15, s21
	v_and_b32_sdwa v15, v69, v83 dst_sel:DWORD dst_unused:UNUSED_PAD src0_sel:WORD_1 src1_sel:DWORD
	v_and_b32_sdwa v17, v71, v83 dst_sel:DWORD dst_unused:UNUSED_PAD src0_sel:WORD_1 src1_sel:DWORD
	v_and_b32_sdwa v14, v68, v83 dst_sel:DWORD dst_unused:UNUSED_PAD src0_sel:WORD_1 src1_sel:DWORD
	v_add3_u32 v15, v69, v15, s21
	v_add3_u32 v17, v71, v17, s21
	v_add3_u32 v14, v68, v14, s21
	v_and_b32_e32 v15, 0xffff0000, v15
	v_and_b32_e32 v17, 0xffff0000, v17
	s_mov_b64 s[56:57], 0x1800
	v_or_b32_sdwa v15, v15, v14 dst_sel:DWORD dst_unused:UNUSED_PAD src0_sel:DWORD src1_sel:WORD_1
	v_or_b32_sdwa v14, v17, v16 dst_sel:DWORD dst_unused:UNUSED_PAD src0_sel:DWORD src1_sel:WORD_1
	v_lshl_add_u64 v[16:17], v[60:61], 0, s[56:57]
	global_store_dwordx2 v[16:17], v[14:15], off sc1
	s_nop 1
	v_mul_f32_e32 v17, 0x417e0000, v71
	v_mul_f32_e32 v16, 0x417e0000, v70
	v_mul_f32_e32 v18, 0x417e0000, v68
	v_mul_f32_e32 v19, 0x417e0000, v69
	v_med3_f32 v17, v17, s23, v5
	v_med3_f32 v16, v16, s23, v5
	v_rndne_f32_e32 v17, v17
	v_med3_f32 v18, v18, s23, v5
	v_med3_f32 v19, v19, s23, v5
	v_rndne_f32_e32 v16, v16
	v_cvt_i32_f32_e32 v17, v17
	v_rndne_f32_e32 v18, v18
	v_rndne_f32_e32 v19, v19
	v_cvt_i32_f32_e32 v16, v16
	v_cvt_i32_f32_sdwa v18, v18 dst_sel:WORD_1 dst_unused:UNUSED_PAD src0_sel:DWORD
	v_cvt_i32_f32_e32 v19, v19
	v_lshlrev_b32_e32 v17, 8, v17
	v_lshl_add_u64 v[14:15], v[58:59], 0, s[50:51]
	v_and_b32_e32 v17, 0xff00, v17
	v_and_b32_e32 v18, 0xff0000, v18
	v_perm_b32 v16, v19, v16, s27
	v_or3_b32 v16, v16, v17, v18
	global_store_dword v[14:15], v16, off sc1
	s_nop 1
	v_and_b32_sdwa v15, v74, v83 dst_sel:DWORD dst_unused:UNUSED_PAD src0_sel:WORD_1 src1_sel:DWORD
	v_add3_u32 v16, v74, v15, s21
	v_and_b32_sdwa v15, v73, v83 dst_sel:DWORD dst_unused:UNUSED_PAD src0_sel:WORD_1 src1_sel:DWORD
	v_and_b32_sdwa v17, v75, v83 dst_sel:DWORD dst_unused:UNUSED_PAD src0_sel:WORD_1 src1_sel:DWORD
	v_and_b32_sdwa v14, v72, v83 dst_sel:DWORD dst_unused:UNUSED_PAD src0_sel:WORD_1 src1_sel:DWORD
	v_add3_u32 v15, v73, v15, s21
	v_add3_u32 v17, v75, v17, s21
	v_add3_u32 v14, v72, v14, s21
	v_and_b32_e32 v15, 0xffff0000, v15
	v_and_b32_e32 v17, 0xffff0000, v17
	s_mov_b64 s[56:57], 0x1a00
	v_or_b32_sdwa v15, v15, v14 dst_sel:DWORD dst_unused:UNUSED_PAD src0_sel:DWORD src1_sel:WORD_1
	v_or_b32_sdwa v14, v17, v16 dst_sel:DWORD dst_unused:UNUSED_PAD src0_sel:DWORD src1_sel:WORD_1
	v_lshl_add_u64 v[16:17], v[60:61], 0, s[56:57]
	global_store_dwordx2 v[16:17], v[14:15], off sc1
	s_nop 1
	v_mul_f32_e32 v17, 0x417e0000, v75
	v_mul_f32_e32 v16, 0x417e0000, v74
	v_mul_f32_e32 v18, 0x417e0000, v72
	v_mul_f32_e32 v19, 0x417e0000, v73
	v_med3_f32 v17, v17, s23, v5
	v_med3_f32 v16, v16, s23, v5
	v_rndne_f32_e32 v17, v17
	v_med3_f32 v18, v18, s23, v5
	v_med3_f32 v19, v19, s23, v5
	v_rndne_f32_e32 v16, v16
	v_cvt_i32_f32_e32 v17, v17
	v_rndne_f32_e32 v18, v18
	v_rndne_f32_e32 v19, v19
	v_cvt_i32_f32_e32 v16, v16
	v_cvt_i32_f32_sdwa v18, v18 dst_sel:WORD_1 dst_unused:UNUSED_PAD src0_sel:DWORD
	v_cvt_i32_f32_e32 v19, v19
	s_mov_b64 s[56:57], 0xd00
	v_lshlrev_b32_e32 v17, 8, v17
	v_lshl_add_u64 v[14:15], v[58:59], 0, s[56:57]
	v_and_b32_e32 v17, 0xff00, v17
	v_and_b32_e32 v18, 0xff0000, v18
	v_perm_b32 v16, v19, v16, s27
	v_or3_b32 v16, v16, v17, v18
	global_store_dword v[14:15], v16, off sc1
	s_nop 1
	v_and_b32_sdwa v15, v78, v83 dst_sel:DWORD dst_unused:UNUSED_PAD src0_sel:WORD_1 src1_sel:DWORD
	v_add3_u32 v16, v78, v15, s21
	v_and_b32_sdwa v15, v77, v83 dst_sel:DWORD dst_unused:UNUSED_PAD src0_sel:WORD_1 src1_sel:DWORD
	v_and_b32_sdwa v17, v79, v83 dst_sel:DWORD dst_unused:UNUSED_PAD src0_sel:WORD_1 src1_sel:DWORD
	v_and_b32_sdwa v14, v76, v83 dst_sel:DWORD dst_unused:UNUSED_PAD src0_sel:WORD_1 src1_sel:DWORD
	v_add3_u32 v15, v77, v15, s21
	v_add3_u32 v17, v79, v17, s21
	v_add3_u32 v14, v76, v14, s21
	v_and_b32_e32 v15, 0xffff0000, v15
	v_and_b32_e32 v17, 0xffff0000, v17
	s_mov_b64 s[56:57], 0x1c00
	v_or_b32_sdwa v15, v15, v14 dst_sel:DWORD dst_unused:UNUSED_PAD src0_sel:DWORD src1_sel:WORD_1
	v_or_b32_sdwa v14, v17, v16 dst_sel:DWORD dst_unused:UNUSED_PAD src0_sel:DWORD src1_sel:WORD_1
	v_lshl_add_u64 v[16:17], v[60:61], 0, s[56:57]
	global_store_dwordx2 v[16:17], v[14:15], off sc1
	s_nop 1
	v_mul_f32_e32 v17, 0x417e0000, v79
	v_mul_f32_e32 v16, 0x417e0000, v78
	v_mul_f32_e32 v18, 0x417e0000, v76
	v_mul_f32_e32 v19, 0x417e0000, v77
	v_med3_f32 v17, v17, s23, v5
	v_med3_f32 v16, v16, s23, v5
	v_rndne_f32_e32 v17, v17
	v_med3_f32 v18, v18, s23, v5
	v_med3_f32 v19, v19, s23, v5
	v_rndne_f32_e32 v16, v16
	v_cvt_i32_f32_e32 v17, v17
	v_rndne_f32_e32 v18, v18
	v_rndne_f32_e32 v19, v19
	v_cvt_i32_f32_e32 v16, v16
	v_cvt_i32_f32_sdwa v18, v18 dst_sel:WORD_1 dst_unused:UNUSED_PAD src0_sel:DWORD
	v_cvt_i32_f32_e32 v19, v19
	v_lshlrev_b32_e32 v17, 8, v17
	v_lshl_add_u64 v[14:15], v[58:59], 0, s[52:53]
	v_and_b32_e32 v17, 0xff00, v17
	v_and_b32_e32 v18, 0xff0000, v18
	v_perm_b32 v16, v19, v16, s27
	v_or3_b32 v16, v16, v17, v18
	global_store_dword v[14:15], v16, off sc1
	s_nop 1
	v_and_b32_sdwa v15, v0, v83 dst_sel:DWORD dst_unused:UNUSED_PAD src0_sel:WORD_1 src1_sel:DWORD
	v_and_b32_sdwa v17, v1, v83 dst_sel:DWORD dst_unused:UNUSED_PAD src0_sel:WORD_1 src1_sel:DWORD
	v_and_b32_sdwa v14, v2, v83 dst_sel:DWORD dst_unused:UNUSED_PAD src0_sel:WORD_1 src1_sel:DWORD
	v_add3_u32 v16, v0, v15, s21
	v_and_b32_sdwa v15, v3, v83 dst_sel:DWORD dst_unused:UNUSED_PAD src0_sel:WORD_1 src1_sel:DWORD
	v_add3_u32 v17, v1, v17, s21
	v_mul_f32_e32 v1, 0x417e0000, v1
	v_add3_u32 v14, v2, v14, s21
	v_add3_u32 v15, v3, v15, s21
	v_mul_f32_e32 v0, 0x417e0000, v0
	v_mul_f32_e32 v2, 0x417e0000, v2
	v_mul_f32_e32 v3, 0x417e0000, v3
	v_med3_f32 v1, v1, s23, v5
	v_med3_f32 v0, v0, s23, v5
	v_rndne_f32_e32 v1, v1
	v_med3_f32 v2, v2, s23, v5
	v_med3_f32 v3, v3, s23, v5
	v_rndne_f32_e32 v0, v0
	v_cvt_i32_f32_e32 v1, v1
	v_rndne_f32_e32 v2, v2
	v_rndne_f32_e32 v3, v3
	v_cvt_i32_f32_e32 v0, v0
	v_cvt_i32_f32_sdwa v2, v2 dst_sel:WORD_1 dst_unused:UNUSED_PAD src0_sel:DWORD
	v_cvt_i32_f32_e32 v3, v3
	v_and_b32_e32 v15, 0xffff0000, v15
	v_and_b32_e32 v17, 0xffff0000, v17
	s_mov_b64 s[56:57], 0x1e00
	v_lshlrev_b32_e32 v1, 8, v1
	v_or_b32_sdwa v15, v15, v14 dst_sel:DWORD dst_unused:UNUSED_PAD src0_sel:DWORD src1_sel:WORD_1
	v_or_b32_sdwa v14, v17, v16 dst_sel:DWORD dst_unused:UNUSED_PAD src0_sel:DWORD src1_sel:WORD_1
	v_lshl_add_u64 v[16:17], v[60:61], 0, s[56:57]
	global_store_dwordx2 v[16:17], v[14:15], off sc1
	s_nop 1
	s_mov_b64 s[56:57], 0xf00
	v_and_b32_e32 v1, 0xff00, v1
	v_and_b32_e32 v2, 0xff0000, v2
	v_perm_b32 v0, v3, v0, s27
	v_lshl_add_u64 v[14:15], v[58:59], 0, s[56:57]
	v_or3_b32 v0, v0, v1, v2
	global_store_dword v[14:15], v0, off sc1
	s_nop 1
	s_and_saveexec_b64 s[56:57], s[16:17]
	s_cbranch_execz .LBB0_1258
	v_mov_b32_e32 v0, s55
	v_mov_b32_e32 v1, s39
	v_pk_add_f32 v[0:1], s[18:19], v[0:1]
	s_nop 0
	v_pk_mul_f32 v[0:1], v[0:1], s[54:55] op_sel_hi:[1,0]
	s_nop 0
	v_fma_f32 v0, -v1, v1, v0
	v_max_f32_e32 v0, 0, v0
	v_add_f32_e32 v0, 0x3727c5ac, v0
	v_mul_f32_e32 v2, 0x4f800000, v0
	v_cmp_gt_f32_e32 vcc, s29, v0
	s_nop 1
	v_cndmask_b32_e32 v0, v0, v2, vcc
	v_sqrt_f32_e32 v2, v0
	s_nop 0
	v_add_u32_e32 v3, -1, v2
	v_fma_f32 v14, -v3, v2, v0
	v_cmp_ge_f32_e64 s[18:19], 0, v14
	v_add_u32_e32 v14, 1, v2
	s_nop 0
	v_cndmask_b32_e64 v3, v2, v3, s[18:19]
	v_fma_f32 v2, -v14, v2, v0
	v_cmp_lt_f32_e64 s[18:19], 0, v2
	s_nop 1
	v_cndmask_b32_e64 v2, v3, v14, s[18:19]
	v_mul_f32_e32 v3, 0x37800000, v2
	v_cndmask_b32_e32 v2, v2, v3, vcc
	v_cmp_class_f32_e32 vcc, v0, v82
	s_nop 1
	v_cndmask_b32_e32 v0, v2, v0, vcc
	v_div_scale_f32 v2, s[18:19], v0, v0, 1.0
	v_rcp_f32_e32 v3, v2
	s_nop 0
	v_fma_f32 v14, -v2, v3, 1.0
	v_fmac_f32_e32 v3, v14, v3
	v_div_scale_f32 v14, vcc, 1.0, v0, 1.0
	v_mul_f32_e32 v15, v14, v3
	v_fma_f32 v16, -v2, v15, v14
	v_fmac_f32_e32 v15, v16, v3
	v_fma_f32 v2, -v2, v15, v14
	v_div_fmas_f32 v2, v2, v3, v15
	v_div_fixup_f32 v3, v2, v0, 1.0
	v_mov_b32_e32 v2, v1
	v_mov_b64_e32 v[0:1], s[8:9]
	global_store_dwordx2 v[0:1], v[2:3], off sc1
	s_nop 1
	s_branch .LBB0_1258

.LBB0_1549:
	v_lshl_add_u64 v[248:249], s[12:13], 0, v[82:83]
	s_mov_b64 s[98:99], 0x100000
	v_lshl_add_u64 v[238:239], v[248:249], 0, s[98:99]
	s_mov_b64 s[98:99], 0x800000
	v_lshl_add_u64 v[240:241], v[238:239], 0, s[98:99]
	v_lshl_add_u64 v[242:243], v[240:241], 0, s[98:99]
	v_lshl_add_u64 v[244:245], v[242:243], 0, s[98:99]
	v_lshl_add_u64 v[246:247], s[12:13], 0, v[78:79]
	s_mov_b64 s[98:99], 0x3d400000
	v_lshl_add_u64 v[246:247], v[246:247], 0, s[98:99]
	s_add_u32 s100, s12, s10
	s_addc_u32 s101, s13, s11
	global_load_dwordx2 v[166:167], v25, s[100:101]
	global_load_dwordx2 v[168:169], v[246:247], off
	global_load_dwordx2 v[170:171], v[238:239], off
	global_load_dwordx2 v[172:173], v[240:241], off
	global_load_dwordx2 v[174:175], v[242:243], off
	global_load_dwordx2 v[176:177], v[244:245], off
	global_load_dwordx2 v[178:179], v[244:245], off offset:512
	global_load_dwordx2 v[180:181], v[242:243], off offset:512
	global_load_dwordx2 v[182:183], v[240:241], off offset:512
	global_load_dwordx2 v[184:185], v[238:239], off offset:512
	global_load_dwordx2 v[186:187], v[246:247], off offset:512
	global_load_dwordx2 v[188:189], v[246:247], off offset:1024
	global_load_dwordx4 v[190:193], v[26:27], off offset:2048
	global_load_dwordx4 v[194:197], v[28:29], off offset:2048
	global_load_dwordx2 v[198:199], v[238:239], off offset:1024
	global_load_dwordx2 v[200:201], v[240:241], off offset:1024
	global_load_dwordx2 v[202:203], v[242:243], off offset:1024
	global_load_dwordx2 v[204:205], v[244:245], off offset:1024
	global_load_dwordx2 v[206:207], v[244:245], off offset:1536
	global_load_dwordx2 v[208:209], v[242:243], off offset:1536
	global_load_dwordx2 v[210:211], v[240:241], off offset:1536
	global_load_dwordx2 v[212:213], v[238:239], off offset:1536
	global_load_dwordx2 v[214:215], v[246:247], off offset:1536
	v_lshl_add_u64 v[84:85], s[12:13], 0, v[78:79]
	s_add_u32 s8, s12, s10
	v_add_co_u32_e32 v116, vcc, 0x3d400000, v84
	s_addc_u32 s9, s13, s11
	s_nop 0
	v_addc_co_u32_e32 v117, vcc, 0, v85, vcc
	v_lshl_add_u64 v[86:87], s[12:13], 0, v[82:83]
	s_mov_b32 s8, 0x100000
	v_add_co_u32_e32 v118, vcc, s8, v86
	s_mov_b32 s8, 0x101000
	s_nop 0
	v_addc_co_u32_e32 v119, vcc, 0, v87, vcc
	s_mov_b64 s[24:25], 0x6b00000
	s_waitcnt vmcnt(21)
	v_mov_b32_e32 v16, v166
	v_mov_b32_e32 v17, v167
	v_mov_b32_e32 v18, v168
	v_mov_b32_e32 v19, v169
	v_lshlrev_b32_e32 v20, 16, v18
	v_and_b32_e32 v18, 0xffff0000, v18
	v_lshlrev_b32_e32 v22, 16, v19
	v_and_b32_e32 v21, 0xffff0000, v19
	v_sub_f32_e32 v19, v18, v16
	v_sub_f32_e32 v18, v20, v16
	v_pk_mul_f32 v[18:19], v[16:17], v[18:19] op_sel:[1,0]
	v_sub_f32_e32 v21, v21, v16
	v_pk_fma_f32 v[88:89], v[0:1], v[18:19], v[8:9]
	v_add_co_u32_e32 v18, vcc, s8, v86
	s_mov_b32 s8, 0x900000
	s_nop 0
	v_addc_co_u32_e32 v19, vcc, 0, v87, vcc
	v_sub_f32_e32 v20, v22, v16
	v_add_co_u32_e32 v120, vcc, s8, v86
	v_pk_mul_f32 v[20:21], v[16:17], v[20:21] op_sel:[1,0]
	s_nop 0
	v_addc_co_u32_e32 v121, vcc, 0, v87, vcc
	s_mov_b32 s8, 0x901000
	v_pk_fma_f32 v[90:91], v[2:3], v[20:21], v[10:11]
	v_add_co_u32_e32 v20, vcc, s8, v86
	s_mov_b32 s8, 0x1100000
	s_nop 0
	v_addc_co_u32_e32 v21, vcc, 0, v87, vcc
	v_add_co_u32_e32 v122, vcc, s8, v86
	s_mov_b32 s8, 0x1101000
	s_nop 0
	v_addc_co_u32_e32 v123, vcc, 0, v87, vcc
	v_add_co_u32_e32 v22, vcc, s8, v86
	s_mov_b32 s8, 0x1900000
	s_nop 0
	v_addc_co_u32_e32 v23, vcc, 0, v87, vcc
	v_add_co_u32_e32 v124, vcc, s8, v86
	s_mov_b32 s8, 0x1901000
	s_nop 0
	v_addc_co_u32_e32 v125, vcc, 0, v87, vcc
	v_add_co_u32_e32 v98, vcc, s8, v86
	v_addc_co_u32_e32 v99, vcc, 0, v87, vcc
	s_mov_b32 s8, 0x3d401000
	s_waitcnt vmcnt(20)
	v_mov_b32_e32 v92, v170
	v_mov_b32_e32 v93, v171
	v_lshlrev_b32_e32 v100, 16, v92
	v_and_b32_e32 v101, 0xffff0000, v92
	v_lshlrev_b32_e32 v92, 16, v93
	v_and_b32_e32 v93, 0xffff0000, v93
	s_waitcnt vmcnt(19)
	v_mov_b32_e32 v94, v172
	v_mov_b32_e32 v95, v173
	v_lshlrev_b32_e32 v102, 16, v94
	v_and_b32_e32 v103, 0xffff0000, v94
	v_lshlrev_b32_e32 v94, 16, v95
	v_and_b32_e32 v95, 0xffff0000, v95
	v_pk_add_f32 v[100:101], v[100:101], v[102:103]
	v_pk_add_f32 v[92:93], v[92:93], v[94:95]
	s_waitcnt vmcnt(18)
	v_mov_b32_e32 v96, v174
	v_mov_b32_e32 v97, v175
	v_lshlrev_b32_e32 v94, 16, v96
	v_and_b32_e32 v95, 0xffff0000, v96
	v_lshlrev_b32_e32 v96, 16, v97
	v_and_b32_e32 v97, 0xffff0000, v97
	s_waitcnt vmcnt(17)
	v_mov_b32_e32 v86, v176
	v_mov_b32_e32 v87, v177
	v_lshlrev_b32_e32 v102, 16, v86
	v_and_b32_e32 v103, 0xffff0000, v86
	v_lshlrev_b32_e32 v86, 16, v87
	v_and_b32_e32 v87, 0xffff0000, v87
	v_pk_add_f32 v[94:95], v[94:95], v[102:103]
	v_pk_add_f32 v[86:87], v[96:97], v[86:87]
	s_nop 0
	v_pk_add_f32 v[86:87], v[92:93], v[86:87]
	v_pk_add_f32 v[92:93], v[100:101], v[94:95]
	v_pk_mul_f32 v[86:87], v[86:87], s[26:27] op_sel_hi:[1,0]
	v_pk_mul_f32 v[92:93], v[92:93], s[26:27] op_sel_hi:[1,0]
	v_pk_fma_f32 v[86:87], v[90:91], s[34:35], v[86:87] op_sel_hi:[1,0,1]
	v_pk_fma_f32 v[88:89], v[88:89], s[34:35], v[92:93] op_sel_hi:[1,0,1]
	v_add_f32_e32 v91, v86, v87
	v_add_f32_e32 v90, v88, v89
	v_add_f32_e32 v90, v90, v91
	v_add_f32_e32 v108, 0, v90
	v_mul_f32_e32 v90, v89, v89
	v_mul_f32_e32 v91, v87, v87
	v_fmac_f32_e32 v90, v88, v88
	v_fmac_f32_e32 v91, v86, v86
	v_add_f32_e32 v109, v90, v91
	s_waitcnt vmcnt(14)
	v_mov_b32_e32 v90, v178
	v_mov_b32_e32 v91, v179
	v_mov_b32_e32 v92, v180
	v_mov_b32_e32 v93, v181
	v_mov_b32_e32 v94, v182
	v_mov_b32_e32 v95, v183
	v_lshlrev_b32_e32 v106, 16, v94
	s_waitcnt vmcnt(13)
	v_mov_b32_e32 v96, v184
	v_mov_b32_e32 v97, v185
	v_lshlrev_b32_e32 v104, 16, v96
	s_waitcnt vmcnt(12)
	v_mov_b32_e32 v100, v186
	v_mov_b32_e32 v101, v187
	v_lshlrev_b32_e32 v102, 16, v100
	v_and_b32_e32 v103, 0xffff0000, v100
	v_lshlrev_b32_e32 v100, 16, v101
	v_and_b32_e32 v101, 0xffff0000, v101
	v_sub_f32_e32 v101, v101, v16
	v_sub_f32_e32 v100, v100, v16
	v_sub_f32_e32 v103, v103, v16
	v_sub_f32_e32 v102, v102, v16
	v_and_b32_e32 v105, 0xffff0000, v96
	v_lshlrev_b32_e32 v96, 16, v97
	v_and_b32_e32 v97, 0xffff0000, v97
	v_and_b32_e32 v107, 0xffff0000, v94
	v_lshlrev_b32_e32 v94, 16, v95
	v_and_b32_e32 v95, 0xffff0000, v95
	v_pk_mul_f32 v[102:103], v[16:17], v[102:103] op_sel:[1,0]
	v_pk_mul_f32 v[100:101], v[16:17], v[100:101] op_sel:[1,0]
	v_pk_add_f32 v[94:95], v[94:95], v[96:97]
	v_pk_add_f32 v[96:97], v[106:107], v[104:105]
	v_lshlrev_b32_e32 v104, 16, v92
	v_and_b32_e32 v105, 0xffff0000, v92
	v_lshlrev_b32_e32 v92, 16, v93
	v_and_b32_e32 v93, 0xffff0000, v93
	v_lshlrev_b32_e32 v106, 16, v90
	v_and_b32_e32 v107, 0xffff0000, v90
	v_lshlrev_b32_e32 v90, 16, v91
	v_and_b32_e32 v91, 0xffff0000, v91
	v_pk_fma_f32 v[100:101], v[6:7], v[100:101], v[14:15]
	v_pk_fma_f32 v[102:103], v[4:5], v[102:103], v[12:13]
	v_pk_add_f32 v[90:91], v[90:91], v[92:93]
	v_pk_add_f32 v[92:93], v[106:107], v[104:105]
	v_pk_add_f32 v[90:91], v[90:91], v[94:95]
	v_pk_add_f32 v[92:93], v[92:93], v[96:97]
	v_pk_mul_f32 v[94:95], v[102:103], s[34:35] op_sel_hi:[1,0]
	v_pk_mul_f32 v[96:97], v[100:101], s[34:35] op_sel_hi:[1,0]
	v_pk_fma_f32 v[92:93], v[92:93], s[26:27], v[94:95] op_sel_hi:[1,0,1]
	v_pk_fma_f32 v[90:91], v[90:91], s[26:27], v[96:97] op_sel_hi:[1,0,1]
	v_add_f32_e32 v94, v92, v93
	v_add_f32_e32 v95, v90, v91
	v_add_f32_e32 v94, v94, v95
	v_add_f32_e32 v100, v108, v94
	v_mul_f32_e32 v94, v93, v93
	v_mul_f32_e32 v95, v91, v91
	v_fmac_f32_e32 v94, v92, v92
	v_fmac_f32_e32 v95, v90, v90
	v_add_f32_e32 v94, v94, v95
	v_add_f32_e32 v101, v109, v94
	s_waitcnt vmcnt(11)
	v_mov_b32_e32 v94, v188
	v_mov_b32_e32 v95, v189
	v_lshlrev_b32_e32 v96, 16, v94
	v_and_b32_e32 v94, 0xffff0000, v94
	v_lshlrev_b32_e32 v102, 16, v95
	v_and_b32_e32 v97, 0xffff0000, v95
	v_sub_f32_e32 v95, v94, v16
	v_sub_f32_e32 v94, v96, v16
	v_sub_f32_e32 v97, v97, v16
	v_sub_f32_e32 v96, v102, v16
	v_pk_mul_f32 v[106:107], v[16:17], v[96:97] op_sel:[1,0]
	v_pk_mul_f32 v[108:109], v[16:17], v[94:95] op_sel:[1,0]
	s_waitcnt vmcnt(9)
	v_mov_b32_e32 v94, v190
	v_mov_b32_e32 v95, v191
	v_mov_b32_e32 v96, v192
	v_mov_b32_e32 v97, v193
	v_mov_b32_e32 v102, v194
	v_mov_b32_e32 v103, v195
	v_mov_b32_e32 v104, v196
	v_mov_b32_e32 v105, v197
	v_pk_fma_f32 v[102:103], v[94:95], v[108:109], v[102:103]
	v_pk_fma_f32 v[94:95], v[96:97], v[106:107], v[104:105]
	s_waitcnt vmcnt(8)
	v_mov_b32_e32 v96, v198
	v_mov_b32_e32 v97, v199
	v_lshlrev_b32_e32 v110, 16, v96
	v_and_b32_e32 v111, 0xffff0000, v96
	v_lshlrev_b32_e32 v96, 16, v97
	v_and_b32_e32 v97, 0xffff0000, v97
	s_waitcnt vmcnt(7)
	v_mov_b32_e32 v104, v200
	v_mov_b32_e32 v105, v201
	v_lshlrev_b32_e32 v112, 16, v104
	v_and_b32_e32 v113, 0xffff0000, v104
	v_lshlrev_b32_e32 v104, 16, v105
	v_and_b32_e32 v105, 0xffff0000, v105
	v_pk_add_f32 v[110:111], v[110:111], v[112:113]
	v_pk_add_f32 v[96:97], v[96:97], v[104:105]
	s_waitcnt vmcnt(6)
	v_mov_b32_e32 v106, v202
	v_mov_b32_e32 v107, v203
	v_lshlrev_b32_e32 v104, 16, v106
	v_and_b32_e32 v105, 0xffff0000, v106
	v_lshlrev_b32_e32 v106, 16, v107
	v_and_b32_e32 v107, 0xffff0000, v107
	s_waitcnt vmcnt(5)
	v_mov_b32_e32 v108, v204
	v_mov_b32_e32 v109, v205
	v_lshlrev_b32_e32 v112, 16, v108
	v_and_b32_e32 v113, 0xffff0000, v108
	v_lshlrev_b32_e32 v108, 16, v109
	v_and_b32_e32 v109, 0xffff0000, v109
	v_pk_add_f32 v[104:105], v[104:105], v[112:113]
	v_pk_add_f32 v[106:107], v[106:107], v[108:109]
	v_pk_add_f32 v[104:105], v[110:111], v[104:105]
	v_pk_add_f32 v[96:97], v[96:97], v[106:107]
	v_pk_mul_f32 v[104:105], v[104:105], s[26:27] op_sel_hi:[1,0]
	v_pk_mul_f32 v[96:97], v[96:97], s[26:27] op_sel_hi:[1,0]
	s_nop 0
	v_pk_fma_f32 v[94:95], v[94:95], s[34:35], v[96:97] op_sel_hi:[1,0,1]
	v_pk_fma_f32 v[96:97], v[102:103], s[34:35], v[104:105] op_sel_hi:[1,0,1]
	v_add_f32_e32 v103, v94, v95
	v_add_f32_e32 v102, v96, v97
	v_add_f32_e32 v102, v102, v103
	v_add_f32_e32 v130, v100, v102
	v_mul_f32_e32 v100, v97, v97
	v_mul_f32_e32 v102, v95, v95
	v_fmac_f32_e32 v100, v96, v96
	v_fmac_f32_e32 v102, v94, v94
	v_add_f32_e32 v100, v100, v102
	v_add_f32_e32 v131, v101, v100
	s_waitcnt vmcnt(0)
	v_mov_b32_e32 v100, v206
	v_mov_b32_e32 v101, v207
	v_mov_b32_e32 v102, v208
	v_mov_b32_e32 v103, v209
	v_mov_b32_e32 v104, v210
	v_mov_b32_e32 v105, v211
	v_mov_b32_e32 v114, v212
	v_mov_b32_e32 v115, v213
	v_mov_b32_e32 v106, v214
	v_mov_b32_e32 v107, v215
	global_load_dwordx4 v[166:169], v[26:27], off offset:3072
	global_load_dwordx4 v[170:173], v[28:29], off offset:3072
	global_load_dwordx2 v[174:175], v[246:247], off offset:2048
	s_mov_b64 s[98:99], 0x1000
	v_lshl_add_u64 v[212:213], v[26:27], 0, s[98:99]
	global_load_dwordx4 v[176:179], v[212:213], off
	s_mov_b64 s[98:99], 0x1000
	v_lshl_add_u64 v[214:215], v[28:29], 0, s[98:99]
	global_load_dwordx4 v[180:183], v[214:215], off
	global_load_dwordx2 v[184:185], v[238:239], off offset:2048
	global_load_dwordx2 v[186:187], v[240:241], off offset:2048
	global_load_dwordx2 v[188:189], v[242:243], off offset:2048
	global_load_dwordx2 v[190:191], v[244:245], off offset:2048
	global_load_dwordx2 v[192:193], v[244:245], off offset:2560
	global_load_dwordx2 v[194:195], v[242:243], off offset:2560
	global_load_dwordx2 v[196:197], v[240:241], off offset:2560
	global_load_dwordx2 v[198:199], v[238:239], off offset:2560
	global_load_dwordx2 v[200:201], v[246:247], off offset:2560
	global_load_dwordx4 v[202:205], v[212:213], off offset:1024
	global_load_dwordx4 v[206:209], v[214:215], off offset:1024
	global_load_dwordx2 v[210:211], v[246:247], off offset:3072
	v_lshlrev_b32_e32 v108, 16, v106
	v_and_b32_e32 v109, 0xffff0000, v106
	v_lshlrev_b32_e32 v106, 16, v107
	v_and_b32_e32 v107, 0xffff0000, v107
	v_sub_f32_e32 v107, v107, v16
	v_sub_f32_e32 v106, v106, v16
	v_sub_f32_e32 v109, v109, v16
	v_sub_f32_e32 v108, v108, v16
	v_pk_mul_f32 v[126:127], v[16:17], v[108:109] op_sel:[1,0]
	v_pk_mul_f32 v[128:129], v[16:17], v[106:107] op_sel:[1,0]
	s_waitcnt vmcnt(15)
	v_mov_b32_e32 v106, v166
	v_mov_b32_e32 v107, v167
	v_mov_b32_e32 v108, v168
	v_mov_b32_e32 v109, v169
	v_mov_b32_e32 v110, v170
	v_mov_b32_e32 v111, v171
	v_mov_b32_e32 v112, v172
	v_mov_b32_e32 v113, v173
	v_pk_fma_f32 v[108:109], v[108:109], v[128:129], v[112:113]
	v_pk_fma_f32 v[106:107], v[106:107], v[126:127], v[110:111]
	v_lshlrev_b32_e32 v110, 16, v114
	v_and_b32_e32 v111, 0xffff0000, v114
	v_lshlrev_b32_e32 v112, 16, v115
	v_and_b32_e32 v113, 0xffff0000, v115
	v_lshlrev_b32_e32 v114, 16, v104
	v_and_b32_e32 v115, 0xffff0000, v104
	v_lshlrev_b32_e32 v104, 16, v105
	v_and_b32_e32 v105, 0xffff0000, v105
	v_pk_add_f32 v[104:105], v[104:105], v[112:113]
	v_pk_add_f32 v[110:111], v[114:115], v[110:111]
	v_lshlrev_b32_e32 v112, 16, v102
	v_and_b32_e32 v113, 0xffff0000, v102
	v_lshlrev_b32_e32 v102, 16, v103
	v_and_b32_e32 v103, 0xffff0000, v103
	v_lshlrev_b32_e32 v114, 16, v100
	v_and_b32_e32 v115, 0xffff0000, v100
	v_lshlrev_b32_e32 v100, 16, v101
	v_and_b32_e32 v101, 0xffff0000, v101
	v_pk_add_f32 v[100:101], v[100:101], v[102:103]
	v_pk_add_f32 v[102:103], v[114:115], v[112:113]
	v_pk_add_f32 v[100:101], v[100:101], v[104:105]
	v_pk_add_f32 v[102:103], v[102:103], v[110:111]
	v_pk_mul_f32 v[104:105], v[106:107], s[34:35] op_sel_hi:[1,0]
	v_pk_mul_f32 v[106:107], v[108:109], s[34:35] op_sel_hi:[1,0]
	v_pk_fma_f32 v[102:103], v[102:103], s[26:27], v[104:105] op_sel_hi:[1,0,1]
	v_pk_fma_f32 v[100:101], v[100:101], s[26:27], v[106:107] op_sel_hi:[1,0,1]
	v_add_f32_e32 v104, v102, v103
	v_add_f32_e32 v105, v100, v101
	v_add_f32_e32 v104, v104, v105
	v_add_f32_e32 v108, v130, v104
	v_mul_f32_e32 v104, v103, v103
	v_mul_f32_e32 v105, v101, v101
	v_fmac_f32_e32 v104, v102, v102
	v_fmac_f32_e32 v105, v100, v100
	v_add_f32_e32 v104, v104, v105
	v_add_f32_e32 v109, v131, v104
	s_waitcnt vmcnt(14)
	v_mov_b32_e32 v104, v174
	v_mov_b32_e32 v105, v175
	v_lshlrev_b32_e32 v106, 16, v104
	v_and_b32_e32 v104, 0xffff0000, v104
	v_lshlrev_b32_e32 v110, 16, v105
	v_and_b32_e32 v107, 0xffff0000, v105
	v_sub_f32_e32 v105, v104, v16
	v_sub_f32_e32 v104, v106, v16
	v_sub_f32_e32 v107, v107, v16
	v_sub_f32_e32 v106, v110, v16
	v_pk_mul_f32 v[114:115], v[16:17], v[106:107] op_sel:[1,0]
	v_pk_mul_f32 v[126:127], v[16:17], v[104:105] op_sel:[1,0]
	s_waitcnt vmcnt(12)
	v_mov_b32_e32 v104, v176
	v_mov_b32_e32 v105, v177
	v_mov_b32_e32 v106, v178
	v_mov_b32_e32 v107, v179
	v_mov_b32_e32 v110, v180
	v_mov_b32_e32 v111, v181
	v_mov_b32_e32 v112, v182
	v_mov_b32_e32 v113, v183
	v_pk_fma_f32 v[110:111], v[104:105], v[126:127], v[110:111]
	v_pk_fma_f32 v[104:105], v[106:107], v[114:115], v[112:113]
	s_waitcnt vmcnt(11)
	v_mov_b32_e32 v106, v184
	v_mov_b32_e32 v107, v185
	v_lshlrev_b32_e32 v128, 16, v106
	v_and_b32_e32 v129, 0xffff0000, v106
	v_lshlrev_b32_e32 v106, 16, v107
	v_and_b32_e32 v107, 0xffff0000, v107
	s_waitcnt vmcnt(10)
	v_mov_b32_e32 v112, v186
	v_mov_b32_e32 v113, v187
	v_lshlrev_b32_e32 v130, 16, v112
	v_and_b32_e32 v131, 0xffff0000, v112
	v_lshlrev_b32_e32 v112, 16, v113
	v_and_b32_e32 v113, 0xffff0000, v113
	v_pk_add_f32 v[128:129], v[128:129], v[130:131]
	v_pk_add_f32 v[106:107], v[106:107], v[112:113]
	s_waitcnt vmcnt(9)
	v_mov_b32_e32 v114, v188
	v_mov_b32_e32 v115, v189
	v_lshlrev_b32_e32 v112, 16, v114
	v_and_b32_e32 v113, 0xffff0000, v114
	v_lshlrev_b32_e32 v114, 16, v115
	v_and_b32_e32 v115, 0xffff0000, v115
	s_waitcnt vmcnt(8)
	v_mov_b32_e32 v126, v190
	v_mov_b32_e32 v127, v191
	v_lshlrev_b32_e32 v130, 16, v126
	v_and_b32_e32 v131, 0xffff0000, v126
	v_lshlrev_b32_e32 v126, 16, v127
	v_and_b32_e32 v127, 0xffff0000, v127
	v_pk_add_f32 v[112:113], v[112:113], v[130:131]
	v_pk_add_f32 v[114:115], v[114:115], v[126:127]
	v_pk_add_f32 v[112:113], v[128:129], v[112:113]
	v_pk_add_f32 v[106:107], v[106:107], v[114:115]
	v_pk_mul_f32 v[112:113], v[112:113], s[26:27] op_sel_hi:[1,0]
	v_pk_mul_f32 v[106:107], v[106:107], s[26:27] op_sel_hi:[1,0]
	s_nop 0
	v_pk_fma_f32 v[104:105], v[104:105], s[34:35], v[106:107] op_sel_hi:[1,0,1]
	v_pk_fma_f32 v[106:107], v[110:111], s[34:35], v[112:113] op_sel_hi:[1,0,1]
	v_add_f32_e32 v111, v104, v105
	v_add_f32_e32 v110, v106, v107
	v_add_f32_e32 v110, v110, v111
	v_add_f32_e32 v138, v108, v110
	v_mul_f32_e32 v108, v107, v107
	v_mul_f32_e32 v110, v105, v105
	v_fmac_f32_e32 v108, v106, v106
	v_fmac_f32_e32 v110, v104, v104
	v_add_f32_e32 v108, v108, v110
	v_add_f32_e32 v139, v109, v108
	s_waitcnt vmcnt(3)
	v_mov_b32_e32 v108, v192
	v_mov_b32_e32 v109, v193
	v_mov_b32_e32 v110, v194
	v_mov_b32_e32 v111, v195
	v_mov_b32_e32 v112, v196
	v_mov_b32_e32 v113, v197
	v_mov_b32_e32 v114, v198
	v_mov_b32_e32 v115, v199
	v_mov_b32_e32 v126, v200
	v_mov_b32_e32 v127, v201
	v_lshlrev_b32_e32 v128, 16, v126
	v_and_b32_e32 v129, 0xffff0000, v126
	v_lshlrev_b32_e32 v126, 16, v127
	v_and_b32_e32 v127, 0xffff0000, v127
	v_sub_f32_e32 v127, v127, v16
	v_sub_f32_e32 v126, v126, v16
	v_sub_f32_e32 v129, v129, v16
	v_sub_f32_e32 v128, v128, v16
	v_pk_mul_f32 v[134:135], v[16:17], v[128:129] op_sel:[1,0]
	v_pk_mul_f32 v[136:137], v[16:17], v[126:127] op_sel:[1,0]
	s_waitcnt vmcnt(1)
	v_mov_b32_e32 v126, v202
	v_mov_b32_e32 v127, v203
	v_mov_b32_e32 v128, v204
	v_mov_b32_e32 v129, v205
	v_mov_b32_e32 v130, v206
	v_mov_b32_e32 v131, v207
	v_mov_b32_e32 v132, v208
	v_mov_b32_e32 v133, v209
	v_pk_fma_f32 v[128:129], v[128:129], v[136:137], v[132:133]
	v_pk_fma_f32 v[126:127], v[126:127], v[134:135], v[130:131]
	v_lshlrev_b32_e32 v130, 16, v114
	v_and_b32_e32 v131, 0xffff0000, v114
	v_lshlrev_b32_e32 v114, 16, v115
	v_and_b32_e32 v115, 0xffff0000, v115
	v_lshlrev_b32_e32 v132, 16, v112
	v_and_b32_e32 v133, 0xffff0000, v112
	v_lshlrev_b32_e32 v112, 16, v113
	v_and_b32_e32 v113, 0xffff0000, v113
	v_pk_add_f32 v[112:113], v[112:113], v[114:115]
	v_pk_add_f32 v[114:115], v[132:133], v[130:131]
	v_lshlrev_b32_e32 v130, 16, v110
	v_and_b32_e32 v131, 0xffff0000, v110
	v_lshlrev_b32_e32 v110, 16, v111
	v_and_b32_e32 v111, 0xffff0000, v111
	v_lshlrev_b32_e32 v132, 16, v108
	v_and_b32_e32 v133, 0xffff0000, v108
	v_lshlrev_b32_e32 v108, 16, v109
	v_and_b32_e32 v109, 0xffff0000, v109
	v_pk_add_f32 v[108:109], v[108:109], v[110:111]
	v_pk_add_f32 v[110:111], v[132:133], v[130:131]
	v_pk_add_f32 v[108:109], v[108:109], v[112:113]
	v_pk_add_f32 v[110:111], v[110:111], v[114:115]
	v_pk_mul_f32 v[112:113], v[126:127], s[34:35] op_sel_hi:[1,0]
	v_pk_mul_f32 v[114:115], v[128:129], s[34:35] op_sel_hi:[1,0]
	v_pk_fma_f32 v[110:111], v[110:111], s[26:27], v[112:113] op_sel_hi:[1,0,1]
	v_pk_fma_f32 v[108:109], v[108:109], s[26:27], v[114:115] op_sel_hi:[1,0,1]
	v_add_f32_e32 v112, v110, v111
	v_add_f32_e32 v113, v108, v109
	v_add_f32_e32 v112, v112, v113
	v_add_f32_e32 v126, v138, v112
	v_mul_f32_e32 v112, v111, v111
	v_mul_f32_e32 v113, v109, v109
	v_fmac_f32_e32 v112, v110, v110
	v_fmac_f32_e32 v113, v108, v108
	v_add_f32_e32 v112, v112, v113
	v_add_f32_e32 v127, v139, v112
	s_waitcnt vmcnt(0)
	v_mov_b32_e32 v112, v210
	v_mov_b32_e32 v113, v211
	s_mov_b64 s[98:99], 0x1000
	v_lshl_add_u64 v[218:219], v[26:27], 0, s[98:99]
	global_load_dwordx4 v[166:169], v[218:219], off offset:2048
	s_mov_b64 s[98:99], 0x1000
	v_lshl_add_u64 v[220:221], v[28:29], 0, s[98:99]
	global_load_dwordx4 v[170:173], v[220:221], off offset:2048
	global_load_dwordx2 v[174:175], v[238:239], off offset:3072
	global_load_dwordx2 v[176:177], v[240:241], off offset:3072
	global_load_dwordx2 v[178:179], v[242:243], off offset:3072
	global_load_dwordx2 v[180:181], v[244:245], off offset:3072
	global_load_dwordx2 v[182:183], v[244:245], off offset:3584
	global_load_dwordx2 v[184:185], v[242:243], off offset:3584
	global_load_dwordx2 v[186:187], v[240:241], off offset:3584
	global_load_dwordx2 v[188:189], v[238:239], off offset:3584
	global_load_dwordx2 v[190:191], v[246:247], off offset:3584
	global_load_dwordx4 v[192:195], v[218:219], off offset:3072
	global_load_dwordx4 v[196:199], v[220:221], off offset:3072
	s_mov_b64 s[98:99], 0x1000
	v_lshl_add_u64 v[222:223], v[246:247], 0, s[98:99]
	global_load_dwordx2 v[200:201], v[222:223], off
	s_mov_b64 s[98:99], 0x2000
	v_lshl_add_u64 v[224:225], v[26:27], 0, s[98:99]
	global_load_dwordx4 v[202:205], v[224:225], off
	s_mov_b64 s[98:99], 0x2000
	v_lshl_add_u64 v[226:227], v[28:29], 0, s[98:99]
	global_load_dwordx4 v[206:209], v[226:227], off
	s_mov_b64 s[98:99], 0x1000
	v_lshl_add_u64 v[228:229], v[238:239], 0, s[98:99]
	global_load_dwordx2 v[210:211], v[228:229], off
	s_mov_b64 s[98:99], 0x1000
	v_lshl_add_u64 v[230:231], v[240:241], 0, s[98:99]
	global_load_dwordx2 v[212:213], v[230:231], off
	s_mov_b64 s[98:99], 0x1000
	v_lshl_add_u64 v[232:233], v[242:243], 0, s[98:99]
	global_load_dwordx2 v[214:215], v[232:233], off
	s_mov_b64 s[98:99], 0x1000
	v_lshl_add_u64 v[234:235], v[244:245], 0, s[98:99]
	global_load_dwordx2 v[216:217], v[234:235], off
	v_lshlrev_b32_e32 v114, 16, v112
	v_and_b32_e32 v112, 0xffff0000, v112
	v_lshlrev_b32_e32 v128, 16, v113
	v_and_b32_e32 v115, 0xffff0000, v113
	v_sub_f32_e32 v113, v112, v16
	v_sub_f32_e32 v112, v114, v16
	v_sub_f32_e32 v115, v115, v16
	v_sub_f32_e32 v114, v128, v16
	v_pk_mul_f32 v[132:133], v[16:17], v[114:115] op_sel:[1,0]
	v_pk_mul_f32 v[134:135], v[16:17], v[112:113] op_sel:[1,0]
	s_waitcnt vmcnt(18)
	v_mov_b32_e32 v112, v166
	v_mov_b32_e32 v113, v167
	v_mov_b32_e32 v114, v168
	v_mov_b32_e32 v115, v169
	v_mov_b32_e32 v128, v170
	v_mov_b32_e32 v129, v171
	v_mov_b32_e32 v130, v172
	v_mov_b32_e32 v131, v173
	v_pk_fma_f32 v[128:129], v[112:113], v[134:135], v[128:129]
	v_pk_fma_f32 v[112:113], v[114:115], v[132:133], v[130:131]
	s_nop 0
	s_nop 0
	s_nop 0
	s_nop 0
	s_nop 0
	s_waitcnt vmcnt(17)
	v_mov_b32_e32 v114, v174
	v_mov_b32_e32 v115, v175
	v_lshlrev_b32_e32 v136, 16, v114
	v_and_b32_e32 v137, 0xffff0000, v114
	v_lshlrev_b32_e32 v114, 16, v115
	v_and_b32_e32 v115, 0xffff0000, v115
	s_waitcnt vmcnt(16)
	v_mov_b32_e32 v130, v176
	v_mov_b32_e32 v131, v177
	v_lshlrev_b32_e32 v138, 16, v130
	v_and_b32_e32 v139, 0xffff0000, v130
	v_lshlrev_b32_e32 v130, 16, v131
	v_and_b32_e32 v131, 0xffff0000, v131
	v_pk_add_f32 v[136:137], v[136:137], v[138:139]
	v_pk_add_f32 v[114:115], v[114:115], v[130:131]
	s_waitcnt vmcnt(15)
	v_mov_b32_e32 v132, v178
	v_mov_b32_e32 v133, v179
	v_lshlrev_b32_e32 v130, 16, v132
	v_and_b32_e32 v131, 0xffff0000, v132
	v_lshlrev_b32_e32 v132, 16, v133
	v_and_b32_e32 v133, 0xffff0000, v133
	s_waitcnt vmcnt(14)
	v_mov_b32_e32 v134, v180
	v_mov_b32_e32 v135, v181
	v_lshlrev_b32_e32 v138, 16, v134
	v_and_b32_e32 v139, 0xffff0000, v134
	v_lshlrev_b32_e32 v134, 16, v135
	v_and_b32_e32 v135, 0xffff0000, v135
	v_pk_add_f32 v[130:131], v[130:131], v[138:139]
	v_pk_add_f32 v[132:133], v[132:133], v[134:135]
	v_pk_add_f32 v[130:131], v[136:137], v[130:131]
	v_pk_add_f32 v[114:115], v[114:115], v[132:133]
	v_pk_mul_f32 v[130:131], v[130:131], s[26:27] op_sel_hi:[1,0]
	v_pk_mul_f32 v[114:115], v[114:115], s[26:27] op_sel_hi:[1,0]
	s_nop 0
	v_pk_fma_f32 v[112:113], v[112:113], s[34:35], v[114:115] op_sel_hi:[1,0,1]
	v_pk_fma_f32 v[114:115], v[128:129], s[34:35], v[130:131] op_sel_hi:[1,0,1]
	v_add_f32_e32 v129, v112, v113
	v_add_f32_e32 v128, v114, v115
	v_add_f32_e32 v128, v128, v129
	v_add_f32_e32 v136, v126, v128
	v_mul_f32_e32 v126, v115, v115
	v_mul_f32_e32 v128, v113, v113
	v_fmac_f32_e32 v126, v114, v114
	v_fmac_f32_e32 v128, v112, v112
	v_add_f32_e32 v126, v126, v128
	v_add_f32_e32 v137, v127, v126
	s_waitcnt vmcnt(9)
	v_mov_b32_e32 v124, v182
	v_mov_b32_e32 v125, v183
	v_mov_b32_e32 v122, v184
	v_mov_b32_e32 v123, v185
	v_mov_b32_e32 v120, v186
	v_mov_b32_e32 v121, v187
	v_mov_b32_e32 v118, v188
	v_mov_b32_e32 v119, v189
	v_mov_b32_e32 v116, v190
	v_mov_b32_e32 v117, v191
	v_lshlrev_b32_e32 v126, 16, v116
	v_and_b32_e32 v127, 0xffff0000, v116
	v_sub_f32_e32 v127, v127, v16
	v_sub_f32_e32 v126, v126, v16
	v_pk_mul_f32 v[134:135], v[16:17], v[126:127] op_sel:[1,0]
	v_lshlrev_b32_e32 v116, 16, v117
	v_and_b32_e32 v117, 0xffff0000, v117
	v_sub_f32_e32 v117, v117, v16
	v_sub_f32_e32 v116, v116, v16
	v_pk_mul_f32 v[116:117], v[16:17], v[116:117] op_sel:[1,0]
	s_waitcnt vmcnt(7)
	v_mov_b32_e32 v126, v192
	v_mov_b32_e32 v127, v193
	v_mov_b32_e32 v128, v194
	v_mov_b32_e32 v129, v195
	v_mov_b32_e32 v130, v196
	v_mov_b32_e32 v131, v197
	v_mov_b32_e32 v132, v198
	v_mov_b32_e32 v133, v199
	v_pk_fma_f32 v[126:127], v[126:127], v[134:135], v[130:131]
	v_pk_fma_f32 v[116:117], v[128:129], v[116:117], v[132:133]
	v_lshlrev_b32_e32 v128, 16, v118
	v_and_b32_e32 v129, 0xffff0000, v118
	v_lshlrev_b32_e32 v118, 16, v119
	v_and_b32_e32 v119, 0xffff0000, v119
	v_lshlrev_b32_e32 v130, 16, v120
	v_and_b32_e32 v131, 0xffff0000, v120
	v_lshlrev_b32_e32 v120, 16, v121
	v_and_b32_e32 v121, 0xffff0000, v121
	v_pk_add_f32 v[118:119], v[120:121], v[118:119]
	v_pk_add_f32 v[120:121], v[130:131], v[128:129]
	v_lshlrev_b32_e32 v128, 16, v122
	v_and_b32_e32 v129, 0xffff0000, v122
	v_lshlrev_b32_e32 v122, 16, v123
	v_and_b32_e32 v123, 0xffff0000, v123
	v_lshlrev_b32_e32 v130, 16, v124
	v_and_b32_e32 v131, 0xffff0000, v124
	v_lshlrev_b32_e32 v124, 16, v125
	v_and_b32_e32 v125, 0xffff0000, v125
	v_pk_add_f32 v[122:123], v[124:125], v[122:123]
	v_pk_add_f32 v[124:125], v[130:131], v[128:129]
	v_pk_add_f32 v[118:119], v[122:123], v[118:119]
	v_pk_add_f32 v[120:121], v[124:125], v[120:121]
	v_pk_mul_f32 v[122:123], v[126:127], s[34:35] op_sel_hi:[1,0]
	v_pk_mul_f32 v[116:117], v[116:117], s[34:35] op_sel_hi:[1,0]
	v_add_co_u32_e32 v132, vcc, s8, v84
	v_pk_fma_f32 v[116:117], v[118:119], s[26:27], v[116:117] op_sel_hi:[1,0,1]
	v_pk_fma_f32 v[118:119], v[120:121], s[26:27], v[122:123] op_sel_hi:[1,0,1]
	v_add_f32_e32 v121, v116, v117
	v_add_f32_e32 v120, v118, v119
	v_add_f32_e32 v120, v120, v121
	v_add_f32_e32 v124, v136, v120
	v_mul_f32_e32 v120, v119, v119
	v_mul_f32_e32 v121, v117, v117
	v_fmac_f32_e32 v120, v118, v118
	v_fmac_f32_e32 v121, v116, v116
	v_add_f32_e32 v120, v120, v121
	v_addc_co_u32_e32 v133, vcc, 0, v85, vcc
	v_add_f32_e32 v125, v137, v120
	s_waitcnt vmcnt(6)
	v_mov_b32_e32 v120, v200
	v_mov_b32_e32 v121, v201
	v_lshlrev_b32_e32 v122, 16, v120
	v_and_b32_e32 v120, 0xffff0000, v120
	v_lshlrev_b32_e32 v126, 16, v121
	v_and_b32_e32 v123, 0xffff0000, v121
	v_sub_f32_e32 v121, v120, v16
	v_sub_f32_e32 v120, v122, v16
	v_sub_f32_e32 v123, v123, v16
	v_sub_f32_e32 v122, v126, v16
	v_pk_mul_f32 v[130:131], v[16:17], v[122:123] op_sel:[1,0]
	v_pk_mul_f32 v[134:135], v[16:17], v[120:121] op_sel:[1,0]
	s_waitcnt vmcnt(4)
	v_mov_b32_e32 v120, v202
	v_mov_b32_e32 v121, v203
	v_mov_b32_e32 v122, v204
	v_mov_b32_e32 v123, v205
	v_mov_b32_e32 v126, v206
	v_mov_b32_e32 v127, v207
	v_mov_b32_e32 v128, v208
	v_mov_b32_e32 v129, v209
	v_pk_fma_f32 v[126:127], v[120:121], v[134:135], v[126:127]
	v_pk_fma_f32 v[120:121], v[122:123], v[130:131], v[128:129]
	s_waitcnt vmcnt(3)
	v_mov_b32_e32 v122, v210
	v_mov_b32_e32 v123, v211
	v_lshlrev_b32_e32 v136, 16, v122
	v_and_b32_e32 v137, 0xffff0000, v122
	v_lshlrev_b32_e32 v122, 16, v123
	v_and_b32_e32 v123, 0xffff0000, v123
	s_waitcnt vmcnt(2)
	v_mov_b32_e32 v128, v212
	v_mov_b32_e32 v129, v213
	v_lshlrev_b32_e32 v138, 16, v128
	v_and_b32_e32 v139, 0xffff0000, v128
	v_lshlrev_b32_e32 v128, 16, v129
	v_and_b32_e32 v129, 0xffff0000, v129
	v_pk_add_f32 v[136:137], v[136:137], v[138:139]
	v_pk_add_f32 v[122:123], v[122:123], v[128:129]
	s_waitcnt vmcnt(1)
	v_mov_b32_e32 v130, v214
	v_mov_b32_e32 v131, v215
	v_lshlrev_b32_e32 v128, 16, v130
	v_and_b32_e32 v129, 0xffff0000, v130
	v_lshlrev_b32_e32 v130, 16, v131
	v_and_b32_e32 v131, 0xffff0000, v131
	s_waitcnt vmcnt(0)
	v_mov_b32_e32 v134, v216
	v_mov_b32_e32 v135, v217
	s_mov_b64 s[98:99], 0x1000
	v_lshl_add_u64 v[212:213], v[244:245], 0, s[98:99]
	global_load_dwordx2 v[166:167], v[212:213], off offset:512
	s_mov_b64 s[98:99], 0x1000
	v_lshl_add_u64 v[214:215], v[242:243], 0, s[98:99]
	global_load_dwordx2 v[168:169], v[214:215], off offset:512
	s_mov_b64 s[98:99], 0x1000
	v_lshl_add_u64 v[216:217], v[240:241], 0, s[98:99]
	global_load_dwordx2 v[170:171], v[216:217], off offset:512
	s_mov_b64 s[98:99], 0x1000
	v_lshl_add_u64 v[218:219], v[238:239], 0, s[98:99]
	global_load_dwordx2 v[172:173], v[218:219], off offset:512
	s_mov_b64 s[98:99], 0x1000
	v_lshl_add_u64 v[220:221], v[246:247], 0, s[98:99]
	global_load_dwordx2 v[174:175], v[220:221], off offset:512
	s_mov_b64 s[98:99], 0x2000
	v_lshl_add_u64 v[222:223], v[26:27], 0, s[98:99]
	global_load_dwordx4 v[176:179], v[222:223], off offset:1024
	s_mov_b64 s[98:99], 0x2000
	v_lshl_add_u64 v[224:225], v[28:29], 0, s[98:99]
	global_load_dwordx4 v[180:183], v[224:225], off offset:1024
	global_load_dwordx2 v[184:185], v[220:221], off offset:1024
	global_load_dwordx4 v[186:189], v[222:223], off offset:2048
	global_load_dwordx4 v[190:193], v[224:225], off offset:2048
	global_load_dwordx2 v[194:195], v[218:219], off offset:1024
	global_load_dwordx2 v[196:197], v[216:217], off offset:1024
	global_load_dwordx2 v[198:199], v[214:215], off offset:1024
	global_load_dwordx2 v[200:201], v[212:213], off offset:1024
	global_load_dwordx2 v[202:203], v[212:213], off offset:1536
	global_load_dwordx2 v[204:205], v[214:215], off offset:1536
	global_load_dwordx2 v[206:207], v[216:217], off offset:1536
	global_load_dwordx2 v[208:209], v[218:219], off offset:1536
	global_load_dwordx2 v[210:211], v[220:221], off offset:1536
	v_lshlrev_b32_e32 v138, 16, v134
	v_and_b32_e32 v139, 0xffff0000, v134
	v_lshlrev_b32_e32 v134, 16, v135
	v_and_b32_e32 v135, 0xffff0000, v135
	v_pk_add_f32 v[128:129], v[128:129], v[138:139]
	v_pk_add_f32 v[130:131], v[130:131], v[134:135]
	v_pk_add_f32 v[128:129], v[136:137], v[128:129]
	v_pk_add_f32 v[122:123], v[122:123], v[130:131]
	v_pk_mul_f32 v[128:129], v[128:129], s[26:27] op_sel_hi:[1,0]
	v_pk_mul_f32 v[122:123], v[122:123], s[26:27] op_sel_hi:[1,0]
	s_nop 0
	v_pk_fma_f32 v[120:121], v[120:121], s[34:35], v[122:123] op_sel_hi:[1,0,1]
	v_pk_fma_f32 v[122:123], v[126:127], s[34:35], v[128:129] op_sel_hi:[1,0,1]
	v_add_f32_e32 v127, v120, v121
	v_add_f32_e32 v126, v122, v123
	v_add_f32_e32 v126, v126, v127
	v_add_f32_e32 v146, v124, v126
	v_mul_f32_e32 v124, v123, v123
	v_mul_f32_e32 v126, v121, v121
	v_fmac_f32_e32 v124, v122, v122
	v_fmac_f32_e32 v126, v120, v120
	v_add_f32_e32 v124, v124, v126
	v_add_f32_e32 v147, v125, v124
	s_waitcnt vmcnt(14)
	v_mov_b32_e32 v124, v166
	v_mov_b32_e32 v125, v167
	v_mov_b32_e32 v126, v168
	v_mov_b32_e32 v127, v169
	v_mov_b32_e32 v128, v170
	v_mov_b32_e32 v129, v171
	v_mov_b32_e32 v130, v172
	v_mov_b32_e32 v131, v173
	v_mov_b32_e32 v134, v174
	v_mov_b32_e32 v135, v175
	v_lshlrev_b32_e32 v136, 16, v134
	v_and_b32_e32 v137, 0xffff0000, v134
	v_lshlrev_b32_e32 v134, 16, v135
	v_and_b32_e32 v135, 0xffff0000, v135
	v_sub_f32_e32 v135, v135, v16
	v_sub_f32_e32 v134, v134, v16
	v_sub_f32_e32 v137, v137, v16
	v_sub_f32_e32 v136, v136, v16
	v_pk_mul_f32 v[142:143], v[16:17], v[136:137] op_sel:[1,0]
	v_pk_mul_f32 v[144:145], v[16:17], v[134:135] op_sel:[1,0]
	s_waitcnt vmcnt(12)
	v_mov_b32_e32 v134, v176
	v_mov_b32_e32 v135, v177
	v_mov_b32_e32 v136, v178
	v_mov_b32_e32 v137, v179
	v_mov_b32_e32 v138, v180
	v_mov_b32_e32 v139, v181
	v_mov_b32_e32 v140, v182
	v_mov_b32_e32 v141, v183
	v_pk_fma_f32 v[136:137], v[136:137], v[144:145], v[140:141]
	v_pk_fma_f32 v[134:135], v[134:135], v[142:143], v[138:139]
	v_lshlrev_b32_e32 v138, 16, v130
	v_and_b32_e32 v139, 0xffff0000, v130
	v_lshlrev_b32_e32 v130, 16, v131
	v_and_b32_e32 v131, 0xffff0000, v131
	v_lshlrev_b32_e32 v140, 16, v128
	v_and_b32_e32 v141, 0xffff0000, v128
	v_lshlrev_b32_e32 v128, 16, v129
	v_and_b32_e32 v129, 0xffff0000, v129
	v_pk_add_f32 v[128:129], v[128:129], v[130:131]
	v_pk_add_f32 v[130:131], v[140:141], v[138:139]
	v_lshlrev_b32_e32 v138, 16, v126
	v_and_b32_e32 v139, 0xffff0000, v126
	v_lshlrev_b32_e32 v126, 16, v127
	v_and_b32_e32 v127, 0xffff0000, v127
	v_lshlrev_b32_e32 v140, 16, v124
	v_and_b32_e32 v141, 0xffff0000, v124
	v_lshlrev_b32_e32 v124, 16, v125
	v_and_b32_e32 v125, 0xffff0000, v125
	v_pk_add_f32 v[124:125], v[124:125], v[126:127]
	v_pk_add_f32 v[126:127], v[140:141], v[138:139]
	v_pk_add_f32 v[124:125], v[124:125], v[128:129]
	v_pk_add_f32 v[126:127], v[126:127], v[130:131]
	v_pk_mul_f32 v[128:129], v[134:135], s[34:35] op_sel_hi:[1,0]
	v_pk_mul_f32 v[130:131], v[136:137], s[34:35] op_sel_hi:[1,0]
	v_pk_fma_f32 v[126:127], v[126:127], s[26:27], v[128:129] op_sel_hi:[1,0,1]
	v_pk_fma_f32 v[124:125], v[124:125], s[26:27], v[130:131] op_sel_hi:[1,0,1]
	v_add_f32_e32 v128, v126, v127
	v_add_f32_e32 v129, v124, v125
	v_add_f32_e32 v128, v128, v129
	v_add_f32_e32 v134, v146, v128
	v_mul_f32_e32 v128, v127, v127
	v_mul_f32_e32 v129, v125, v125
	v_fmac_f32_e32 v128, v126, v126
	v_fmac_f32_e32 v129, v124, v124
	v_add_f32_e32 v128, v128, v129
	v_add_f32_e32 v135, v147, v128
	s_waitcnt vmcnt(11)
	v_mov_b32_e32 v128, v184
	v_mov_b32_e32 v129, v185
	v_lshlrev_b32_e32 v130, 16, v128
	v_and_b32_e32 v128, 0xffff0000, v128
	v_lshlrev_b32_e32 v136, 16, v129
	v_and_b32_e32 v131, 0xffff0000, v129
	v_sub_f32_e32 v129, v128, v16
	v_sub_f32_e32 v128, v130, v16
	v_sub_f32_e32 v131, v131, v16
	v_sub_f32_e32 v130, v136, v16
	v_pk_mul_f32 v[140:141], v[16:17], v[130:131] op_sel:[1,0]
	v_pk_mul_f32 v[142:143], v[16:17], v[128:129] op_sel:[1,0]
	s_waitcnt vmcnt(9)
	v_mov_b32_e32 v128, v186
	v_mov_b32_e32 v129, v187
	v_mov_b32_e32 v130, v188
	v_mov_b32_e32 v131, v189
	v_mov_b32_e32 v136, v190
	v_mov_b32_e32 v137, v191
	v_mov_b32_e32 v138, v192
	v_mov_b32_e32 v139, v193
	v_pk_fma_f32 v[136:137], v[128:129], v[142:143], v[136:137]
	v_pk_fma_f32 v[128:129], v[130:131], v[140:141], v[138:139]
	s_waitcnt vmcnt(8)
	v_mov_b32_e32 v130, v194
	v_mov_b32_e32 v131, v195
	v_lshlrev_b32_e32 v144, 16, v130
	v_and_b32_e32 v145, 0xffff0000, v130
	v_lshlrev_b32_e32 v130, 16, v131
	v_and_b32_e32 v131, 0xffff0000, v131
	s_waitcnt vmcnt(7)
	v_mov_b32_e32 v138, v196
	v_mov_b32_e32 v139, v197
	v_lshlrev_b32_e32 v146, 16, v138
	v_and_b32_e32 v147, 0xffff0000, v138
	v_lshlrev_b32_e32 v138, 16, v139
	v_and_b32_e32 v139, 0xffff0000, v139
	v_pk_add_f32 v[144:145], v[144:145], v[146:147]
	v_pk_add_f32 v[130:131], v[130:131], v[138:139]
	s_waitcnt vmcnt(6)
	v_mov_b32_e32 v140, v198
	v_mov_b32_e32 v141, v199
	v_lshlrev_b32_e32 v138, 16, v140
	v_and_b32_e32 v139, 0xffff0000, v140
	v_lshlrev_b32_e32 v140, 16, v141
	v_and_b32_e32 v141, 0xffff0000, v141
	s_waitcnt vmcnt(5)
	v_mov_b32_e32 v142, v200
	v_mov_b32_e32 v143, v201
	v_lshlrev_b32_e32 v146, 16, v142
	v_and_b32_e32 v147, 0xffff0000, v142
	v_lshlrev_b32_e32 v142, 16, v143
	v_and_b32_e32 v143, 0xffff0000, v143
	v_pk_add_f32 v[138:139], v[138:139], v[146:147]
	v_pk_add_f32 v[140:141], v[140:141], v[142:143]
	v_pk_add_f32 v[138:139], v[144:145], v[138:139]
	v_pk_add_f32 v[130:131], v[130:131], v[140:141]
	v_pk_mul_f32 v[138:139], v[138:139], s[26:27] op_sel_hi:[1,0]
	v_pk_mul_f32 v[130:131], v[130:131], s[26:27] op_sel_hi:[1,0]
	s_nop 0
	v_pk_fma_f32 v[128:129], v[128:129], s[34:35], v[130:131] op_sel_hi:[1,0,1]
	v_pk_fma_f32 v[130:131], v[136:137], s[34:35], v[138:139] op_sel_hi:[1,0,1]
	v_add_f32_e32 v137, v128, v129
	v_add_f32_e32 v136, v130, v131
	v_add_f32_e32 v136, v136, v137
	v_add_f32_e32 v154, v134, v136
	v_mul_f32_e32 v134, v131, v131
	v_mul_f32_e32 v136, v129, v129
	v_fmac_f32_e32 v134, v130, v130
	v_fmac_f32_e32 v136, v128, v128
	v_add_f32_e32 v134, v134, v136
	v_add_f32_e32 v155, v135, v134
	s_waitcnt vmcnt(0)
	v_mov_b32_e32 v134, v202
	v_mov_b32_e32 v135, v203
	v_mov_b32_e32 v136, v204
	v_mov_b32_e32 v137, v205
	v_mov_b32_e32 v138, v206
	v_mov_b32_e32 v139, v207
	v_mov_b32_e32 v148, v208
	v_mov_b32_e32 v149, v209
	v_mov_b32_e32 v140, v210
	v_mov_b32_e32 v141, v211
	s_mov_b64 s[98:99], 0x2000
	v_lshl_add_u64 v[212:213], v[26:27], 0, s[98:99]
	global_load_dwordx4 v[166:169], v[212:213], off offset:3072
	s_mov_b64 s[98:99], 0x2000
	v_lshl_add_u64 v[214:215], v[28:29], 0, s[98:99]
	global_load_dwordx4 v[170:173], v[214:215], off offset:3072
	s_mov_b64 s[98:99], 0x1000
	v_lshl_add_u64 v[216:217], v[246:247], 0, s[98:99]
	global_load_dwordx2 v[174:175], v[216:217], off offset:2048
	s_mov_b64 s[98:99], 0x3000
	v_lshl_add_u64 v[218:219], v[26:27], 0, s[98:99]
	global_load_dwordx4 v[176:179], v[218:219], off
	s_mov_b64 s[98:99], 0x3000
	v_lshl_add_u64 v[220:221], v[28:29], 0, s[98:99]
	global_load_dwordx4 v[180:183], v[220:221], off
	s_mov_b64 s[98:99], 0x1000
	v_lshl_add_u64 v[222:223], v[238:239], 0, s[98:99]
	global_load_dwordx2 v[184:185], v[222:223], off offset:2048
	s_mov_b64 s[98:99], 0x1000
	v_lshl_add_u64 v[224:225], v[240:241], 0, s[98:99]
	global_load_dwordx2 v[186:187], v[224:225], off offset:2048
	s_mov_b64 s[98:99], 0x1000
	v_lshl_add_u64 v[226:227], v[242:243], 0, s[98:99]
	global_load_dwordx2 v[188:189], v[226:227], off offset:2048
	s_mov_b64 s[98:99], 0x1000
	v_lshl_add_u64 v[228:229], v[244:245], 0, s[98:99]
	global_load_dwordx2 v[190:191], v[228:229], off offset:2048
	global_load_dwordx2 v[192:193], v[228:229], off offset:2560
	global_load_dwordx2 v[194:195], v[226:227], off offset:2560
	global_load_dwordx2 v[196:197], v[224:225], off offset:2560
	global_load_dwordx2 v[198:199], v[222:223], off offset:2560
	global_load_dwordx2 v[200:201], v[216:217], off offset:2560
	global_load_dwordx4 v[202:205], v[218:219], off offset:1024
	global_load_dwordx4 v[206:209], v[220:221], off offset:1024
	global_load_dwordx2 v[210:211], v[216:217], off offset:3072
	v_lshlrev_b32_e32 v142, 16, v140
	v_and_b32_e32 v143, 0xffff0000, v140
	v_lshlrev_b32_e32 v140, 16, v141
	v_and_b32_e32 v141, 0xffff0000, v141
	v_sub_f32_e32 v141, v141, v16
	v_sub_f32_e32 v140, v140, v16
	v_sub_f32_e32 v143, v143, v16
	v_sub_f32_e32 v142, v142, v16
	v_pk_mul_f32 v[150:151], v[16:17], v[142:143] op_sel:[1,0]
	v_pk_mul_f32 v[152:153], v[16:17], v[140:141] op_sel:[1,0]
	s_waitcnt vmcnt(15)
	v_mov_b32_e32 v140, v166
	v_mov_b32_e32 v141, v167
	v_mov_b32_e32 v142, v168
	v_mov_b32_e32 v143, v169
	v_mov_b32_e32 v144, v170
	v_mov_b32_e32 v145, v171
	v_mov_b32_e32 v146, v172
	v_mov_b32_e32 v147, v173
	v_pk_fma_f32 v[142:143], v[142:143], v[152:153], v[146:147]
	v_pk_fma_f32 v[140:141], v[140:141], v[150:151], v[144:145]
	v_lshlrev_b32_e32 v144, 16, v148
	v_and_b32_e32 v145, 0xffff0000, v148
	v_lshlrev_b32_e32 v146, 16, v149
	v_and_b32_e32 v147, 0xffff0000, v149
	v_lshlrev_b32_e32 v148, 16, v138
	v_and_b32_e32 v149, 0xffff0000, v138
	v_lshlrev_b32_e32 v138, 16, v139
	v_and_b32_e32 v139, 0xffff0000, v139
	v_pk_add_f32 v[138:139], v[138:139], v[146:147]
	v_pk_add_f32 v[144:145], v[148:149], v[144:145]
	v_lshlrev_b32_e32 v146, 16, v136
	v_and_b32_e32 v147, 0xffff0000, v136
	v_lshlrev_b32_e32 v136, 16, v137
	v_and_b32_e32 v137, 0xffff0000, v137
	v_lshlrev_b32_e32 v148, 16, v134
	v_and_b32_e32 v149, 0xffff0000, v134
	v_lshlrev_b32_e32 v134, 16, v135
	v_and_b32_e32 v135, 0xffff0000, v135
	v_pk_add_f32 v[134:135], v[134:135], v[136:137]
	v_pk_add_f32 v[136:137], v[148:149], v[146:147]
	v_pk_add_f32 v[134:135], v[134:135], v[138:139]
	v_pk_add_f32 v[136:137], v[136:137], v[144:145]
	v_pk_mul_f32 v[138:139], v[140:141], s[34:35] op_sel_hi:[1,0]
	v_pk_mul_f32 v[140:141], v[142:143], s[34:35] op_sel_hi:[1,0]
	v_pk_fma_f32 v[136:137], v[136:137], s[26:27], v[138:139] op_sel_hi:[1,0,1]
	v_pk_fma_f32 v[134:135], v[134:135], s[26:27], v[140:141] op_sel_hi:[1,0,1]
	v_add_f32_e32 v138, v136, v137
	v_add_f32_e32 v139, v134, v135
	v_add_f32_e32 v138, v138, v139
	v_add_f32_e32 v142, v154, v138
	v_mul_f32_e32 v138, v137, v137
	v_mul_f32_e32 v139, v135, v135
	v_fmac_f32_e32 v138, v136, v136
	v_fmac_f32_e32 v139, v134, v134
	v_add_f32_e32 v138, v138, v139
	v_add_f32_e32 v143, v155, v138
	s_waitcnt vmcnt(14)
	v_mov_b32_e32 v138, v174
	v_mov_b32_e32 v139, v175
	v_lshlrev_b32_e32 v140, 16, v138
	v_and_b32_e32 v138, 0xffff0000, v138
	v_lshlrev_b32_e32 v144, 16, v139
	v_and_b32_e32 v141, 0xffff0000, v139
	v_sub_f32_e32 v139, v138, v16
	v_sub_f32_e32 v138, v140, v16
	v_sub_f32_e32 v141, v141, v16
	v_sub_f32_e32 v140, v144, v16
	v_pk_mul_f32 v[148:149], v[16:17], v[140:141] op_sel:[1,0]
	v_pk_mul_f32 v[150:151], v[16:17], v[138:139] op_sel:[1,0]
	s_waitcnt vmcnt(12)
	v_mov_b32_e32 v138, v176
	v_mov_b32_e32 v139, v177
	v_mov_b32_e32 v140, v178
	v_mov_b32_e32 v141, v179
	v_mov_b32_e32 v144, v180
	v_mov_b32_e32 v145, v181
	v_mov_b32_e32 v146, v182
	v_mov_b32_e32 v147, v183
	v_pk_fma_f32 v[144:145], v[138:139], v[150:151], v[144:145]
	v_pk_fma_f32 v[138:139], v[140:141], v[148:149], v[146:147]
	s_waitcnt vmcnt(11)
	v_mov_b32_e32 v140, v184
	v_mov_b32_e32 v141, v185
	v_lshlrev_b32_e32 v152, 16, v140
	v_and_b32_e32 v153, 0xffff0000, v140
	v_lshlrev_b32_e32 v140, 16, v141
	v_and_b32_e32 v141, 0xffff0000, v141
	s_waitcnt vmcnt(10)
	v_mov_b32_e32 v146, v186
	v_mov_b32_e32 v147, v187
	v_lshlrev_b32_e32 v154, 16, v146
	v_and_b32_e32 v155, 0xffff0000, v146
	v_lshlrev_b32_e32 v146, 16, v147
	v_and_b32_e32 v147, 0xffff0000, v147
	v_pk_add_f32 v[152:153], v[152:153], v[154:155]
	v_pk_add_f32 v[140:141], v[140:141], v[146:147]
	s_waitcnt vmcnt(9)
	v_mov_b32_e32 v148, v188
	v_mov_b32_e32 v149, v189
	v_lshlrev_b32_e32 v146, 16, v148
	v_and_b32_e32 v147, 0xffff0000, v148
	v_lshlrev_b32_e32 v148, 16, v149
	v_and_b32_e32 v149, 0xffff0000, v149
	s_waitcnt vmcnt(8)
	v_mov_b32_e32 v150, v190
	v_mov_b32_e32 v151, v191
	v_lshlrev_b32_e32 v154, 16, v150
	v_and_b32_e32 v155, 0xffff0000, v150
	v_lshlrev_b32_e32 v150, 16, v151
	v_and_b32_e32 v151, 0xffff0000, v151
	v_pk_add_f32 v[146:147], v[146:147], v[154:155]
	v_pk_add_f32 v[148:149], v[148:149], v[150:151]
	v_pk_add_f32 v[146:147], v[152:153], v[146:147]
	v_pk_add_f32 v[140:141], v[140:141], v[148:149]
	v_pk_mul_f32 v[146:147], v[146:147], s[26:27] op_sel_hi:[1,0]
	v_pk_mul_f32 v[140:141], v[140:141], s[26:27] op_sel_hi:[1,0]
	s_nop 0
	v_pk_fma_f32 v[138:139], v[138:139], s[34:35], v[140:141] op_sel_hi:[1,0,1]
	v_pk_fma_f32 v[140:141], v[144:145], s[34:35], v[146:147] op_sel_hi:[1,0,1]
	v_add_f32_e32 v145, v138, v139
	v_add_f32_e32 v144, v140, v141
	v_add_f32_e32 v144, v144, v145
	v_add_f32_e32 v164, v142, v144
	v_mul_f32_e32 v142, v141, v141
	v_mul_f32_e32 v144, v139, v139
	v_fmac_f32_e32 v142, v140, v140
	v_fmac_f32_e32 v144, v138, v138
	v_add_f32_e32 v142, v142, v144
	v_add_f32_e32 v165, v143, v142
	s_waitcnt vmcnt(3)
	v_mov_b32_e32 v142, v192
	v_mov_b32_e32 v143, v193
	v_mov_b32_e32 v144, v194
	v_mov_b32_e32 v145, v195
	v_mov_b32_e32 v146, v196
	v_mov_b32_e32 v147, v197
	v_mov_b32_e32 v156, v198
	v_mov_b32_e32 v157, v199
	v_mov_b32_e32 v148, v200
	v_mov_b32_e32 v149, v201
	v_lshlrev_b32_e32 v150, 16, v148
	v_and_b32_e32 v151, 0xffff0000, v148
	v_lshlrev_b32_e32 v148, 16, v149
	v_and_b32_e32 v149, 0xffff0000, v149
	v_sub_f32_e32 v149, v149, v16
	v_sub_f32_e32 v148, v148, v16
	v_sub_f32_e32 v151, v151, v16
	v_sub_f32_e32 v150, v150, v16
	v_pk_mul_f32 v[160:161], v[16:17], v[150:151] op_sel:[1,0]
	v_pk_mul_f32 v[162:163], v[16:17], v[148:149] op_sel:[1,0]
	s_waitcnt vmcnt(1)
	v_mov_b32_e32 v148, v202
	v_mov_b32_e32 v149, v203
	v_mov_b32_e32 v150, v204
	v_mov_b32_e32 v151, v205
	v_mov_b32_e32 v152, v206
	v_mov_b32_e32 v153, v207
	v_mov_b32_e32 v154, v208
	v_mov_b32_e32 v155, v209
	v_pk_fma_f32 v[150:151], v[150:151], v[162:163], v[154:155]
	v_pk_fma_f32 v[148:149], v[148:149], v[160:161], v[152:153]
	v_lshlrev_b32_e32 v152, 16, v156
	v_and_b32_e32 v153, 0xffff0000, v156
	v_lshlrev_b32_e32 v154, 16, v157
	v_and_b32_e32 v155, 0xffff0000, v157
	v_lshlrev_b32_e32 v156, 16, v146
	v_and_b32_e32 v157, 0xffff0000, v146
	v_lshlrev_b32_e32 v146, 16, v147
	v_and_b32_e32 v147, 0xffff0000, v147
	v_pk_add_f32 v[146:147], v[146:147], v[154:155]
	v_pk_add_f32 v[152:153], v[156:157], v[152:153]
	v_lshlrev_b32_e32 v154, 16, v144
	v_and_b32_e32 v155, 0xffff0000, v144
	v_lshlrev_b32_e32 v144, 16, v145
	v_and_b32_e32 v145, 0xffff0000, v145
	v_lshlrev_b32_e32 v156, 16, v142
	v_and_b32_e32 v157, 0xffff0000, v142
	v_lshlrev_b32_e32 v142, 16, v143
	v_and_b32_e32 v143, 0xffff0000, v143
	v_pk_add_f32 v[142:143], v[142:143], v[144:145]
	v_pk_add_f32 v[144:145], v[156:157], v[154:155]
	v_pk_add_f32 v[142:143], v[142:143], v[146:147]
	v_pk_add_f32 v[144:145], v[144:145], v[152:153]
	v_pk_mul_f32 v[146:147], v[148:149], s[34:35] op_sel_hi:[1,0]
	v_pk_mul_f32 v[148:149], v[150:151], s[34:35] op_sel_hi:[1,0]
	v_pk_fma_f32 v[144:145], v[144:145], s[26:27], v[146:147] op_sel_hi:[1,0,1]
	v_pk_fma_f32 v[142:143], v[142:143], s[26:27], v[148:149] op_sel_hi:[1,0,1]
	v_add_f32_e32 v146, v144, v145
	v_add_f32_e32 v147, v142, v143
	v_add_f32_e32 v146, v146, v147
	v_add_f32_e32 v150, v164, v146
	v_mul_f32_e32 v146, v145, v145
	v_mul_f32_e32 v147, v143, v143
	v_fmac_f32_e32 v146, v144, v144
	v_fmac_f32_e32 v147, v142, v142
	v_add_f32_e32 v146, v146, v147
	v_add_f32_e32 v151, v165, v146
	s_waitcnt vmcnt(0)
	v_mov_b32_e32 v146, v210
	v_mov_b32_e32 v147, v211
	s_mov_b64 s[98:99], 0x3000
	v_lshl_add_u64 v[200:201], v[26:27], 0, s[98:99]
	global_load_dwordx4 v[166:169], v[200:201], off offset:2048
	s_mov_b64 s[98:99], 0x3000
	v_lshl_add_u64 v[202:203], v[28:29], 0, s[98:99]
	global_load_dwordx4 v[170:173], v[202:203], off offset:2048
	s_mov_b64 s[98:99], 0x1000
	v_lshl_add_u64 v[204:205], v[238:239], 0, s[98:99]
	global_load_dwordx2 v[174:175], v[204:205], off offset:3072
	s_mov_b64 s[98:99], 0x1000
	v_lshl_add_u64 v[206:207], v[240:241], 0, s[98:99]
	global_load_dwordx2 v[176:177], v[206:207], off offset:3072
	s_mov_b64 s[98:99], 0x1000
	v_lshl_add_u64 v[208:209], v[242:243], 0, s[98:99]
	global_load_dwordx2 v[178:179], v[208:209], off offset:3072
	s_mov_b64 s[98:99], 0x1000
	v_lshl_add_u64 v[210:211], v[244:245], 0, s[98:99]
	global_load_dwordx2 v[180:181], v[210:211], off offset:3072
	global_load_dwordx2 v[182:183], v[210:211], off offset:3584
	global_load_dwordx2 v[184:185], v[208:209], off offset:3584
	global_load_dwordx2 v[186:187], v[206:207], off offset:3584
	global_load_dwordx2 v[188:189], v[204:205], off offset:3584
	s_mov_b64 s[98:99], 0x1000
	v_lshl_add_u64 v[212:213], v[246:247], 0, s[98:99]
	global_load_dwordx2 v[190:191], v[212:213], off offset:3584
	global_load_dwordx4 v[192:195], v[200:201], off offset:3072
	global_load_dwordx4 v[196:199], v[202:203], off offset:3072
	v_lshlrev_b32_e32 v148, 16, v146
	v_and_b32_e32 v146, 0xffff0000, v146
	v_lshlrev_b32_e32 v152, 16, v147
	v_and_b32_e32 v149, 0xffff0000, v147
	v_sub_f32_e32 v147, v146, v16
	v_sub_f32_e32 v146, v148, v16
	v_sub_f32_e32 v149, v149, v16
	v_sub_f32_e32 v148, v152, v16
	v_pk_mul_f32 v[156:157], v[16:17], v[148:149] op_sel:[1,0]
	v_pk_mul_f32 v[160:161], v[16:17], v[146:147] op_sel:[1,0]
	s_waitcnt vmcnt(11)
	v_mov_b32_e32 v146, v166
	v_mov_b32_e32 v147, v167
	v_mov_b32_e32 v148, v168
	v_mov_b32_e32 v149, v169
	v_mov_b32_e32 v152, v170
	v_mov_b32_e32 v153, v171
	v_mov_b32_e32 v154, v172
	v_mov_b32_e32 v155, v173
	v_pk_fma_f32 v[152:153], v[146:147], v[160:161], v[152:153]
	v_pk_fma_f32 v[146:147], v[148:149], v[156:157], v[154:155]
	s_waitcnt vmcnt(10)
	v_mov_b32_e32 v148, v174
	v_mov_b32_e32 v149, v175
	v_lshlrev_b32_e32 v162, 16, v148
	v_and_b32_e32 v163, 0xffff0000, v148
	v_lshlrev_b32_e32 v148, 16, v149
	v_and_b32_e32 v149, 0xffff0000, v149
	s_waitcnt vmcnt(9)
	v_mov_b32_e32 v154, v176
	v_mov_b32_e32 v155, v177
	v_lshlrev_b32_e32 v164, 16, v154
	v_and_b32_e32 v165, 0xffff0000, v154
	v_lshlrev_b32_e32 v154, 16, v155
	v_and_b32_e32 v155, 0xffff0000, v155
	v_pk_add_f32 v[162:163], v[162:163], v[164:165]
	v_pk_add_f32 v[148:149], v[148:149], v[154:155]
	s_waitcnt vmcnt(8)
	v_mov_b32_e32 v156, v178
	v_mov_b32_e32 v157, v179
	v_lshlrev_b32_e32 v154, 16, v156
	v_and_b32_e32 v155, 0xffff0000, v156
	v_lshlrev_b32_e32 v156, 16, v157
	v_and_b32_e32 v157, 0xffff0000, v157
	s_waitcnt vmcnt(7)
	v_mov_b32_e32 v160, v180
	v_mov_b32_e32 v161, v181
	v_lshlrev_b32_e32 v164, 16, v160
	v_and_b32_e32 v165, 0xffff0000, v160
	v_lshlrev_b32_e32 v160, 16, v161
	v_and_b32_e32 v161, 0xffff0000, v161
	v_pk_add_f32 v[154:155], v[154:155], v[164:165]
	v_pk_add_f32 v[156:157], v[156:157], v[160:161]
	v_pk_add_f32 v[154:155], v[162:163], v[154:155]
	v_pk_add_f32 v[148:149], v[148:149], v[156:157]
	v_pk_mul_f32 v[154:155], v[154:155], s[26:27] op_sel_hi:[1,0]
	v_pk_mul_f32 v[148:149], v[148:149], s[26:27] op_sel_hi:[1,0]
	s_nop 0
	v_pk_fma_f32 v[146:147], v[146:147], s[34:35], v[148:149] op_sel_hi:[1,0,1]
	v_pk_fma_f32 v[148:149], v[152:153], s[34:35], v[154:155] op_sel_hi:[1,0,1]
	v_add_f32_e32 v153, v146, v147
	v_add_f32_e32 v152, v148, v149
	v_add_f32_e32 v152, v152, v153
	v_add_f32_e32 v161, v150, v152
	v_mul_f32_e32 v150, v149, v149
	v_mul_f32_e32 v152, v147, v147
	v_fmac_f32_e32 v150, v148, v148
	v_fmac_f32_e32 v152, v146, v146
	v_add_f32_e32 v150, v150, v152
	v_add_f32_e32 v160, v151, v150
	s_nop 0
	s_nop 0
	s_waitcnt vmcnt(2)
	v_mov_b32_e32 v98, v182
	v_mov_b32_e32 v99, v183
	v_mov_b32_e32 v150, v184
	v_mov_b32_e32 v151, v185
	v_mov_b32_e32 v152, v186
	v_mov_b32_e32 v153, v187
	v_mov_b32_e32 v154, v188
	v_mov_b32_e32 v155, v189
	v_mov_b32_e32 v18, v190
	v_mov_b32_e32 v19, v191
	v_lshlrev_b32_e32 v20, 16, v18
	v_and_b32_e32 v21, 0xffff0000, v18
	v_lshlrev_b32_e32 v18, 16, v19
	v_and_b32_e32 v19, 0xffff0000, v19
	v_sub_f32_e32 v19, v19, v16
	v_sub_f32_e32 v18, v18, v16
	v_sub_f32_e32 v21, v21, v16
	v_sub_f32_e32 v20, v20, v16
	v_pk_mul_f32 v[132:133], v[16:17], v[20:21] op_sel:[1,0]
	v_pk_mul_f32 v[156:157], v[16:17], v[18:19] op_sel:[1,0]
	s_waitcnt vmcnt(0)
	v_mov_b32_e32 v16, v192
	v_mov_b32_e32 v17, v193
	v_mov_b32_e32 v18, v194
	v_mov_b32_e32 v19, v195
	v_mov_b32_e32 v20, v196
	v_mov_b32_e32 v21, v197
	v_mov_b32_e32 v22, v198
	v_mov_b32_e32 v23, v199
	v_pk_fma_f32 v[18:19], v[18:19], v[156:157], v[22:23]
	v_pk_fma_f32 v[16:17], v[16:17], v[132:133], v[20:21]
	v_lshlrev_b32_e32 v20, 16, v154
	v_and_b32_e32 v21, 0xffff0000, v154
	v_lshlrev_b32_e32 v22, 16, v155
	v_and_b32_e32 v23, 0xffff0000, v155
	v_lshlrev_b32_e32 v132, 16, v152
	v_and_b32_e32 v133, 0xffff0000, v152
	v_lshlrev_b32_e32 v152, 16, v153
	v_and_b32_e32 v153, 0xffff0000, v153
	v_pk_add_f32 v[22:23], v[152:153], v[22:23]
	v_pk_add_f32 v[20:21], v[132:133], v[20:21]
	v_lshlrev_b32_e32 v132, 16, v150
	v_and_b32_e32 v133, 0xffff0000, v150
	v_lshlrev_b32_e32 v150, 16, v151
	v_and_b32_e32 v151, 0xffff0000, v151
	v_lshlrev_b32_e32 v152, 16, v98
	v_and_b32_e32 v153, 0xffff0000, v98
	v_lshlrev_b32_e32 v98, 16, v99
	v_and_b32_e32 v99, 0xffff0000, v99
	v_pk_add_f32 v[98:99], v[98:99], v[150:151]
	v_pk_add_f32 v[132:133], v[152:153], v[132:133]
	v_pk_add_f32 v[22:23], v[98:99], v[22:23]
	v_pk_add_f32 v[20:21], v[132:133], v[20:21]
	v_pk_mul_f32 v[98:99], v[16:17], s[34:35] op_sel_hi:[1,0]
	v_pk_mul_f32 v[16:17], v[18:19], s[34:35] op_sel_hi:[1,0]
	v_pk_fma_f32 v[18:19], v[20:21], s[26:27], v[98:99] op_sel_hi:[1,0,1]
	v_pk_fma_f32 v[16:17], v[22:23], s[26:27], v[16:17] op_sel_hi:[1,0,1]
	v_add_f32_e32 v20, v18, v19
	v_add_f32_e32 v21, v16, v17
	v_add_f32_e32 v20, v20, v21
	v_mul_f32_e32 v21, v19, v19
	v_mul_f32_e32 v22, v17, v17
	v_add_f32_e32 v20, v161, v20
	v_fmac_f32_e32 v21, v18, v18
	v_fmac_f32_e32 v22, v16, v16
	v_add_f32_e32 v21, v21, v22
	ds_swizzle_b32 v22, v20 offset:swizzle(SWAP,1)
	v_add_f32_e32 v21, v160, v21
	v_and_b32_sdwa v99, v88, v159 dst_sel:DWORD dst_unused:UNUSED_PAD src0_sel:WORD_1 src1_sel:DWORD
	v_add3_u32 v132, v88, v99, s3
	v_and_b32_sdwa v99, v87, v159 dst_sel:DWORD dst_unused:UNUSED_PAD src0_sel:WORD_1 src1_sel:DWORD
	s_waitcnt lgkmcnt(0)
	v_add_f32_e32 v20, v20, v22
	ds_swizzle_b32 v22, v20 offset:swizzle(SWAP,2)
	v_and_b32_sdwa v133, v89, v159 dst_sel:DWORD dst_unused:UNUSED_PAD src0_sel:WORD_1 src1_sel:DWORD
	v_and_b32_sdwa v98, v86, v159 dst_sel:DWORD dst_unused:UNUSED_PAD src0_sel:WORD_1 src1_sel:DWORD
	v_add3_u32 v99, v87, v99, s3
	v_add3_u32 v133, v89, v133, s3
	s_waitcnt lgkmcnt(0)
	v_add_f32_e32 v20, v20, v22
	ds_swizzle_b32 v22, v20 offset:swizzle(SWAP,4)
	v_add3_u32 v98, v86, v98, s3
	v_and_b32_e32 v99, 0xffff0000, v99
	v_and_b32_e32 v133, 0xffff0000, v133
	v_or_b32_sdwa v99, v99, v98 dst_sel:DWORD dst_unused:UNUSED_PAD src0_sel:DWORD src1_sel:WORD_1
	s_waitcnt lgkmcnt(0)
	v_add_f32_e32 v20, v20, v22
	ds_swizzle_b32 v22, v20 offset:swizzle(SWAP,8)
	v_or_b32_sdwa v98, v133, v132 dst_sel:DWORD dst_unused:UNUSED_PAD src0_sel:DWORD src1_sel:WORD_1
	s_waitcnt lgkmcnt(0)
	v_add_f32_e32 v20, v20, v22
	ds_swizzle_b32 v22, v20 offset:swizzle(SWAP,16)
	s_waitcnt lgkmcnt(0)
	v_add_f32_e32 v20, v20, v22
	s_nop 0
	v_readlane_b32 s9, v20, 0
	v_readlane_b32 s23, v20, 32
	ds_swizzle_b32 v20, v21 offset:swizzle(SWAP,1)
	v_lshl_add_u64 v[22:23], v[84:85], 0, s[24:25]
	global_store_dwordx2 v[22:23], v[98:99], off sc1
	s_nop 1
	v_mov_b32_e32 v22, 0
	v_cvt_pk_fp8_f32 v22, v88, v89
	s_waitcnt lgkmcnt(0)
	v_add_f32_e32 v20, v21, v20
	ds_swizzle_b32 v21, v20 offset:swizzle(SWAP,2)
	v_and_b32_sdwa v23, v92, v159 dst_sel:DWORD dst_unused:UNUSED_PAD src0_sel:WORD_1 src1_sel:DWORD
	v_cvt_pk_fp8_f32 v22, v86, v87 op_sel:[0,0,1]
	v_add3_u32 v86, v92, v23, s3
	v_and_b32_sdwa v23, v91, v159 dst_sel:DWORD dst_unused:UNUSED_PAD src0_sel:WORD_1 src1_sel:DWORD
	s_waitcnt lgkmcnt(0)
	v_add_f32_e32 v20, v20, v21
	ds_swizzle_b32 v21, v20 offset:swizzle(SWAP,4)
	v_and_b32_sdwa v87, v93, v159 dst_sel:DWORD dst_unused:UNUSED_PAD src0_sel:WORD_1 src1_sel:DWORD
	v_add3_u32 v23, v91, v23, s3
	v_add3_u32 v87, v93, v87, s3
	v_and_b32_e32 v23, 0xffff0000, v23
	s_waitcnt lgkmcnt(0)
	v_add_f32_e32 v20, v20, v21
	ds_swizzle_b32 v21, v20 offset:swizzle(SWAP,8)
	v_and_b32_e32 v87, 0xffff0000, v87
	s_mov_b64 s[24:25], 0x6b00200
	s_waitcnt lgkmcnt(0)
	v_add_f32_e32 v20, v20, v21
	ds_swizzle_b32 v21, v20 offset:swizzle(SWAP,16)
	s_waitcnt lgkmcnt(0)
	v_add_f32_e32 v20, v20, v21
	s_nop 0
	v_readlane_b32 s8, v20, 0
	v_readlane_b32 s27, v20, 32
	v_lshl_add_u64 v[20:21], s[12:13], 0, v[80:81]
	global_store_dword v[20:21], v22, off sc1
	s_nop 1
	v_and_b32_sdwa v22, v90, v159 dst_sel:DWORD dst_unused:UNUSED_PAD src0_sel:WORD_1 src1_sel:DWORD
	v_add3_u32 v22, v90, v22, s3
	v_or_b32_sdwa v23, v23, v22 dst_sel:DWORD dst_unused:UNUSED_PAD src0_sel:DWORD src1_sel:WORD_1
	v_or_b32_sdwa v22, v87, v86 dst_sel:DWORD dst_unused:UNUSED_PAD src0_sel:DWORD src1_sel:WORD_1
	v_lshl_add_u64 v[86:87], v[84:85], 0, s[24:25]
	global_store_dwordx2 v[86:87], v[22:23], off sc1
	s_nop 1
	v_mov_b32_e32 v86, 0
	v_cvt_pk_fp8_f32 v86, v92, v93
	s_mov_b64 s[24:25], 0x100
	v_lshl_add_u64 v[22:23], v[20:21], 0, s[24:25]
	v_and_b32_sdwa v87, v97, v159 dst_sel:DWORD dst_unused:UNUSED_PAD src0_sel:WORD_1 src1_sel:DWORD
	v_cvt_pk_fp8_f32 v86, v90, v91 op_sel:[0,0,1]
	v_add3_u32 v87, v97, v87, s3
	global_store_dword v[22:23], v86, off sc1
	s_nop 1
	v_and_b32_sdwa v23, v96, v159 dst_sel:DWORD dst_unused:UNUSED_PAD src0_sel:WORD_1 src1_sel:DWORD
	v_add3_u32 v86, v96, v23, s3
	v_and_b32_sdwa v23, v95, v159 dst_sel:DWORD dst_unused:UNUSED_PAD src0_sel:WORD_1 src1_sel:DWORD
	v_and_b32_sdwa v22, v94, v159 dst_sel:DWORD dst_unused:UNUSED_PAD src0_sel:WORD_1 src1_sel:DWORD
	v_add3_u32 v23, v95, v23, s3
	v_add3_u32 v22, v94, v22, s3
	v_and_b32_e32 v23, 0xffff0000, v23
	v_and_b32_e32 v87, 0xffff0000, v87
	s_mov_b64 s[24:25], 0x6b00400
	v_or_b32_sdwa v23, v23, v22 dst_sel:DWORD dst_unused:UNUSED_PAD src0_sel:DWORD src1_sel:WORD_1
	v_or_b32_sdwa v22, v87, v86 dst_sel:DWORD dst_unused:UNUSED_PAD src0_sel:DWORD src1_sel:WORD_1
	v_lshl_add_u64 v[86:87], v[84:85], 0, s[24:25]
	global_store_dwordx2 v[86:87], v[22:23], off sc1
	s_nop 1
	v_mov_b32_e32 v86, 0
	v_cvt_pk_fp8_f32 v86, v96, v97
	s_mov_b64 s[24:25], 0x200
	v_lshl_add_u64 v[22:23], v[20:21], 0, s[24:25]
	v_and_b32_sdwa v87, v103, v159 dst_sel:DWORD dst_unused:UNUSED_PAD src0_sel:WORD_1 src1_sel:DWORD
	v_cvt_pk_fp8_f32 v86, v94, v95 op_sel:[0,0,1]
	v_add3_u32 v87, v103, v87, s3
	global_store_dword v[22:23], v86, off sc1
	s_nop 1
	v_and_b32_sdwa v23, v102, v159 dst_sel:DWORD dst_unused:UNUSED_PAD src0_sel:WORD_1 src1_sel:DWORD
	v_add3_u32 v86, v102, v23, s3
	v_and_b32_sdwa v23, v101, v159 dst_sel:DWORD dst_unused:UNUSED_PAD src0_sel:WORD_1 src1_sel:DWORD
	v_and_b32_sdwa v22, v100, v159 dst_sel:DWORD dst_unused:UNUSED_PAD src0_sel:WORD_1 src1_sel:DWORD
	v_add3_u32 v23, v101, v23, s3
	v_add3_u32 v22, v100, v22, s3
	v_and_b32_e32 v23, 0xffff0000, v23
	v_and_b32_e32 v87, 0xffff0000, v87
	s_mov_b64 s[24:25], 0x6b00600
	v_or_b32_sdwa v23, v23, v22 dst_sel:DWORD dst_unused:UNUSED_PAD src0_sel:DWORD src1_sel:WORD_1
	v_or_b32_sdwa v22, v87, v86 dst_sel:DWORD dst_unused:UNUSED_PAD src0_sel:DWORD src1_sel:WORD_1
	v_lshl_add_u64 v[86:87], v[84:85], 0, s[24:25]
	global_store_dwordx2 v[86:87], v[22:23], off sc1
	s_nop 1
	v_mov_b32_e32 v86, 0
	v_cvt_pk_fp8_f32 v86, v102, v103
	s_mov_b64 s[24:25], 0x300
	v_lshl_add_u64 v[22:23], v[20:21], 0, s[24:25]
	v_and_b32_sdwa v87, v107, v159 dst_sel:DWORD dst_unused:UNUSED_PAD src0_sel:WORD_1 src1_sel:DWORD
	v_cvt_pk_fp8_f32 v86, v100, v101 op_sel:[0,0,1]
	v_add3_u32 v87, v107, v87, s3
	global_store_dword v[22:23], v86, off sc1
	s_nop 1
	v_and_b32_sdwa v23, v106, v159 dst_sel:DWORD dst_unused:UNUSED_PAD src0_sel:WORD_1 src1_sel:DWORD
	v_add3_u32 v86, v106, v23, s3
	v_and_b32_sdwa v23, v105, v159 dst_sel:DWORD dst_unused:UNUSED_PAD src0_sel:WORD_1 src1_sel:DWORD
	v_and_b32_sdwa v22, v104, v159 dst_sel:DWORD dst_unused:UNUSED_PAD src0_sel:WORD_1 src1_sel:DWORD
	v_add3_u32 v23, v105, v23, s3
	v_add3_u32 v22, v104, v22, s3
	v_and_b32_e32 v23, 0xffff0000, v23
	v_and_b32_e32 v87, 0xffff0000, v87
	s_mov_b64 s[24:25], 0x6b00800
	v_or_b32_sdwa v23, v23, v22 dst_sel:DWORD dst_unused:UNUSED_PAD src0_sel:DWORD src1_sel:WORD_1
	v_or_b32_sdwa v22, v87, v86 dst_sel:DWORD dst_unused:UNUSED_PAD src0_sel:DWORD src1_sel:WORD_1
	v_lshl_add_u64 v[86:87], v[84:85], 0, s[24:25]
	global_store_dwordx2 v[86:87], v[22:23], off sc1
	s_nop 1
	v_mov_b32_e32 v86, 0
	v_cvt_pk_fp8_f32 v86, v106, v107
	s_mov_b64 s[24:25], 0x400
	v_lshl_add_u64 v[22:23], v[20:21], 0, s[24:25]
	v_and_b32_sdwa v87, v111, v159 dst_sel:DWORD dst_unused:UNUSED_PAD src0_sel:WORD_1 src1_sel:DWORD
	v_cvt_pk_fp8_f32 v86, v104, v105 op_sel:[0,0,1]
	v_add3_u32 v87, v111, v87, s3
	global_store_dword v[22:23], v86, off sc1
	s_nop 1
	v_and_b32_sdwa v23, v110, v159 dst_sel:DWORD dst_unused:UNUSED_PAD src0_sel:WORD_1 src1_sel:DWORD
	v_add3_u32 v86, v110, v23, s3
	v_and_b32_sdwa v23, v109, v159 dst_sel:DWORD dst_unused:UNUSED_PAD src0_sel:WORD_1 src1_sel:DWORD
	v_and_b32_sdwa v22, v108, v159 dst_sel:DWORD dst_unused:UNUSED_PAD src0_sel:WORD_1 src1_sel:DWORD
	v_add3_u32 v23, v109, v23, s3
	v_add3_u32 v22, v108, v22, s3
	v_and_b32_e32 v23, 0xffff0000, v23
	v_and_b32_e32 v87, 0xffff0000, v87
	s_mov_b64 s[24:25], 0x6b00a00
	v_or_b32_sdwa v23, v23, v22 dst_sel:DWORD dst_unused:UNUSED_PAD src0_sel:DWORD src1_sel:WORD_1
	v_or_b32_sdwa v22, v87, v86 dst_sel:DWORD dst_unused:UNUSED_PAD src0_sel:DWORD src1_sel:WORD_1
	v_lshl_add_u64 v[86:87], v[84:85], 0, s[24:25]
	global_store_dwordx2 v[86:87], v[22:23], off sc1
	s_nop 1
	v_mov_b32_e32 v86, 0
	v_cvt_pk_fp8_f32 v86, v110, v111
	s_mov_b64 s[24:25], 0x500
	v_lshl_add_u64 v[22:23], v[20:21], 0, s[24:25]
	v_and_b32_sdwa v87, v115, v159 dst_sel:DWORD dst_unused:UNUSED_PAD src0_sel:WORD_1 src1_sel:DWORD
	v_cvt_pk_fp8_f32 v86, v108, v109 op_sel:[0,0,1]
	v_add3_u32 v87, v115, v87, s3
	global_store_dword v[22:23], v86, off sc1
	s_nop 1
	v_and_b32_sdwa v23, v114, v159 dst_sel:DWORD dst_unused:UNUSED_PAD src0_sel:WORD_1 src1_sel:DWORD
	v_add3_u32 v86, v114, v23, s3
	v_and_b32_sdwa v23, v113, v159 dst_sel:DWORD dst_unused:UNUSED_PAD src0_sel:WORD_1 src1_sel:DWORD
	v_and_b32_sdwa v22, v112, v159 dst_sel:DWORD dst_unused:UNUSED_PAD src0_sel:WORD_1 src1_sel:DWORD
	v_add3_u32 v23, v113, v23, s3
	v_add3_u32 v22, v112, v22, s3
	v_and_b32_e32 v23, 0xffff0000, v23
	v_and_b32_e32 v87, 0xffff0000, v87
	s_mov_b64 s[24:25], 0x6b00c00
	v_or_b32_sdwa v23, v23, v22 dst_sel:DWORD dst_unused:UNUSED_PAD src0_sel:DWORD src1_sel:WORD_1
	v_or_b32_sdwa v22, v87, v86 dst_sel:DWORD dst_unused:UNUSED_PAD src0_sel:DWORD src1_sel:WORD_1
	v_lshl_add_u64 v[86:87], v[84:85], 0, s[24:25]
	global_store_dwordx2 v[86:87], v[22:23], off sc1
	s_nop 1
	v_mov_b32_e32 v86, 0
	v_cvt_pk_fp8_f32 v86, v114, v115
	s_mov_b64 s[24:25], 0x600
	v_lshl_add_u64 v[22:23], v[20:21], 0, s[24:25]
	v_and_b32_sdwa v87, v119, v159 dst_sel:DWORD dst_unused:UNUSED_PAD src0_sel:WORD_1 src1_sel:DWORD
	v_cvt_pk_fp8_f32 v86, v112, v113 op_sel:[0,0,1]
	v_add3_u32 v87, v119, v87, s3
	global_store_dword v[22:23], v86, off sc1
	s_nop 1
	v_and_b32_sdwa v23, v118, v159 dst_sel:DWORD dst_unused:UNUSED_PAD src0_sel:WORD_1 src1_sel:DWORD
	v_add3_u32 v86, v118, v23, s3
	v_and_b32_sdwa v23, v117, v159 dst_sel:DWORD dst_unused:UNUSED_PAD src0_sel:WORD_1 src1_sel:DWORD
	v_and_b32_sdwa v22, v116, v159 dst_sel:DWORD dst_unused:UNUSED_PAD src0_sel:WORD_1 src1_sel:DWORD
	v_add3_u32 v23, v117, v23, s3
	v_add3_u32 v22, v116, v22, s3
	v_and_b32_e32 v23, 0xffff0000, v23
	v_and_b32_e32 v87, 0xffff0000, v87
	s_mov_b64 s[24:25], 0x6b00e00
	v_or_b32_sdwa v23, v23, v22 dst_sel:DWORD dst_unused:UNUSED_PAD src0_sel:DWORD src1_sel:WORD_1
	v_or_b32_sdwa v22, v87, v86 dst_sel:DWORD dst_unused:UNUSED_PAD src0_sel:DWORD src1_sel:WORD_1
	v_lshl_add_u64 v[86:87], v[84:85], 0, s[24:25]
	global_store_dwordx2 v[86:87], v[22:23], off sc1
	s_nop 1
	v_mov_b32_e32 v86, 0
	v_cvt_pk_fp8_f32 v86, v118, v119
	s_mov_b64 s[24:25], 0x700
	v_lshl_add_u64 v[22:23], v[20:21], 0, s[24:25]
	v_and_b32_sdwa v87, v123, v159 dst_sel:DWORD dst_unused:UNUSED_PAD src0_sel:WORD_1 src1_sel:DWORD
	v_cvt_pk_fp8_f32 v86, v116, v117 op_sel:[0,0,1]
	v_add3_u32 v87, v123, v87, s3
	global_store_dword v[22:23], v86, off sc1
	s_nop 1
	v_and_b32_sdwa v23, v122, v159 dst_sel:DWORD dst_unused:UNUSED_PAD src0_sel:WORD_1 src1_sel:DWORD
	v_add3_u32 v86, v122, v23, s3
	v_and_b32_sdwa v23, v121, v159 dst_sel:DWORD dst_unused:UNUSED_PAD src0_sel:WORD_1 src1_sel:DWORD
	v_and_b32_sdwa v22, v120, v159 dst_sel:DWORD dst_unused:UNUSED_PAD src0_sel:WORD_1 src1_sel:DWORD
	v_add3_u32 v23, v121, v23, s3
	v_add3_u32 v22, v120, v22, s3
	v_and_b32_e32 v23, 0xffff0000, v23
	v_and_b32_e32 v87, 0xffff0000, v87
	s_mov_b64 s[24:25], 0x6b01000
	v_or_b32_sdwa v23, v23, v22 dst_sel:DWORD dst_unused:UNUSED_PAD src0_sel:DWORD src1_sel:WORD_1
	v_or_b32_sdwa v22, v87, v86 dst_sel:DWORD dst_unused:UNUSED_PAD src0_sel:DWORD src1_sel:WORD_1
	v_lshl_add_u64 v[86:87], v[84:85], 0, s[24:25]
	global_store_dwordx2 v[86:87], v[22:23], off sc1
	s_nop 1
	v_mov_b32_e32 v86, 0
	v_cvt_pk_fp8_f32 v86, v122, v123
	v_lshl_add_u64 v[22:23], v[20:21], 0, s[36:37]
	v_and_b32_sdwa v87, v127, v159 dst_sel:DWORD dst_unused:UNUSED_PAD src0_sel:WORD_1 src1_sel:DWORD
	v_add3_u32 v87, v127, v87, s3
	v_cvt_pk_fp8_f32 v86, v120, v121 op_sel:[0,0,1]
	v_and_b32_e32 v87, 0xffff0000, v87
	global_store_dword v[22:23], v86, off sc1
	s_nop 1
	v_and_b32_sdwa v23, v126, v159 dst_sel:DWORD dst_unused:UNUSED_PAD src0_sel:WORD_1 src1_sel:DWORD
	v_add3_u32 v86, v126, v23, s3
	v_and_b32_sdwa v23, v125, v159 dst_sel:DWORD dst_unused:UNUSED_PAD src0_sel:WORD_1 src1_sel:DWORD
	v_and_b32_sdwa v22, v124, v159 dst_sel:DWORD dst_unused:UNUSED_PAD src0_sel:WORD_1 src1_sel:DWORD
	v_add3_u32 v23, v125, v23, s3
	v_add3_u32 v22, v124, v22, s3
	v_and_b32_e32 v23, 0xffff0000, v23
	v_or_b32_sdwa v23, v23, v22 dst_sel:DWORD dst_unused:UNUSED_PAD src0_sel:DWORD src1_sel:WORD_1
	v_or_b32_sdwa v22, v87, v86 dst_sel:DWORD dst_unused:UNUSED_PAD src0_sel:DWORD src1_sel:WORD_1
	v_lshl_add_u64 v[86:87], v[84:85], 0, s[38:39]
	global_store_dwordx2 v[86:87], v[22:23], off sc1
	s_nop 1
	v_mov_b32_e32 v86, 0
	v_cvt_pk_fp8_f32 v86, v126, v127
	v_lshl_add_u64 v[22:23], v[20:21], 0, s[40:41]
	v_and_b32_sdwa v87, v131, v159 dst_sel:DWORD dst_unused:UNUSED_PAD src0_sel:WORD_1 src1_sel:DWORD
	v_add3_u32 v87, v131, v87, s3
	v_cvt_pk_fp8_f32 v86, v124, v125 op_sel:[0,0,1]
	v_and_b32_e32 v87, 0xffff0000, v87
	global_store_dword v[22:23], v86, off sc1
	s_nop 1
	v_and_b32_sdwa v23, v130, v159 dst_sel:DWORD dst_unused:UNUSED_PAD src0_sel:WORD_1 src1_sel:DWORD
	v_add3_u32 v86, v130, v23, s3
	v_and_b32_sdwa v23, v129, v159 dst_sel:DWORD dst_unused:UNUSED_PAD src0_sel:WORD_1 src1_sel:DWORD
	v_and_b32_sdwa v22, v128, v159 dst_sel:DWORD dst_unused:UNUSED_PAD src0_sel:WORD_1 src1_sel:DWORD
	v_add3_u32 v23, v129, v23, s3
	v_add3_u32 v22, v128, v22, s3
	v_and_b32_e32 v23, 0xffff0000, v23
	v_or_b32_sdwa v23, v23, v22 dst_sel:DWORD dst_unused:UNUSED_PAD src0_sel:DWORD src1_sel:WORD_1
	v_or_b32_sdwa v22, v87, v86 dst_sel:DWORD dst_unused:UNUSED_PAD src0_sel:DWORD src1_sel:WORD_1
	v_lshl_add_u64 v[86:87], v[84:85], 0, s[42:43]
	global_store_dwordx2 v[86:87], v[22:23], off sc1
	s_nop 1
	v_mov_b32_e32 v86, 0
	v_cvt_pk_fp8_f32 v86, v130, v131
	v_lshl_add_u64 v[22:23], v[20:21], 0, s[44:45]
	v_and_b32_sdwa v87, v137, v159 dst_sel:DWORD dst_unused:UNUSED_PAD src0_sel:WORD_1 src1_sel:DWORD
	v_add3_u32 v87, v137, v87, s3
	v_cvt_pk_fp8_f32 v86, v128, v129 op_sel:[0,0,1]
	v_and_b32_e32 v87, 0xffff0000, v87
	global_store_dword v[22:23], v86, off sc1
	s_nop 1
	v_and_b32_sdwa v23, v136, v159 dst_sel:DWORD dst_unused:UNUSED_PAD src0_sel:WORD_1 src1_sel:DWORD
	v_add3_u32 v86, v136, v23, s3
	v_and_b32_sdwa v23, v135, v159 dst_sel:DWORD dst_unused:UNUSED_PAD src0_sel:WORD_1 src1_sel:DWORD
	v_and_b32_sdwa v22, v134, v159 dst_sel:DWORD dst_unused:UNUSED_PAD src0_sel:WORD_1 src1_sel:DWORD
	v_add3_u32 v23, v135, v23, s3
	v_add3_u32 v22, v134, v22, s3
	v_and_b32_e32 v23, 0xffff0000, v23
	v_or_b32_sdwa v23, v23, v22 dst_sel:DWORD dst_unused:UNUSED_PAD src0_sel:DWORD src1_sel:WORD_1
	v_or_b32_sdwa v22, v87, v86 dst_sel:DWORD dst_unused:UNUSED_PAD src0_sel:DWORD src1_sel:WORD_1
	v_lshl_add_u64 v[86:87], v[84:85], 0, s[46:47]
	global_store_dwordx2 v[86:87], v[22:23], off sc1
	s_nop 1
	v_mov_b32_e32 v86, 0
	v_cvt_pk_fp8_f32 v86, v136, v137
	v_lshl_add_u64 v[22:23], v[20:21], 0, s[48:49]
	v_and_b32_sdwa v87, v141, v159 dst_sel:DWORD dst_unused:UNUSED_PAD src0_sel:WORD_1 src1_sel:DWORD
	v_add3_u32 v87, v141, v87, s3
	v_cvt_pk_fp8_f32 v86, v134, v135 op_sel:[0,0,1]
	v_and_b32_e32 v87, 0xffff0000, v87
	global_store_dword v[22:23], v86, off sc1
	s_nop 1
	v_and_b32_sdwa v23, v140, v159 dst_sel:DWORD dst_unused:UNUSED_PAD src0_sel:WORD_1 src1_sel:DWORD
	v_add3_u32 v86, v140, v23, s3
	v_and_b32_sdwa v23, v139, v159 dst_sel:DWORD dst_unused:UNUSED_PAD src0_sel:WORD_1 src1_sel:DWORD
	v_and_b32_sdwa v22, v138, v159 dst_sel:DWORD dst_unused:UNUSED_PAD src0_sel:WORD_1 src1_sel:DWORD
	v_add3_u32 v23, v139, v23, s3
	v_add3_u32 v22, v138, v22, s3
	v_and_b32_e32 v23, 0xffff0000, v23
	v_or_b32_sdwa v23, v23, v22 dst_sel:DWORD dst_unused:UNUSED_PAD src0_sel:DWORD src1_sel:WORD_1
	v_or_b32_sdwa v22, v87, v86 dst_sel:DWORD dst_unused:UNUSED_PAD src0_sel:DWORD src1_sel:WORD_1
	v_lshl_add_u64 v[86:87], v[84:85], 0, s[50:51]
	global_store_dwordx2 v[86:87], v[22:23], off sc1
	s_nop 1
	v_mov_b32_e32 v86, 0
	v_cvt_pk_fp8_f32 v86, v140, v141
	v_lshl_add_u64 v[22:23], v[20:21], 0, s[52:53]
	v_and_b32_sdwa v87, v145, v159 dst_sel:DWORD dst_unused:UNUSED_PAD src0_sel:WORD_1 src1_sel:DWORD
	v_add3_u32 v87, v145, v87, s3
	v_cvt_pk_fp8_f32 v86, v138, v139 op_sel:[0,0,1]
	v_and_b32_e32 v87, 0xffff0000, v87
	global_store_dword v[22:23], v86, off sc1
	s_nop 1
	v_and_b32_sdwa v23, v144, v159 dst_sel:DWORD dst_unused:UNUSED_PAD src0_sel:WORD_1 src1_sel:DWORD
	v_add3_u32 v86, v144, v23, s3
	v_and_b32_sdwa v23, v143, v159 dst_sel:DWORD dst_unused:UNUSED_PAD src0_sel:WORD_1 src1_sel:DWORD
	v_and_b32_sdwa v22, v142, v159 dst_sel:DWORD dst_unused:UNUSED_PAD src0_sel:WORD_1 src1_sel:DWORD
	v_add3_u32 v23, v143, v23, s3
	v_add3_u32 v22, v142, v22, s3
	v_and_b32_e32 v23, 0xffff0000, v23
	v_or_b32_sdwa v23, v23, v22 dst_sel:DWORD dst_unused:UNUSED_PAD src0_sel:DWORD src1_sel:WORD_1
	v_or_b32_sdwa v22, v87, v86 dst_sel:DWORD dst_unused:UNUSED_PAD src0_sel:DWORD src1_sel:WORD_1
	v_lshl_add_u64 v[86:87], v[84:85], 0, s[54:55]
	global_store_dwordx2 v[86:87], v[22:23], off sc1
	s_nop 1
	v_mov_b32_e32 v86, 0
	v_cvt_pk_fp8_f32 v86, v144, v145
	v_lshl_add_u64 v[22:23], v[20:21], 0, s[56:57]
	v_and_b32_sdwa v87, v149, v159 dst_sel:DWORD dst_unused:UNUSED_PAD src0_sel:WORD_1 src1_sel:DWORD
	v_add3_u32 v87, v149, v87, s3
	v_cvt_pk_fp8_f32 v86, v142, v143 op_sel:[0,0,1]
	v_and_b32_e32 v87, 0xffff0000, v87
	global_store_dword v[22:23], v86, off sc1
	s_nop 1
	v_and_b32_sdwa v23, v148, v159 dst_sel:DWORD dst_unused:UNUSED_PAD src0_sel:WORD_1 src1_sel:DWORD
	v_add3_u32 v86, v148, v23, s3
	v_and_b32_sdwa v23, v147, v159 dst_sel:DWORD dst_unused:UNUSED_PAD src0_sel:WORD_1 src1_sel:DWORD
	v_and_b32_sdwa v22, v146, v159 dst_sel:DWORD dst_unused:UNUSED_PAD src0_sel:WORD_1 src1_sel:DWORD
	v_add3_u32 v23, v147, v23, s3
	v_add3_u32 v22, v146, v22, s3
	v_and_b32_e32 v23, 0xffff0000, v23
	v_or_b32_sdwa v23, v23, v22 dst_sel:DWORD dst_unused:UNUSED_PAD src0_sel:DWORD src1_sel:WORD_1
	v_or_b32_sdwa v22, v87, v86 dst_sel:DWORD dst_unused:UNUSED_PAD src0_sel:DWORD src1_sel:WORD_1
	v_lshl_add_u64 v[86:87], v[84:85], 0, s[58:59]
	global_store_dwordx2 v[86:87], v[22:23], off sc1
	s_nop 1
	v_mov_b32_e32 v86, 0
	v_cvt_pk_fp8_f32 v86, v148, v149
	v_lshl_add_u64 v[22:23], v[20:21], 0, s[60:61]
	v_and_b32_sdwa v87, v19, v159 dst_sel:DWORD dst_unused:UNUSED_PAD src0_sel:WORD_1 src1_sel:DWORD
	v_add3_u32 v87, v19, v87, s3
	v_cvt_pk_fp8_f32 v86, v146, v147 op_sel:[0,0,1]
	v_and_b32_e32 v87, 0xffff0000, v87
	global_store_dword v[22:23], v86, off sc1
	s_nop 1
	v_and_b32_sdwa v23, v18, v159 dst_sel:DWORD dst_unused:UNUSED_PAD src0_sel:WORD_1 src1_sel:DWORD
	v_add3_u32 v86, v18, v23, s3
	v_and_b32_sdwa v23, v17, v159 dst_sel:DWORD dst_unused:UNUSED_PAD src0_sel:WORD_1 src1_sel:DWORD
	v_and_b32_sdwa v22, v16, v159 dst_sel:DWORD dst_unused:UNUSED_PAD src0_sel:WORD_1 src1_sel:DWORD
	v_add3_u32 v23, v17, v23, s3
	v_add3_u32 v22, v16, v22, s3
	v_and_b32_e32 v23, 0xffff0000, v23
	v_or_b32_sdwa v23, v23, v22 dst_sel:DWORD dst_unused:UNUSED_PAD src0_sel:DWORD src1_sel:WORD_1
	v_or_b32_sdwa v22, v87, v86 dst_sel:DWORD dst_unused:UNUSED_PAD src0_sel:DWORD src1_sel:WORD_1
	v_lshl_add_u64 v[84:85], v[84:85], 0, s[62:63]
	global_store_dwordx2 v[84:85], v[22:23], off sc1
	s_nop 1
	v_mov_b32_e32 v22, 0
	v_cvt_pk_fp8_f32 v22, v18, v19
	v_lshl_add_u64 v[20:21], v[20:21], 0, s[64:65]
	v_cvt_pk_fp8_f32 v22, v16, v17 op_sel:[0,0,1]
	s_nop 0
	global_store_dword v[20:21], v22, off sc1
	s_nop 1
	s_and_saveexec_b64 s[68:69], s[6:7]
	s_cbranch_execz .LBB0_1548
	v_mov_b32_e32 v16, s27
	v_mov_b32_e32 v17, s23
	v_pk_add_f32 v[16:17], s[8:9], v[16:17]
	s_nop 0
	v_pk_mul_f32 v[16:17], v[16:17], s[66:67] op_sel_hi:[1,0]
	s_nop 0
	v_fma_f32 v16, -v17, v17, v16
	v_max_f32_e32 v16, 0, v16
	v_add_f32_e32 v16, 0x3727c5ac, v16
	v_mul_f32_e32 v18, 0x4f800000, v16
	v_cmp_gt_f32_e32 vcc, s21, v16
	s_nop 1
	v_cndmask_b32_e32 v16, v16, v18, vcc
	v_sqrt_f32_e32 v18, v16
	s_nop 0
	v_add_u32_e32 v19, -1, v18
	v_fma_f32 v20, -v19, v18, v16
	v_cmp_ge_f32_e64 s[8:9], 0, v20
	v_add_u32_e32 v20, 1, v18
	s_nop 0
	v_cndmask_b32_e64 v19, v18, v19, s[8:9]
	v_fma_f32 v18, -v20, v18, v16
	v_cmp_lt_f32_e64 s[8:9], 0, v18
	s_nop 1
	v_cndmask_b32_e64 v18, v19, v20, s[8:9]
	v_mul_f32_e32 v19, 0x37800000, v18
	v_cndmask_b32_e32 v18, v18, v19, vcc
	v_cmp_class_f32_e32 vcc, v16, v158
	s_nop 1
	v_cndmask_b32_e32 v16, v18, v16, vcc
	v_div_scale_f32 v18, s[8:9], v16, v16, 1.0
	v_rcp_f32_e32 v19, v18
	s_add_u32 s8, s0, s10
	s_addc_u32 s9, s1, s11
	v_fma_f32 v20, -v18, v19, 1.0
	v_fmac_f32_e32 v19, v20, v19
	v_div_scale_f32 v20, vcc, 1.0, v16, 1.0
	v_mul_f32_e32 v21, v20, v19
	v_fma_f32 v22, -v18, v21, v20
	v_fmac_f32_e32 v21, v22, v19
	v_fma_f32 v18, -v18, v21, v20
	v_div_fmas_f32 v18, v18, v19, v21
	v_div_fixup_f32 v19, v18, v16, 1.0
	v_mov_b32_e32 v18, v17
	v_mov_b64_e32 v[16:17], s[8:9]
	global_store_dwordx2 v[16:17], v[18:19], off sc1
	s_nop 1
	s_branch .LBB0_1548
